# sc1 write-through only on QKV q/k and attention O dwordx4 stores (consumers on other XCDs)
# baseline (speedup 1.0000x reference)
; DI void attn_item(const Params& p, int layer, int item, char* smem) {
;     ...
;   float l_tot = lacc[0];
;   if (hasSink) l_tot += __builtin_amdgcn_exp2f(sinkv * LOG2E - m_fix);
;   float inv = 1.f / l_tot;
;   int T = (mode == 3) ? (TLAT + b * 256 + (qpos - 4096)) : (b * 4096 + qpos);
;   u16* od = p.O + (size_t)T * LDK + head16 * 64;
; #pragma unroll
;   for (int g = 0; g < 4; ++g) {
;     int d0 = 8 * g + 4 * h;
;     *(uint2*)(od + d0) = make_uint2(pack_bf16(o0[4 * g] * inv, o0[4 * g + 1] * inv), pack_bf16(o0[4 * g + 2] * inv, o0[4 * g + 3] * inv));
;     *(uint2*)(od + 32 + d0) = make_uint2(pack_bf16(o1[4 * g] * inv, o1[4 * g + 1] * inv), pack_bf16(o1[4 * g + 2] * inv, o1[4 * g + 3] * inv));
;   }
.LBB0_267:
	s_nop 5
	v_add_f32_e32 v51, v51, v52
	s_nop 0
	v_mov_b32_e32 v52, v51
	s_nop 1
	v_permlane32_swap_b32_e32 v51, v52
	s_nop 1
	v_add_f32_e32 v50, v50, v51
	v_add_f32_e32 v50, v50, v52
	v_div_scale_f32 v0, s[0:1], v50, v50, 1.0
	v_rcp_f32_e32 v3, v0
	v_lshl_add_u32 v2, s5, 12, v134
	s_lshl_b32 s0, s4, 6
	s_ashr_i32 s1, s0, 31
	v_fma_f32 v4, -v0, v3, 1.0
	v_fmac_f32_e32 v3, v4, v3
	v_div_scale_f32 v4, vcc, 1.0, v50, 1.0
	v_mul_f32_e32 v5, v4, v3
	v_fma_f32 v6, -v0, v5, v4
	v_fmac_f32_e32 v5, v6, v3
	v_fma_f32 v0, -v0, v5, v4
	v_div_fmas_f32 v0, v0, v3, v5
	v_ashrrev_i32_e32 v3, 31, v2
	v_lshlrev_b64 v[2:3], 11, v[2:3]
	v_div_fixup_f32 v4, v0, v50, 1.0
	v_lshl_add_u64 v[2:3], s[90:91], 0, v[2:3]
	v_lshl_add_u64 v[2:3], s[0:1], 1, v[2:3]
	v_lshlrev_b32_e32 v0, 4, v140
	v_lshl_add_u64 v[2:3], v[2:3], 0, v[0:1]
	v_pk_mul_f32 v[6:7], v[34:35], v[4:5] op_sel_hi:[1,0]
	v_pk_mul_f32 v[8:9], v[36:37], v[4:5] op_sel_hi:[1,0]
	v_pk_mul_f32 v[10:11], v[38:39], v[4:5] op_sel_hi:[1,0]
	v_pk_mul_f32 v[12:13], v[40:41], v[4:5] op_sel_hi:[1,0]
	v_cvt_pk_bf16_f32 v6, v6, v7
	v_cvt_pk_bf16_f32 v7, v8, v9
	v_cvt_pk_bf16_f32 v8, v10, v11
	v_cvt_pk_bf16_f32 v9, v12, v13
	s_nop 1
	v_permlane32_swap_b32_e32 v6, v8
	v_permlane32_swap_b32_e32 v7, v9
	global_store_dwordx4 v[2:3], v[6:9], off offset:1280 sc1
	v_pk_mul_f32 v[14:15], v[42:43], v[4:5] op_sel_hi:[1,0]
	v_pk_mul_f32 v[16:17], v[44:45], v[4:5] op_sel_hi:[1,0]
	v_pk_mul_f32 v[10:11], v[46:47], v[4:5] op_sel_hi:[1,0]
	v_pk_mul_f32 v[12:13], v[48:49], v[4:5] op_sel_hi:[1,0]
	v_cvt_pk_bf16_f32 v14, v14, v15
	v_cvt_pk_bf16_f32 v15, v16, v17
	v_cvt_pk_bf16_f32 v16, v10, v11
	v_cvt_pk_bf16_f32 v17, v12, v13
	s_nop 1
	v_permlane32_swap_b32_e32 v14, v16
	v_permlane32_swap_b32_e32 v15, v17
	global_store_dwordx4 v[2:3], v[14:17], off offset:1312 sc1
	v_pk_mul_f32 v[6:7], v[18:19], v[4:5] op_sel_hi:[1,0]
	v_pk_mul_f32 v[8:9], v[20:21], v[4:5] op_sel_hi:[1,0]
	v_pk_mul_f32 v[10:11], v[22:23], v[4:5] op_sel_hi:[1,0]
	v_pk_mul_f32 v[12:13], v[24:25], v[4:5] op_sel_hi:[1,0]
	v_cvt_pk_bf16_f32 v6, v6, v7
	v_cvt_pk_bf16_f32 v7, v8, v9
	v_cvt_pk_bf16_f32 v8, v10, v11
	v_cvt_pk_bf16_f32 v9, v12, v13
	s_nop 1
	v_permlane32_swap_b32_e32 v6, v8
	v_permlane32_swap_b32_e32 v7, v9
	global_store_dwordx4 v[2:3], v[6:9], off offset:1344 sc1
	v_pk_mul_f32 v[14:15], v[26:27], v[4:5] op_sel_hi:[1,0]
	v_pk_mul_f32 v[16:17], v[28:29], v[4:5] op_sel_hi:[1,0]
	v_pk_mul_f32 v[10:11], v[30:31], v[4:5] op_sel_hi:[1,0]
	v_pk_mul_f32 v[12:13], v[32:33], v[4:5] op_sel_hi:[1,0]
	v_cvt_pk_bf16_f32 v14, v14, v15
	v_cvt_pk_bf16_f32 v15, v16, v17
	v_cvt_pk_bf16_f32 v16, v10, v11
	v_cvt_pk_bf16_f32 v17, v12, v13
	s_nop 1
	v_permlane32_swap_b32_e32 v14, v16
	v_permlane32_swap_b32_e32 v15, v17
	global_store_dwordx4 v[2:3], v[14:17], off offset:1376 sc1
	s_and_saveexec_b64 s[0:1], s[68:69]
	s_cbranch_execz .LBB0_236
	s_branch .LBB0_498

; DI void attn_item(const Params& p, int layer, int item, char* smem) {
;     ...
;   float l_tot = lacc[0];
;   if (hasSink) l_tot += __builtin_amdgcn_exp2f(sinkv * LOG2E - m_fix);
;   float inv = 1.f / l_tot;
;   int T = (mode == 3) ? (TLAT + b * 256 + (qpos - 4096)) : (b * 4096 + qpos);
;   u16* od = p.O + (size_t)T * LDK + head16 * 64;
; #pragma unroll
;   for (int g = 0; g < 4; ++g) {
;     int d0 = 8 * g + 4 * h;
;     *(uint2*)(od + d0) = make_uint2(pack_bf16(o0[4 * g] * inv, o0[4 * g + 1] * inv), pack_bf16(o0[4 * g + 2] * inv, o0[4 * g + 3] * inv));
;     *(uint2*)(od + 32 + d0) = make_uint2(pack_bf16(o1[4 * g] * inv, o1[4 * g + 1] * inv), pack_bf16(o1[4 * g + 2] * inv, o1[4 * g + 3] * inv));
;   }
.LBB0_485:
	s_mov_b32 s0, 0x3fb8aa3b
	v_fma_f32 v0, v174, s0, -v165
	v_exp_f32_e32 v0, v0
	v_readlane_b32 s0, v254, 54
	v_readlane_b32 s1, v254, 55
	s_lshl_b32 s2, s16, 7
	v_add_f32_e32 v0, v0, v64
	v_cndmask_b32_e64 v0, v64, v0, s[0:1]
	v_div_scale_f32 v3, s[0:1], v0, v0, 1.0
	v_rcp_f32_e32 v4, v3
	v_readlane_b32 s0, v252, 35
	v_readlane_b32 s1, v252, 36
	s_mov_b32 s3, s1
	v_fma_f32 v5, -v3, v4, 1.0
	v_fmac_f32_e32 v4, v5, v4
	v_div_scale_f32 v5, vcc, 1.0, v0, 1.0
	v_mul_f32_e32 v6, v5, v4
	v_fma_f32 v7, -v3, v6, v5
	v_fmac_f32_e32 v6, v7, v4
	v_fma_f32 v3, -v3, v6, v5
	v_div_fmas_f32 v3, v3, v4, v6
	v_div_fixup_f32 v4, v3, v0, 1.0
	v_ashrrev_i32_e32 v3, 31, v2
	v_lshlrev_b64 v[2:3], 11, v[2:3]
	v_lshl_add_u64 v[2:3], s[90:91], 0, v[2:3]
	v_lshl_add_u64 v[2:3], v[2:3], 0, s[2:3]
	v_lshlrev_b32_e32 v0, 4, v175
	v_lshl_add_u64 v[2:3], v[2:3], 0, v[0:1]
	v_pk_mul_f32 v[6:7], v[32:33], v[4:5] op_sel_hi:[1,0]
	v_pk_mul_f32 v[8:9], v[34:35], v[4:5] op_sel_hi:[1,0]
	v_pk_mul_f32 v[10:11], v[36:37], v[4:5] op_sel_hi:[1,0]
	v_pk_mul_f32 v[12:13], v[38:39], v[4:5] op_sel_hi:[1,0]
	v_cvt_pk_bf16_f32 v6, v6, v7
	v_cvt_pk_bf16_f32 v7, v8, v9
	v_cvt_pk_bf16_f32 v8, v10, v11
	v_cvt_pk_bf16_f32 v9, v12, v13
	s_nop 1
	v_permlane32_swap_b32_e32 v6, v8
	v_permlane32_swap_b32_e32 v7, v9
	global_store_dwordx4 v[2:3], v[6:9], off sc1
	s_nop 1
	v_pk_mul_f32 v[6:7], v[40:41], v[4:5] op_sel_hi:[1,0]
	v_pk_mul_f32 v[8:9], v[42:43], v[4:5] op_sel_hi:[1,0]
	v_pk_mul_f32 v[10:11], v[44:45], v[4:5] op_sel_hi:[1,0]
	v_pk_mul_f32 v[12:13], v[46:47], v[4:5] op_sel_hi:[1,0]
	v_cvt_pk_bf16_f32 v6, v6, v7
	v_cvt_pk_bf16_f32 v7, v8, v9
	v_cvt_pk_bf16_f32 v8, v10, v11
	v_cvt_pk_bf16_f32 v9, v12, v13
	s_nop 1
	v_permlane32_swap_b32_e32 v6, v8
	v_permlane32_swap_b32_e32 v7, v9
	global_store_dwordx4 v[2:3], v[6:9], off offset:32 sc1
	s_nop 1
	v_pk_mul_f32 v[6:7], v[16:17], v[4:5] op_sel_hi:[1,0]
	v_pk_mul_f32 v[8:9], v[18:19], v[4:5] op_sel_hi:[1,0]
	v_pk_mul_f32 v[10:11], v[20:21], v[4:5] op_sel_hi:[1,0]
	v_pk_mul_f32 v[12:13], v[22:23], v[4:5] op_sel_hi:[1,0]
	v_cvt_pk_bf16_f32 v6, v6, v7
	v_cvt_pk_bf16_f32 v7, v8, v9
	v_cvt_pk_bf16_f32 v8, v10, v11
	v_cvt_pk_bf16_f32 v9, v12, v13
	s_nop 1
	v_permlane32_swap_b32_e32 v6, v8
	v_permlane32_swap_b32_e32 v7, v9
	global_store_dwordx4 v[2:3], v[6:9], off offset:64 sc1
	s_nop 1
	v_pk_mul_f32 v[6:7], v[24:25], v[4:5] op_sel_hi:[1,0]
	v_pk_mul_f32 v[8:9], v[26:27], v[4:5] op_sel_hi:[1,0]
	v_pk_mul_f32 v[10:11], v[28:29], v[4:5] op_sel_hi:[1,0]
	v_pk_mul_f32 v[12:13], v[30:31], v[4:5] op_sel_hi:[1,0]
	v_cvt_pk_bf16_f32 v6, v6, v7
	v_cvt_pk_bf16_f32 v7, v8, v9
	v_cvt_pk_bf16_f32 v8, v10, v11
	v_cvt_pk_bf16_f32 v9, v12, v13
	s_nop 1
	v_permlane32_swap_b32_e32 v6, v8
	v_permlane32_swap_b32_e32 v7, v9
	v_writelane_b32 v252, s0, 35
	v_writelane_b32 v252, s1, 36
	global_store_dwordx4 v[2:3], v[6:9], off offset:96 sc1
	s_mov_b64 s[0:1], 0

;   DI void operator()(const f32x4 (&acc)[2][2][4][2], const Unit& u, int wr, int wc, int fr, int fq) const {
;     ...
;     const int row0 = u.pm * BM + wr * 64 + fr, col0 = u.pn * BM + wc * 32 + 4 * fq;
;     f32x4 gv[2][2];
; #pragma unroll
;     for (int bj = 0; bj < 2; ++bj)
; #pragma unroll
;       for (int n = 0; n < 2; ++n) gv[bj][n] = *(const f32x4*)(gate + col0 + bj * HALF + n * 16);
; #pragma unroll
;     for (int ai = 0; ai < 2; ++ai) {
;       f32x4 sv[4][2][2];
; #pragma unroll
;       for (int m = 0; m < 4; ++m) {
;         const size_t ro = (size_t)(row0 + ai * HALF + m * 16) * DM + col0;
; #pragma unroll
;         for (int bj = 0; bj < 2; ++bj)
; #pragma unroll
;           for (int n = 0; n < 2; ++n) sv[m][bj][n] = *(const f32x4*)(src + ro + bj * HALF + n * 16);
;       }
; #pragma unroll
;       for (int m = 0; m < 4; ++m) {
;         const size_t ro = (size_t)(row0 + ai * HALF + m * 16) * DM + col0;
; #pragma unroll
;         for (int bj = 0; bj < 2; ++bj)
; #pragma unroll
;           for (int n = 0; n < 2; ++n) *(f32x4*)(dst + ro + bj * HALF + n * 16) = sv[m][bj][n] + gv[bj][n] * acc[ai][bj][m][n];
.LBB0_493:
	s_lshl_b32 s0, s15, 8
	v_lshl_or_b32 v0, v132, 2, s0
	v_or_b32_e32 v0, s16, v0
	v_readlane_b32 s0, v255, 10
	v_lshlrev_b64 v[174:175], 2, v[0:1]
	v_readlane_b32 s1, v255, 11
	v_lshl_add_u32 v146, s13, 8, v146
	v_ashrrev_i32_e32 v147, 31, v146
	v_lshl_add_u64 v[126:127], s[0:1], 0, v[174:175]
	v_readlane_b32 s0, v255, 6
	v_readlane_b32 s1, v255, 7
	v_lshlrev_b64 v[186:187], 12, v[146:147]
	global_load_dwordx4 v[142:145], v[126:127], off
	global_load_dwordx4 v[138:141], v[126:127], off offset:64
	global_load_dwordx4 v[130:133], v[126:127], off offset:512
	s_nop 0
	global_load_dwordx4 v[126:129], v[126:127], off offset:576
	v_lshl_add_u64 v[176:177], s[0:1], 0, v[174:175]
	s_waitcnt vmcnt(0)
	v_lshl_add_u64 v[148:149], v[176:177], 0, v[186:187]
	global_load_dwordx4 v[190:193], v[148:149], off
	global_load_dwordx4 v[198:201], v[148:149], off offset:64
	global_load_dwordx4 v[202:205], v[148:149], off offset:512
	global_load_dwordx4 v[206:209], v[148:149], off offset:576
	v_or_b32_e32 v148, 16, v146
	v_ashrrev_i32_e32 v149, 31, v148
	v_lshlrev_b64 v[180:181], 12, v[148:149]
	v_lshl_add_u64 v[148:149], v[176:177], 0, v[180:181]
	global_load_dwordx4 v[214:217], v[148:149], off
	global_load_dwordx4 v[218:221], v[148:149], off offset:64
	global_load_dwordx4 v[222:225], v[148:149], off offset:512
	global_load_dwordx4 v[226:229], v[148:149], off offset:576
	v_or_b32_e32 v148, 32, v146
	v_ashrrev_i32_e32 v149, 31, v148
	v_lshlrev_b64 v[182:183], 12, v[148:149]
	v_or_b32_e32 v146, 48, v146
	v_lshl_add_u64 v[148:149], v[176:177], 0, v[182:183]
	v_ashrrev_i32_e32 v147, 31, v146
	global_load_dwordx4 v[230:233], v[148:149], off
	global_load_dwordx4 v[166:169], v[148:149], off offset:64
	global_load_dwordx4 v[162:165], v[148:149], off offset:512
	global_load_dwordx4 v[158:161], v[148:149], off offset:576
	v_lshlrev_b64 v[188:189], 12, v[146:147]
	v_lshl_add_u64 v[146:147], v[176:177], 0, v[188:189]
	global_load_dwordx4 v[170:173], v[146:147], off
	global_load_dwordx4 v[154:157], v[146:147], off offset:64
	global_load_dwordx4 v[150:153], v[146:147], off offset:512
	s_nop 0
	global_load_dwordx4 v[146:149], v[146:147], off offset:576
	v_readlane_b32 s2, v254, 31
	v_readlane_b32 s3, v254, 32
	s_mov_b64 s[0:1], 0x80000
	s_cmpk_lt_u32 s12, 0x100
	v_lshl_add_u64 v[184:185], s[2:3], 0, v[186:187]
	v_lshl_add_u64 v[184:185], v[184:185], 0, v[174:175]
	s_waitcnt vmcnt(0) lgkmcnt(0)
	v_pk_fma_f32 v[136:137], v[136:137], v[144:145], v[192:193]
	v_pk_fma_f32 v[124:125], v[124:125], v[140:141], v[200:201]
	v_pk_fma_f32 v[122:123], v[122:123], v[138:139], v[198:199]
	v_pk_fma_f32 v[116:117], v[116:117], v[128:129], v[208:209]
	v_pk_fma_f32 v[114:115], v[114:115], v[126:127], v[206:207]
	global_store_dwordx4 v[184:185], v[114:117], off offset:576 sc1
	v_pk_fma_f32 v[134:135], v[134:135], v[142:143], v[190:191]
	global_store_dwordx4 v[184:185], v[122:125], off offset:64 sc1
	v_lshl_add_u64 v[114:115], s[2:3], 0, v[180:181]
	v_lshl_add_u64 v[114:115], v[114:115], 0, v[174:175]
	v_pk_fma_f32 v[100:101], v[100:101], v[128:129], v[228:229]
	v_pk_fma_f32 v[98:99], v[98:99], v[126:127], v[226:227]
	global_store_dwordx4 v[114:115], v[98:101], off offset:576 sc1
	v_pk_fma_f32 v[120:121], v[120:121], v[132:133], v[204:205]
	v_pk_fma_f32 v[118:119], v[118:119], v[130:131], v[202:203]
	v_lshl_add_u64 v[98:99], s[2:3], 0, v[182:183]
	v_lshl_add_u64 v[98:99], v[98:99], 0, v[174:175]
	v_pk_fma_f32 v[84:85], v[84:85], v[128:129], v[160:161]
	v_pk_fma_f32 v[82:83], v[82:83], v[126:127], v[158:159]
	global_store_dwordx4 v[98:99], v[82:85], off offset:576 sc1
	v_pk_fma_f32 v[112:113], v[112:113], v[144:145], v[216:217]
	v_pk_fma_f32 v[110:111], v[110:111], v[142:143], v[214:215]
	v_lshl_add_u64 v[82:83], s[2:3], 0, v[188:189]
	v_pk_fma_f32 v[108:109], v[108:109], v[140:141], v[220:221]
	v_pk_fma_f32 v[106:107], v[106:107], v[138:139], v[218:219]
	v_pk_fma_f32 v[104:105], v[104:105], v[132:133], v[224:225]
	v_pk_fma_f32 v[102:103], v[102:103], v[130:131], v[222:223]
	v_pk_fma_f32 v[96:97], v[96:97], v[144:145], v[232:233]
	v_pk_fma_f32 v[94:95], v[94:95], v[142:143], v[230:231]
	v_pk_fma_f32 v[92:93], v[92:93], v[140:141], v[168:169]
	v_pk_fma_f32 v[90:91], v[90:91], v[138:139], v[166:167]
	v_pk_fma_f32 v[88:89], v[88:89], v[132:133], v[164:165]
	v_pk_fma_f32 v[86:87], v[86:87], v[130:131], v[162:163]
	v_pk_fma_f32 v[80:81], v[80:81], v[144:145], v[172:173]
	v_pk_fma_f32 v[78:79], v[78:79], v[142:143], v[170:171]
	v_lshl_add_u64 v[82:83], v[82:83], 0, v[174:175]
	v_pk_fma_f32 v[76:77], v[76:77], v[140:141], v[156:157]
	v_pk_fma_f32 v[74:75], v[74:75], v[138:139], v[154:155]
	v_pk_fma_f32 v[72:73], v[72:73], v[132:133], v[152:153]
	v_pk_fma_f32 v[70:71], v[70:71], v[130:131], v[150:151]
	v_pk_fma_f32 v[68:69], v[68:69], v[128:129], v[148:149]
	v_pk_fma_f32 v[66:67], v[66:67], v[126:127], v[146:147]
	v_lshl_add_u64 v[124:125], v[186:187], 0, s[0:1]
	global_store_dwordx4 v[184:185], v[134:137], off sc1
	global_store_dwordx4 v[184:185], v[118:121], off offset:512 sc1
	global_store_dwordx4 v[114:115], v[110:113], off sc1
	global_store_dwordx4 v[114:115], v[106:109], off offset:64 sc1
	global_store_dwordx4 v[114:115], v[102:105], off offset:512 sc1
	global_store_dwordx4 v[98:99], v[94:97], off sc1
	global_store_dwordx4 v[98:99], v[90:93], off offset:64 sc1
	global_store_dwordx4 v[98:99], v[86:89], off offset:512 sc1
	global_store_dwordx4 v[82:83], v[78:81], off sc1
	global_store_dwordx4 v[82:83], v[74:77], off offset:64 sc1
	global_store_dwordx4 v[82:83], v[70:73], off offset:512 sc1
	global_store_dwordx4 v[82:83], v[66:69], off offset:576 sc1
	s_mov_b64 s[0:1], 0x90000
	v_lshl_add_u64 v[150:151], v[186:187], 0, s[0:1]
	v_lshl_add_u64 v[66:67], v[176:177], 0, v[124:125]
	global_load_dwordx4 v[80:83], v[66:67], off
	global_load_dwordx4 v[84:87], v[66:67], off offset:64
	global_load_dwordx4 v[88:91], v[66:67], off offset:512
	global_load_dwordx4 v[92:95], v[66:67], off offset:576
	v_lshl_add_u64 v[66:67], v[176:177], 0, v[150:151]
	s_mov_b64 s[0:1], 0xa0000
	global_load_dwordx4 v[96:99], v[66:67], off
	global_load_dwordx4 v[100:103], v[66:67], off offset:64
	global_load_dwordx4 v[104:107], v[66:67], off offset:512
	global_load_dwordx4 v[108:111], v[66:67], off offset:576
	v_lshl_add_u64 v[152:153], v[186:187], 0, s[0:1]
	v_lshl_add_u64 v[66:67], v[176:177], 0, v[152:153]
	s_mov_b64 s[0:1], 0xb0000
	global_load_dwordx4 v[112:115], v[66:67], off
	global_load_dwordx4 v[116:119], v[66:67], off offset:64
	global_load_dwordx4 v[120:123], v[66:67], off offset:512
	global_load_dwordx4 v[134:137], v[66:67], off offset:576
	v_lshl_add_u64 v[78:79], v[186:187], 0, s[0:1]
	v_lshl_add_u64 v[66:67], v[176:177], 0, v[78:79]
	global_load_dwordx4 v[146:149], v[66:67], off
	global_load_dwordx4 v[74:77], v[66:67], off offset:64
	global_load_dwordx4 v[70:73], v[66:67], off offset:512
	s_nop 0
	global_load_dwordx4 v[66:69], v[66:67], off offset:576
	s_waitcnt vmcnt(0) lgkmcnt(0)
;   DI void operator()(const f32x4 (&acc)[2][2][4][2], const Unit& u, int wr, int wc, int fr, int fq) const {
;     ...
;     for (int ai = 0; ai < 2; ++ai) {
;       f32x4 sv[4][2][2];
; #pragma unroll
;       for (int m = 0; m < 4; ++m) {
;         const size_t ro = (size_t)(row0 + ai * HALF + m * 16) * DM + col0;
; #pragma unroll
;         for (int bj = 0; bj < 2; ++bj)
; #pragma unroll
;           for (int n = 0; n < 2; ++n) sv[m][bj][n] = *(const f32x4*)(src + ro + bj * HALF + n * 16);
;       }
; #pragma unroll
;       for (int m = 0; m < 4; ++m) {
;         const size_t ro = (size_t)(row0 + ai * HALF + m * 16) * DM + col0;
; #pragma unroll
;         for (int bj = 0; bj < 2; ++bj)
; #pragma unroll
;           for (int n = 0; n < 2; ++n) *(f32x4*)(dst + ro + bj * HALF + n * 16) = sv[m][bj][n] + gv[bj][n] * acc[ai][bj][m][n];
;       }
	v_pk_fma_f32 v[62:63], v[62:63], v[142:143], v[80:81]
	v_lshl_add_u64 v[80:81], s[2:3], 0, v[124:125]
	v_lshl_add_u64 v[80:81], v[80:81], 0, v[174:175]
	v_pk_fma_f32 v[48:49], v[48:49], v[128:129], v[94:95]
	v_pk_fma_f32 v[46:47], v[46:47], v[126:127], v[92:93]
	global_store_dwordx4 v[80:81], v[46:49], off offset:576 sc1
	v_pk_fma_f32 v[32:33], v[32:33], v[128:129], v[110:111]
	v_pk_fma_f32 v[30:31], v[30:31], v[126:127], v[108:109]
	v_pk_fma_f32 v[46:47], v[50:51], v[142:143], v[96:97]
	v_lshl_add_u64 v[50:51], s[2:3], 0, v[150:151]
	v_lshl_add_u64 v[50:51], v[50:51], 0, v[174:175]
	global_store_dwordx4 v[50:51], v[30:33], off offset:576 sc1
	v_pk_fma_f32 v[16:17], v[16:17], v[128:129], v[136:137]
	v_pk_fma_f32 v[14:15], v[14:15], v[126:127], v[134:135]
	v_pk_fma_f32 v[30:31], v[34:35], v[142:143], v[112:113]
	v_lshl_add_u64 v[34:35], s[2:3], 0, v[152:153]
	v_lshl_add_u64 v[34:35], v[34:35], 0, v[174:175]
	global_store_dwordx4 v[34:35], v[14:17], off offset:576 sc1
	v_pk_fma_f32 v[64:65], v[64:65], v[144:145], v[82:83]
	v_pk_fma_f32 v[60:61], v[60:61], v[140:141], v[86:87]
	v_pk_fma_f32 v[14:15], v[18:19], v[142:143], v[146:147]
	v_lshl_add_u64 v[18:19], s[2:3], 0, v[78:79]
	v_pk_fma_f32 v[58:59], v[58:59], v[138:139], v[84:85]
	v_pk_fma_f32 v[56:57], v[56:57], v[132:133], v[90:91]
	v_pk_fma_f32 v[54:55], v[54:55], v[130:131], v[88:89]
	v_pk_fma_f32 v[48:49], v[52:53], v[144:145], v[98:99]
	v_pk_fma_f32 v[44:45], v[44:45], v[140:141], v[102:103]
	v_pk_fma_f32 v[42:43], v[42:43], v[138:139], v[100:101]
	v_pk_fma_f32 v[40:41], v[40:41], v[132:133], v[106:107]
	v_pk_fma_f32 v[38:39], v[38:39], v[130:131], v[104:105]
	v_pk_fma_f32 v[32:33], v[36:37], v[144:145], v[114:115]
	v_pk_fma_f32 v[28:29], v[28:29], v[140:141], v[118:119]
	v_pk_fma_f32 v[26:27], v[26:27], v[138:139], v[116:117]
	v_pk_fma_f32 v[24:25], v[24:25], v[132:133], v[122:123]
	v_pk_fma_f32 v[22:23], v[22:23], v[130:131], v[120:121]
	v_pk_fma_f32 v[16:17], v[20:21], v[144:145], v[148:149]
	v_lshl_add_u64 v[18:19], v[18:19], 0, v[174:175]
	v_pk_fma_f32 v[12:13], v[12:13], v[140:141], v[76:77]
	v_pk_fma_f32 v[10:11], v[10:11], v[138:139], v[74:75]
	v_pk_fma_f32 v[8:9], v[8:9], v[132:133], v[72:73]
	v_pk_fma_f32 v[6:7], v[6:7], v[130:131], v[70:71]
	v_pk_fma_f32 v[4:5], v[4:5], v[128:129], v[68:69]
	v_pk_fma_f32 v[2:3], v[2:3], v[126:127], v[66:67]
	global_store_dwordx4 v[80:81], v[62:65], off sc1
	global_store_dwordx4 v[80:81], v[58:61], off offset:64 sc1
	global_store_dwordx4 v[80:81], v[54:57], off offset:512 sc1
	global_store_dwordx4 v[50:51], v[46:49], off sc1
	global_store_dwordx4 v[50:51], v[42:45], off offset:64 sc1
	global_store_dwordx4 v[50:51], v[38:41], off offset:512 sc1
	global_store_dwordx4 v[34:35], v[30:33], off sc1
	global_store_dwordx4 v[34:35], v[26:29], off offset:64 sc1
	global_store_dwordx4 v[34:35], v[22:25], off offset:512 sc1
	global_store_dwordx4 v[18:19], v[14:17], off sc1
	global_store_dwordx4 v[18:19], v[10:13], off offset:64 sc1
	global_store_dwordx4 v[18:19], v[6:9], off offset:512 sc1
	global_store_dwordx4 v[18:19], v[2:5], off offset:576 sc1
	s_waitcnt vmcnt(0)
	s_cbranch_scc0 .LBB0_495
	s_barrier

; DI u16 f2bf(float a) { return (u16)(pack_bf16(a, 0.f) & 0xffffu); }
;   DI void operator()(const f32x4 (&acc)[2][2][4][2], const Unit& u, int wr, int wc, int fr, int fq) const {
;     ...
;         const int t = u.pm * BM + ai * HALF + wr * 64 + m * 16 + fr;
;         int b, pos;
;         if (rowbase == 0) { b = t >> 12; pos = t & 4095; } else { b = t >> 8; pos = 4096 + (t & 255); }
;         u16* base = qkv + (size_t)(b * 32 + chunk) * LTOT * 64;
;         if (isV) {
; #pragma unroll
;           for (int bj = 0; bj < 2; ++bj)
; #pragma unroll
;             for (int n = 0; n < 2; ++n)
; #pragma unroll
;               for (int e = 0; e < 4; ++e) {
;                 int d = 32 * bj + 8 * fq + 4 * n + e;
;                 base[(size_t)d * LTOT + pos] = f2bf(acc[ai][bj][m][n][e]);
;               }
;         } else {
;           float ss = 0.f;
; #pragma unroll
;           for (int bj = 0; bj < 2; ++bj)
; #pragma unroll
;             for (int n = 0; n < 2; ++n)
; #pragma unroll
;               for (int e = 0; e < 4; ++e) ss += acc[ai][bj][m][n][e] * acc[ai][bj][m][n][e];
;           ss += __shfl_xor(ss, 16);
;           ss += __shfl_xor(ss, 32);
;           const float rinv = rsqrtf(ss * (1.f / 64.f) + EPSV);
;           float o1[8], o2[8];
; #pragma unroll
;           for (int n = 0; n < 2; ++n) {
;             f32x4 cs0 = (f32x4){1.f, 0.f, 1.f, 0.f}, cs1 = cs0;
;             if (ropeT) { cs0 = csr[m & 1][n][0]; cs1 = csr[m & 1][n][1]; }
; #pragma unroll
;             for (int e = 0; e < 4; ++e) {
;               float x1 = acc[ai][0][m][n][e] * (rinv * qs) * g4[0][n][e];
;               float x2 = acc[ai][1][m][n][e] * (rinv * qs) * g4[1][n][e];
;               float c = (e < 2) ? cs0[2 * e] : cs1[2 * (e - 2)], s = (e < 2) ? cs0[2 * e + 1] : cs1[2 * (e - 2) + 1];
;               o1[n * 4 + e] = x1 * c - x2 * s;
;               o2[n * 4 + e] = x2 * c + x1 * s;
;             }
;           }
;           u16* dst = base + (size_t)pos * 64 + 8 * fq;
;           *(uint4*)(dst) = make_uint4(pack_bf16(o1[0], o1[1]), pack_bf16(o1[2], o1[3]), pack_bf16(o1[4], o1[5]), pack_bf16(o1[6], o1[7]));
;           *(uint4*)(dst + 32) = make_uint4(pack_bf16(o2[0], o2[1]), pack_bf16(o2[2], o2[3]), pack_bf16(o2[4], o2[5]), pack_bf16(o2[6], o2[7]));
.LBB0_536:
	s_xor_b64 s[52:53], s[8:9], -1
	s_or_b64 s[8:9], s[10:11], s[22:23]
	s_or_b64 vcc, s[24:25], s[8:9]
	s_ashr_i32 s8, s49, 7
	s_andn2_b32 s8, s8, 31
	s_add_i32 s8, s8, s48
	s_mul_hi_i32 s9, s8, 0x88000
	s_mul_i32 s8, s8, 0x88000
	s_add_u32 s10, s88, s8
	v_cndmask_b32_e64 v180, 0, 1, s[52:53]
	v_cndmask_b32_e32 v217, 1.0, v248, vcc
	s_addc_u32 s11, s89, s9
	s_mov_b64 s[22:23], -1
	v_cmp_ne_u32_e64 s[8:9], 1, v180
	s_andn2_b64 vcc, exec, s[52:53]
	v_lshlrev_b32_e32 v206, 1, v184
	s_cbranch_vccnz .LBB0_538
	v_mul_f32_e32 v180, v175, v175
	v_fmac_f32_e32 v180, v174, v174
	v_fmac_f32_e32 v180, v176, v176
	v_fmac_f32_e32 v180, v177, v177
	v_fmac_f32_e32 v180, v170, v170
	v_fmac_f32_e32 v180, v171, v171
	v_fmac_f32_e32 v180, v172, v172
	v_fmac_f32_e32 v180, v173, v173
	v_pk_mul_f32 v[220:221], v[166:167], v[166:167]
	v_pk_mul_f32 v[218:219], v[168:169], v[168:169]
	v_add_f32_e32 v180, v220, v180
	v_add_f32_e32 v180, v221, v180
	v_add_f32_e32 v180, v218, v180
	v_add_f32_e32 v180, v219, v180
	v_pk_mul_f32 v[220:221], v[162:163], v[162:163]
	v_add_f32_e32 v180, v220, v180
	v_pk_mul_f32 v[218:219], v[164:165], v[164:165]
	v_add_f32_e32 v180, v221, v180
	v_add_f32_e32 v180, v218, v180
	v_add_f32_e32 v180, v219, v180
	v_mov_b32_e32 v181, v180
	s_nop 1
	v_permlane16_swap_b32_e32 v180, v181
	s_mov_b32 s22, 0x800000
	v_mov_b32_e32 v226, v174
	v_mov_b32_e32 v227, v167
	s_waitcnt vmcnt(0)
	v_mov_b32_e32 v228, v74
	s_waitcnt lgkmcnt(0)
	v_add_f32_e32 v180, v180, v181
	v_mov_b32_e32 v229, v79
	v_mov_b32_e32 v230, v78
	v_mov_b32_e32 v181, v180
	s_nop 1
	v_permlane32_swap_b32_e32 v180, v181
	v_mov_b32_e32 v231, v75
	v_cndmask_b32_e64 v219, 0, v129, s[6:7]
	v_cndmask_b32_e64 v218, 1.0, v126, s[6:7]
	v_cndmask_b32_e64 v221, 1.0, v128, s[6:7]
	s_waitcnt lgkmcnt(0)
	v_add_f32_e32 v180, v180, v181
	v_fmamk_f32 v180, v180, 0x3c800000, v210
	v_mul_f32_e32 v181, 0x4b800000, v180
	v_cmp_gt_f32_e32 vcc, s22, v180
	v_cndmask_b32_e64 v220, 0, v127, s[6:7]
	v_mov_b32_e32 v233, v221
	v_cndmask_b32_e32 v180, v180, v181, vcc
	v_rsq_f32_e32 v180, v180
	v_mov_b32_e32 v232, v218
	v_cndmask_b32_e64 v223, 0, v125, s[6:7]
	v_cndmask_b32_e64 v222, 1.0, v122, s[6:7]
	v_mul_f32_e32 v181, 0x45800000, v180
	v_cndmask_b32_e32 v180, v180, v181, vcc
	v_mul_f32_e32 v208, v217, v180
	v_pk_mul_f32 v[226:227], v[226:227], v[208:209] op_sel_hi:[1,0]
	v_cndmask_b32_e64 v225, 1.0, v124, s[6:7]
	v_pk_mul_f32 v[226:227], v[228:229], v[226:227]
	v_mov_b32_e32 v228, v166
	v_mov_b32_e32 v229, v175
	v_pk_mul_f32 v[228:229], v[228:229], v[208:209] op_sel_hi:[1,0]
	v_mov_b32_e32 v234, v226
	v_pk_mul_f32 v[228:229], v[230:231], v[228:229]
	v_cndmask_b32_e64 v224, 0, v123, s[6:7]
	v_pk_mul_f32 v[230:231], v[218:219], v[228:229]
	v_mov_b32_e32 v235, v229
	v_pk_fma_f32 v[230:231], v[220:221], v[226:227], v[230:231]
	v_mov_b32_e32 v221, v219
	v_mov_b32_e32 v229, v227
	v_pk_mul_f32 v[218:219], v[220:221], v[228:229]
	v_mov_b32_e32 v220, v176
	v_mov_b32_e32 v221, v169
	v_pk_mul_f32 v[220:221], v[220:221], v[208:209] op_sel_hi:[1,0]
	v_mov_b32_e32 v226, v76
	v_mov_b32_e32 v227, v81
	v_pk_mul_f32 v[220:221], v[226:227], v[220:221]
	v_mov_b32_e32 v226, v168
	v_mov_b32_e32 v227, v177
	v_pk_mul_f32 v[226:227], v[226:227], v[208:209] op_sel_hi:[1,0]
	v_mov_b32_e32 v228, v80
	v_mov_b32_e32 v229, v77
	v_pk_mul_f32 v[226:227], v[228:229], v[226:227]
	v_pk_fma_f32 v[218:219], v[232:233], v[234:235], v[218:219] neg_lo:[0,0,1] neg_hi:[0,0,1]
	v_pk_mul_f32 v[228:229], v[222:223], v[226:227]
	v_mov_b32_e32 v233, v225
	v_pk_fma_f32 v[228:229], v[224:225], v[220:221], v[228:229]
	v_mov_b32_e32 v235, v227
	v_mov_b32_e32 v225, v223
	v_mov_b32_e32 v227, v221
	v_mov_b32_e32 v232, v222
	v_mov_b32_e32 v234, v220
	v_pk_mul_f32 v[220:221], v[224:225], v[226:227]
	v_mov_b32_e32 v236, v66
	v_pk_fma_f32 v[220:221], v[232:233], v[234:235], v[220:221] neg_lo:[0,0,1] neg_hi:[0,0,1]
	v_mov_b32_e32 v234, v170
	v_mov_b32_e32 v235, v163
	v_pk_mul_f32 v[234:235], v[234:235], v[208:209] op_sel_hi:[1,0]
	v_mov_b32_e32 v237, v71
	v_pk_mul_f32 v[234:235], v[236:237], v[234:235]
	v_mov_b32_e32 v236, v162
	v_mov_b32_e32 v237, v171
	v_pk_mul_f32 v[236:237], v[236:237], v[208:209] op_sel_hi:[1,0]
	v_mov_b32_e32 v238, v70
	v_mov_b32_e32 v239, v67
	v_cndmask_b32_e64 v223, 0, v121, s[6:7]
	v_cndmask_b32_e64 v222, 1.0, v118, s[6:7]
	v_pk_mul_f32 v[236:237], v[238:239], v[236:237]
	v_cndmask_b32_e64 v225, 1.0, v120, s[6:7]
	v_cndmask_b32_e64 v224, 0, v119, s[6:7]
	v_pk_mul_f32 v[238:239], v[222:223], v[236:237]
	v_mov_b32_e32 v241, v225
	v_pk_fma_f32 v[238:239], v[224:225], v[234:235], v[238:239]
	v_mov_b32_e32 v243, v237
	v_mov_b32_e32 v225, v223
	v_mov_b32_e32 v237, v235
	v_mov_b32_e32 v240, v222
	v_pk_mul_f32 v[222:223], v[224:225], v[236:237]
	v_mov_b32_e32 v224, v172
	v_mov_b32_e32 v225, v165
	v_mov_b32_e32 v242, v234
	v_pk_mul_f32 v[224:225], v[224:225], v[208:209] op_sel_hi:[1,0]
	v_mov_b32_e32 v234, v68
	v_mov_b32_e32 v235, v73
	v_pk_mul_f32 v[224:225], v[234:235], v[224:225]
	v_mov_b32_e32 v234, v164
	v_mov_b32_e32 v235, v173
	v_pk_mul_f32 v[234:235], v[234:235], v[208:209] op_sel_hi:[1,0]
	v_mov_b32_e32 v236, v72
	v_mov_b32_e32 v237, v69
	v_cndmask_b32_e64 v227, 0, v117, s[6:7]
	v_cndmask_b32_e64 v226, 1.0, v114, s[6:7]
	v_pk_mul_f32 v[234:235], v[236:237], v[234:235]
	v_cndmask_b32_e64 v233, 1.0, v116, s[6:7]
	v_cndmask_b32_e64 v232, 0, v115, s[6:7]
	v_pk_mul_f32 v[236:237], v[226:227], v[234:235]
	v_pk_fma_f32 v[222:223], v[240:241], v[242:243], v[222:223] neg_lo:[0,0,1] neg_hi:[0,0,1]
	v_pk_fma_f32 v[236:237], v[232:233], v[224:225], v[236:237]
	v_mov_b32_e32 v241, v233
	v_mov_b32_e32 v243, v235
	v_mov_b32_e32 v233, v227
	v_mov_b32_e32 v235, v225
	v_mov_b32_e32 v240, v226
	v_mov_b32_e32 v242, v224
	v_pk_mul_f32 v[224:225], v[232:233], v[234:235]
	v_lshlrev_b32_e32 v226, 7, v209
	v_mov_b32_e32 v227, v1
	v_pk_fma_f32 v[224:225], v[240:241], v[242:243], v[224:225] neg_lo:[0,0,1] neg_hi:[0,0,1]
	v_lshl_add_u64 v[226:227], s[10:11], 0, v[226:227]
	v_mov_b32_e32 v207, v1
	v_lshl_add_u64 v[226:227], v[226:227], 0, v[206:207]
	v_cvt_pk_bf16_f32 v218, v218, v219
	v_cvt_pk_bf16_f32 v219, v220, v221
	v_cvt_pk_bf16_f32 v220, v222, v223
	v_cvt_pk_bf16_f32 v221, v224, v225
	global_store_dwordx4 v[226:227], v[218:221], off sc1
	s_mov_b64 s[22:23], 0
	s_nop 0
	v_cvt_pk_bf16_f32 v218, v230, v231
	v_cvt_pk_bf16_f32 v219, v228, v229
	v_cvt_pk_bf16_f32 v220, v238, v239
	v_cvt_pk_bf16_f32 v221, v236, v237
	global_store_dwordx4 v[226:227], v[218:221], off offset:64 sc1

; DI u16 f2bf(float a) { return (u16)(pack_bf16(a, 0.f) & 0xffffu); }
;   DI void operator()(const f32x4 (&acc)[2][2][4][2], const Unit& u, int wr, int wc, int fr, int fq) const {
;     ...
;         const int t = u.pm * BM + ai * HALF + wr * 64 + m * 16 + fr;
;         int b, pos;
;         if (rowbase == 0) { b = t >> 12; pos = t & 4095; } else { b = t >> 8; pos = 4096 + (t & 255); }
;         u16* base = qkv + (size_t)(b * 32 + chunk) * LTOT * 64;
;         if (isV) {
; #pragma unroll
;           for (int bj = 0; bj < 2; ++bj)
; #pragma unroll
;             for (int n = 0; n < 2; ++n)
; #pragma unroll
;               for (int e = 0; e < 4; ++e) {
;                 int d = 32 * bj + 8 * fq + 4 * n + e;
;                 base[(size_t)d * LTOT + pos] = f2bf(acc[ai][bj][m][n][e]);
;               }
;         } else {
;           float ss = 0.f;
; #pragma unroll
;           for (int bj = 0; bj < 2; ++bj)
; #pragma unroll
;             for (int n = 0; n < 2; ++n)
; #pragma unroll
;               for (int e = 0; e < 4; ++e) ss += acc[ai][bj][m][n][e] * acc[ai][bj][m][n][e];
;           ss += __shfl_xor(ss, 16);
;           ss += __shfl_xor(ss, 32);
;           const float rinv = rsqrtf(ss * (1.f / 64.f) + EPSV);
;           float o1[8], o2[8];
; #pragma unroll
;           for (int n = 0; n < 2; ++n) {
;             f32x4 cs0 = (f32x4){1.f, 0.f, 1.f, 0.f}, cs1 = cs0;
;             if (ropeT) { cs0 = csr[m & 1][n][0]; cs1 = csr[m & 1][n][1]; }
; #pragma unroll
;             for (int e = 0; e < 4; ++e) {
;               float x1 = acc[ai][0][m][n][e] * (rinv * qs) * g4[0][n][e];
;               float x2 = acc[ai][1][m][n][e] * (rinv * qs) * g4[1][n][e];
;               float c = (e < 2) ? cs0[2 * e] : cs1[2 * (e - 2)], s = (e < 2) ? cs0[2 * e + 1] : cs1[2 * (e - 2) + 1];
;               o1[n * 4 + e] = x1 * c - x2 * s;
;               o2[n * 4 + e] = x2 * c + x1 * s;
;             }
;           }
;           u16* dst = base + (size_t)pos * 64 + 8 * fq;
;           *(uint4*)(dst) = make_uint4(pack_bf16(o1[0], o1[1]), pack_bf16(o1[2], o1[3]), pack_bf16(o1[4], o1[5]), pack_bf16(o1[6], o1[7]));
;           *(uint4*)(dst + 32) = make_uint4(pack_bf16(o2[0], o2[1]), pack_bf16(o2[2], o2[3]), pack_bf16(o2[4], o2[5]), pack_bf16(o2[6], o2[7]));
.LBB0_540:
	s_add_i32 s10, s50, s42
	s_and_b32 s11, s10, 0xfd0
	s_ashr_i32 s10, s10, 7
	s_andn2_b32 s10, s10, 31
	s_add_i32 s10, s10, s48
	v_or_b32_e32 v162, s11, v214
	s_mul_hi_i32 s11, s10, 0x88000
	s_mul_i32 s10, s10, 0x88000
	s_add_u32 s10, s88, s10
	s_addc_u32 s11, s89, s11
	s_and_b64 vcc, exec, s[8:9]
	s_mov_b64 s[22:23], -1
	v_readlane_b32 s52, v253, 59
	v_readlane_b32 s53, v253, 60
	s_cbranch_vccnz .LBB0_542
	v_mul_f32_e32 v163, v159, v159
	v_fmac_f32_e32 v163, v158, v158
	v_fmac_f32_e32 v163, v160, v160
	v_fmac_f32_e32 v163, v161, v161
	v_fmac_f32_e32 v163, v154, v154
	v_fmac_f32_e32 v163, v155, v155
	v_fmac_f32_e32 v163, v156, v156
	v_fmac_f32_e32 v163, v157, v157
	v_pk_mul_f32 v[166:167], v[150:151], v[150:151]
	v_pk_mul_f32 v[164:165], v[152:153], v[152:153]
	v_add_f32_e32 v163, v166, v163
	v_add_f32_e32 v163, v167, v163
	v_add_f32_e32 v163, v164, v163
	v_add_f32_e32 v163, v165, v163
	v_pk_mul_f32 v[166:167], v[146:147], v[146:147]
	v_pk_mul_f32 v[164:165], v[148:149], v[148:149]
	v_add_f32_e32 v163, v166, v163
	v_add_f32_e32 v163, v167, v163
	v_add_f32_e32 v163, v164, v163
	v_add_f32_e32 v163, v165, v163
	s_mov_b32 s22, 0x800000
	v_mov_b32_e32 v174, v158
	v_mov_b32_e32 v164, v163
	s_nop 1
	v_permlane16_swap_b32_e32 v163, v164
	v_mov_b32_e32 v175, v151
	v_mov_b32_e32 v176, v74
	v_mov_b32_e32 v177, v79
	v_mov_b32_e32 v218, v78
	s_waitcnt lgkmcnt(0)
	v_add_f32_e32 v163, v163, v164
	v_mov_b32_e32 v219, v75
	v_cndmask_b32_e64 v167, 0, v97, s[6:7]
	v_mov_b32_e32 v164, v163
	s_nop 1
	v_permlane32_swap_b32_e32 v163, v164
	v_cndmask_b32_e64 v166, 1.0, v94, s[6:7]
	v_cndmask_b32_e64 v169, 1.0, v96, s[6:7]
	v_cndmask_b32_e64 v168, 0, v95, s[6:7]
	v_mov_b32_e32 v221, v169
	s_waitcnt lgkmcnt(0)
	v_add_f32_e32 v163, v163, v164
	v_fmamk_f32 v163, v163, 0x3c800000, v210
	v_mul_f32_e32 v164, 0x4b800000, v163
	v_cmp_gt_f32_e32 vcc, s22, v163
	v_mov_b32_e32 v220, v166
	v_cndmask_b32_e64 v171, 0, v101, s[6:7]
	v_cndmask_b32_e32 v163, v163, v164, vcc
	v_rsq_f32_e32 v163, v163
	v_cndmask_b32_e64 v170, 1.0, v98, s[6:7]
	v_cndmask_b32_e64 v173, 1.0, v100, s[6:7]
	v_cndmask_b32_e64 v172, 0, v99, s[6:7]
	v_mul_f32_e32 v164, 0x45800000, v163
	v_cndmask_b32_e32 v163, v163, v164, vcc
	v_mul_f32_e32 v164, v217, v163
	v_pk_mul_f32 v[174:175], v[174:175], v[164:165] op_sel_hi:[1,0]
	v_mov_b32_e32 v224, v66
	v_pk_mul_f32 v[174:175], v[176:177], v[174:175]
	v_mov_b32_e32 v176, v150
	v_mov_b32_e32 v177, v159
	v_pk_mul_f32 v[176:177], v[176:177], v[164:165] op_sel_hi:[1,0]
	v_mov_b32_e32 v222, v174
	v_pk_mul_f32 v[176:177], v[218:219], v[176:177]
	v_mov_b32_e32 v225, v71
	v_pk_mul_f32 v[218:219], v[166:167], v[176:177]
	v_mov_b32_e32 v223, v177
	v_pk_fma_f32 v[218:219], v[168:169], v[174:175], v[218:219]
	v_mov_b32_e32 v169, v167
	v_mov_b32_e32 v177, v175
	v_pk_mul_f32 v[166:167], v[168:169], v[176:177]
	v_mov_b32_e32 v168, v160
	v_mov_b32_e32 v169, v153
	v_pk_mul_f32 v[168:169], v[168:169], v[164:165] op_sel_hi:[1,0]
	v_mov_b32_e32 v174, v76
	v_mov_b32_e32 v175, v81
	v_pk_mul_f32 v[168:169], v[174:175], v[168:169]
	v_mov_b32_e32 v174, v152
	v_mov_b32_e32 v175, v161
	v_pk_mul_f32 v[174:175], v[174:175], v[164:165] op_sel_hi:[1,0]
	v_mov_b32_e32 v176, v80
	v_mov_b32_e32 v177, v77
	v_pk_mul_f32 v[174:175], v[176:177], v[174:175]
	v_pk_fma_f32 v[166:167], v[220:221], v[222:223], v[166:167] neg_lo:[0,0,1] neg_hi:[0,0,1]
	v_pk_mul_f32 v[176:177], v[170:171], v[174:175]
	v_mov_b32_e32 v221, v173
	v_pk_fma_f32 v[176:177], v[172:173], v[168:169], v[176:177]
	v_mov_b32_e32 v223, v175
	v_mov_b32_e32 v173, v171
	v_mov_b32_e32 v175, v169
	v_mov_b32_e32 v220, v170
	v_mov_b32_e32 v222, v168
	v_pk_mul_f32 v[168:169], v[172:173], v[174:175]
	v_mov_b32_e32 v226, v70
	v_pk_fma_f32 v[168:169], v[220:221], v[222:223], v[168:169] neg_lo:[0,0,1] neg_hi:[0,0,1]
	v_mov_b32_e32 v222, v154
	v_mov_b32_e32 v223, v147
	v_pk_mul_f32 v[222:223], v[222:223], v[164:165] op_sel_hi:[1,0]
	v_mov_b32_e32 v227, v67
	v_pk_mul_f32 v[222:223], v[224:225], v[222:223]
	v_mov_b32_e32 v224, v146
	v_mov_b32_e32 v225, v155
	v_pk_mul_f32 v[224:225], v[224:225], v[164:165] op_sel_hi:[1,0]
	v_cndmask_b32_e64 v171, 0, v89, s[6:7]
	v_cndmask_b32_e64 v170, 1.0, v86, s[6:7]
	v_pk_mul_f32 v[224:225], v[226:227], v[224:225]
	v_cndmask_b32_e64 v173, 1.0, v88, s[6:7]
	v_cndmask_b32_e64 v172, 0, v87, s[6:7]
	v_pk_mul_f32 v[226:227], v[170:171], v[224:225]
	v_mov_b32_e32 v229, v173
	v_pk_fma_f32 v[226:227], v[172:173], v[222:223], v[226:227]
	v_mov_b32_e32 v231, v225
	v_mov_b32_e32 v173, v171
	v_mov_b32_e32 v225, v223
	v_mov_b32_e32 v228, v170
	v_pk_mul_f32 v[170:171], v[172:173], v[224:225]
	v_mov_b32_e32 v172, v156
	v_mov_b32_e32 v173, v149
	v_mov_b32_e32 v230, v222
	v_pk_mul_f32 v[172:173], v[172:173], v[164:165] op_sel_hi:[1,0]
	v_mov_b32_e32 v222, v68
	v_mov_b32_e32 v223, v73
	v_pk_mul_f32 v[172:173], v[222:223], v[172:173]
	v_mov_b32_e32 v222, v148
	v_mov_b32_e32 v223, v157
	v_pk_mul_f32 v[164:165], v[222:223], v[164:165] op_sel_hi:[1,0]
	v_mov_b32_e32 v222, v72
	v_mov_b32_e32 v223, v69
	v_cndmask_b32_e64 v175, 0, v85, s[6:7]
	v_cndmask_b32_e64 v174, 1.0, v82, s[6:7]
	v_pk_mul_f32 v[164:165], v[222:223], v[164:165]
	v_cndmask_b32_e64 v221, 1.0, v84, s[6:7]
	v_cndmask_b32_e64 v220, 0, v83, s[6:7]
	v_pk_mul_f32 v[222:223], v[174:175], v[164:165]
	v_pk_fma_f32 v[170:171], v[228:229], v[230:231], v[170:171] neg_lo:[0,0,1] neg_hi:[0,0,1]
	v_pk_fma_f32 v[222:223], v[220:221], v[172:173], v[222:223]
	v_mov_b32_e32 v225, v221
	v_mov_b32_e32 v229, v165
	v_mov_b32_e32 v221, v175
	v_mov_b32_e32 v165, v173
	v_mov_b32_e32 v224, v174
	v_mov_b32_e32 v228, v172
	v_pk_mul_f32 v[164:165], v[220:221], v[164:165]
	v_mov_b32_e32 v207, v1
	v_pk_fma_f32 v[172:173], v[224:225], v[228:229], v[164:165] neg_lo:[0,0,1] neg_hi:[0,0,1]
	v_lshlrev_b32_e32 v164, 7, v162
	v_mov_b32_e32 v165, v1
	v_lshl_add_u64 v[164:165], s[10:11], 0, v[164:165]
	v_lshl_add_u64 v[174:175], v[164:165], 0, v[206:207]
	v_cvt_pk_bf16_f32 v164, v166, v167
	v_cvt_pk_bf16_f32 v165, v168, v169
	v_cvt_pk_bf16_f32 v166, v170, v171
	v_cvt_pk_bf16_f32 v167, v172, v173
	global_store_dwordx4 v[174:175], v[164:167], off sc1
	s_mov_b64 s[22:23], 0
	s_nop 0
	v_cvt_pk_bf16_f32 v164, v218, v219
	v_cvt_pk_bf16_f32 v165, v176, v177
	v_cvt_pk_bf16_f32 v166, v226, v227
	v_cvt_pk_bf16_f32 v167, v222, v223
	global_store_dwordx4 v[174:175], v[164:167], off offset:64 sc1

; DI u16 f2bf(float a) { return (u16)(pack_bf16(a, 0.f) & 0xffffu); }
;   DI void operator()(const f32x4 (&acc)[2][2][4][2], const Unit& u, int wr, int wc, int fr, int fq) const {
;     ...
;         const int t = u.pm * BM + ai * HALF + wr * 64 + m * 16 + fr;
;         int b, pos;
;         if (rowbase == 0) { b = t >> 12; pos = t & 4095; } else { b = t >> 8; pos = 4096 + (t & 255); }
;         u16* base = qkv + (size_t)(b * 32 + chunk) * LTOT * 64;
;         if (isV) {
; #pragma unroll
;           for (int bj = 0; bj < 2; ++bj)
; #pragma unroll
;             for (int n = 0; n < 2; ++n)
; #pragma unroll
;               for (int e = 0; e < 4; ++e) {
;                 int d = 32 * bj + 8 * fq + 4 * n + e;
;                 base[(size_t)d * LTOT + pos] = f2bf(acc[ai][bj][m][n][e]);
;               }
;         } else {
;           float ss = 0.f;
; #pragma unroll
;           for (int bj = 0; bj < 2; ++bj)
; #pragma unroll
;             for (int n = 0; n < 2; ++n)
; #pragma unroll
;               for (int e = 0; e < 4; ++e) ss += acc[ai][bj][m][n][e] * acc[ai][bj][m][n][e];
;           ss += __shfl_xor(ss, 16);
;           ss += __shfl_xor(ss, 32);
;           const float rinv = rsqrtf(ss * (1.f / 64.f) + EPSV);
;           float o1[8], o2[8];
; #pragma unroll
;           for (int n = 0; n < 2; ++n) {
;             f32x4 cs0 = (f32x4){1.f, 0.f, 1.f, 0.f}, cs1 = cs0;
;             if (ropeT) { cs0 = csr[m & 1][n][0]; cs1 = csr[m & 1][n][1]; }
; #pragma unroll
;             for (int e = 0; e < 4; ++e) {
;               float x1 = acc[ai][0][m][n][e] * (rinv * qs) * g4[0][n][e];
;               float x2 = acc[ai][1][m][n][e] * (rinv * qs) * g4[1][n][e];
;               float c = (e < 2) ? cs0[2 * e] : cs1[2 * (e - 2)], s = (e < 2) ? cs0[2 * e + 1] : cs1[2 * (e - 2) + 1];
;               o1[n * 4 + e] = x1 * c - x2 * s;
;               o2[n * 4 + e] = x2 * c + x1 * s;
;             }
;           }
;           u16* dst = base + (size_t)pos * 64 + 8 * fq;
;           *(uint4*)(dst) = make_uint4(pack_bf16(o1[0], o1[1]), pack_bf16(o1[2], o1[3]), pack_bf16(o1[4], o1[5]), pack_bf16(o1[6], o1[7]));
;           *(uint4*)(dst + 32) = make_uint4(pack_bf16(o2[0], o2[1]), pack_bf16(o2[2], o2[3]), pack_bf16(o2[4], o2[5]), pack_bf16(o2[6], o2[7]));
.LBB0_546:
	s_add_i32 s2, s50, s43
	s_and_b32 s3, s2, 0xfe0
	s_ashr_i32 s2, s2, 7
	s_andn2_b32 s2, s2, 31
	s_add_i32 s2, s2, s48
	v_or_b32_e32 v146, s3, v214
	s_mul_hi_i32 s3, s2, 0x88000
	s_mul_i32 s2, s2, 0x88000
	s_add_u32 s2, s88, s2
	s_addc_u32 s3, s89, s3
	s_and_b64 vcc, exec, s[8:9]
	s_mov_b64 s[22:23], -1
	s_cbranch_vccnz .LBB0_548
	v_mul_f32_e32 v0, v143, v143
	v_fmac_f32_e32 v0, v142, v142
	v_fmac_f32_e32 v0, v144, v144
	v_fmac_f32_e32 v0, v145, v145
	v_fmac_f32_e32 v0, v138, v138
	v_fmac_f32_e32 v0, v139, v139
	v_fmac_f32_e32 v0, v140, v140
	v_fmac_f32_e32 v0, v141, v141
	v_pk_mul_f32 v[150:151], v[134:135], v[134:135]
	v_pk_mul_f32 v[148:149], v[136:137], v[136:137]
	v_add_f32_e32 v0, v150, v0
	v_add_f32_e32 v0, v151, v0
	v_add_f32_e32 v0, v148, v0
	v_add_f32_e32 v0, v149, v0
	v_pk_mul_f32 v[150:151], v[130:131], v[130:131]
	v_pk_mul_f32 v[148:149], v[132:133], v[132:133]
	v_add_f32_e32 v0, v150, v0
	v_add_f32_e32 v0, v151, v0
	v_add_f32_e32 v0, v148, v0
	v_add_f32_e32 v0, v149, v0
	s_mov_b32 s22, 0x800000
	v_mov_b32_e32 v147, v0
	s_nop 1
	v_permlane16_swap_b32_e32 v0, v147
	v_mov_b32_e32 v156, v142
	v_mov_b32_e32 v157, v135
	s_waitcnt vmcnt(0)
	v_mov_b32_e32 v158, v74
	v_mov_b32_e32 v159, v79
	s_waitcnt lgkmcnt(0)
	v_add_f32_e32 v0, v0, v147
	v_mov_b32_e32 v160, v78
	v_mov_b32_e32 v161, v75
	v_mov_b32_e32 v147, v0
	s_nop 1
	v_permlane32_swap_b32_e32 v0, v147
	v_cndmask_b32_e64 v149, 0, v129, s[6:7]
	v_cndmask_b32_e64 v148, 1.0, v126, s[6:7]
	v_cndmask_b32_e64 v151, 1.0, v128, s[6:7]
	v_cndmask_b32_e64 v150, 0, v127, s[6:7]
	s_waitcnt lgkmcnt(0)
	v_add_f32_e32 v0, v0, v147
	v_fmamk_f32 v0, v0, 0x3c800000, v210
	v_mul_f32_e32 v147, 0x4b800000, v0
	v_cmp_gt_f32_e32 vcc, s22, v0
	v_mov_b32_e32 v163, v151
	v_mov_b32_e32 v162, v148
	v_cndmask_b32_e32 v0, v0, v147, vcc
	v_rsq_f32_e32 v0, v0
	v_cndmask_b32_e64 v153, 0, v125, s[6:7]
	v_cndmask_b32_e64 v152, 1.0, v122, s[6:7]
	v_cndmask_b32_e64 v155, 1.0, v124, s[6:7]
	v_mul_f32_e32 v147, 0x45800000, v0
	v_cndmask_b32_e32 v0, v0, v147, vcc
	v_mul_f32_e32 v0, v217, v0
	v_pk_mul_f32 v[156:157], v[156:157], v[0:1] op_sel_hi:[1,0]
	v_cndmask_b32_e64 v154, 0, v123, s[6:7]
	v_pk_mul_f32 v[156:157], v[158:159], v[156:157]
	v_mov_b32_e32 v158, v134
	v_mov_b32_e32 v159, v143
	v_pk_mul_f32 v[158:159], v[158:159], v[0:1] op_sel_hi:[1,0]
	v_mov_b32_e32 v164, v156
	v_pk_mul_f32 v[158:159], v[160:161], v[158:159]
	v_mov_b32_e32 v166, v66
	v_pk_mul_f32 v[160:161], v[148:149], v[158:159]
	v_mov_b32_e32 v165, v159
	v_pk_fma_f32 v[160:161], v[150:151], v[156:157], v[160:161]
	v_mov_b32_e32 v151, v149
	v_mov_b32_e32 v159, v157
	v_pk_mul_f32 v[148:149], v[150:151], v[158:159]
	v_mov_b32_e32 v150, v144
	v_mov_b32_e32 v151, v137
	v_pk_mul_f32 v[150:151], v[150:151], v[0:1] op_sel_hi:[1,0]
	v_mov_b32_e32 v156, v76
	v_mov_b32_e32 v157, v81
	v_pk_mul_f32 v[150:151], v[156:157], v[150:151]
	v_mov_b32_e32 v156, v136
	v_mov_b32_e32 v157, v145
	v_pk_mul_f32 v[156:157], v[156:157], v[0:1] op_sel_hi:[1,0]
	v_mov_b32_e32 v158, v80
	v_mov_b32_e32 v159, v77
	v_pk_mul_f32 v[156:157], v[158:159], v[156:157]
	v_pk_fma_f32 v[148:149], v[162:163], v[164:165], v[148:149] neg_lo:[0,0,1] neg_hi:[0,0,1]
	v_pk_mul_f32 v[158:159], v[152:153], v[156:157]
	v_mov_b32_e32 v163, v155
	v_pk_fma_f32 v[158:159], v[154:155], v[150:151], v[158:159]
	v_mov_b32_e32 v165, v157
	v_mov_b32_e32 v155, v153
	v_mov_b32_e32 v157, v151
	v_mov_b32_e32 v162, v152
	v_mov_b32_e32 v164, v150
	v_pk_mul_f32 v[150:151], v[154:155], v[156:157]
	v_mov_b32_e32 v167, v71
	v_pk_fma_f32 v[150:151], v[162:163], v[164:165], v[150:151] neg_lo:[0,0,1] neg_hi:[0,0,1]
	v_mov_b32_e32 v164, v138
	v_mov_b32_e32 v165, v131
	v_pk_mul_f32 v[164:165], v[164:165], v[0:1] op_sel_hi:[1,0]
	v_mov_b32_e32 v168, v70
	v_pk_mul_f32 v[164:165], v[166:167], v[164:165]
	v_mov_b32_e32 v166, v130
	v_mov_b32_e32 v167, v139
	v_pk_mul_f32 v[166:167], v[166:167], v[0:1] op_sel_hi:[1,0]
	v_mov_b32_e32 v169, v67
	v_cndmask_b32_e64 v153, 0, v121, s[6:7]
	v_cndmask_b32_e64 v152, 1.0, v118, s[6:7]
	v_pk_mul_f32 v[166:167], v[168:169], v[166:167]
	v_cndmask_b32_e64 v155, 1.0, v120, s[6:7]
	v_cndmask_b32_e64 v154, 0, v119, s[6:7]
	v_pk_mul_f32 v[168:169], v[152:153], v[166:167]
	v_mov_b32_e32 v171, v155
	v_pk_fma_f32 v[168:169], v[154:155], v[164:165], v[168:169]
	v_mov_b32_e32 v173, v167
	v_mov_b32_e32 v155, v153
	v_mov_b32_e32 v167, v165
	v_mov_b32_e32 v170, v152
	v_pk_mul_f32 v[152:153], v[154:155], v[166:167]
	v_mov_b32_e32 v154, v140
	v_mov_b32_e32 v155, v133
	v_mov_b32_e32 v172, v164
	v_pk_mul_f32 v[154:155], v[154:155], v[0:1] op_sel_hi:[1,0]
	v_mov_b32_e32 v164, v68
	v_mov_b32_e32 v165, v73
	v_pk_mul_f32 v[154:155], v[164:165], v[154:155]
	v_mov_b32_e32 v164, v132
	v_mov_b32_e32 v165, v141
	v_pk_mul_f32 v[164:165], v[164:165], v[0:1] op_sel_hi:[1,0]
	v_mov_b32_e32 v166, v72
	v_mov_b32_e32 v167, v69
	v_cndmask_b32_e64 v157, 0, v117, s[6:7]
	v_cndmask_b32_e64 v156, 1.0, v114, s[6:7]
	v_pk_mul_f32 v[164:165], v[166:167], v[164:165]
	v_cndmask_b32_e64 v163, 1.0, v116, s[6:7]
	v_cndmask_b32_e64 v162, 0, v115, s[6:7]
	v_pk_mul_f32 v[166:167], v[156:157], v[164:165]
	v_pk_fma_f32 v[152:153], v[170:171], v[172:173], v[152:153] neg_lo:[0,0,1] neg_hi:[0,0,1]
	v_pk_fma_f32 v[166:167], v[162:163], v[154:155], v[166:167]
	v_mov_b32_e32 v171, v163
	v_mov_b32_e32 v173, v165
	v_mov_b32_e32 v163, v157
	v_mov_b32_e32 v165, v155
	v_mov_b32_e32 v170, v156
	v_mov_b32_e32 v172, v154
	v_pk_mul_f32 v[154:155], v[162:163], v[164:165]
	v_lshlrev_b32_e32 v0, 7, v146
	v_pk_fma_f32 v[154:155], v[170:171], v[172:173], v[154:155] neg_lo:[0,0,1] neg_hi:[0,0,1]
	v_lshl_add_u64 v[156:157], s[2:3], 0, v[0:1]
	v_mov_b32_e32 v207, v1
	v_lshl_add_u64 v[156:157], v[156:157], 0, v[206:207]
	v_cvt_pk_bf16_f32 v148, v148, v149
	v_cvt_pk_bf16_f32 v149, v150, v151
	v_cvt_pk_bf16_f32 v150, v152, v153
	v_cvt_pk_bf16_f32 v151, v154, v155
	global_store_dwordx4 v[156:157], v[148:151], off sc1
	s_mov_b64 s[22:23], 0
	s_nop 0
	v_cvt_pk_bf16_f32 v148, v160, v161
	v_cvt_pk_bf16_f32 v149, v158, v159
	v_cvt_pk_bf16_f32 v150, v168, v169
	v_cvt_pk_bf16_f32 v151, v166, v167
	global_store_dwordx4 v[156:157], v[148:151], off offset:64 sc1

; DI u16 f2bf(float a) { return (u16)(pack_bf16(a, 0.f) & 0xffffu); }
;   DI void operator()(const f32x4 (&acc)[2][2][4][2], const Unit& u, int wr, int wc, int fr, int fq) const {
;     ...
;         const int t = u.pm * BM + ai * HALF + wr * 64 + m * 16 + fr;
;         int b, pos;
;         if (rowbase == 0) { b = t >> 12; pos = t & 4095; } else { b = t >> 8; pos = 4096 + (t & 255); }
;         u16* base = qkv + (size_t)(b * 32 + chunk) * LTOT * 64;
;         if (isV) {
; #pragma unroll
;           for (int bj = 0; bj < 2; ++bj)
; #pragma unroll
;             for (int n = 0; n < 2; ++n)
; #pragma unroll
;               for (int e = 0; e < 4; ++e) {
;                 int d = 32 * bj + 8 * fq + 4 * n + e;
;                 base[(size_t)d * LTOT + pos] = f2bf(acc[ai][bj][m][n][e]);
;               }
;         } else {
;           float ss = 0.f;
; #pragma unroll
;           for (int bj = 0; bj < 2; ++bj)
; #pragma unroll
;             for (int n = 0; n < 2; ++n)
; #pragma unroll
;               for (int e = 0; e < 4; ++e) ss += acc[ai][bj][m][n][e] * acc[ai][bj][m][n][e];
;           ss += __shfl_xor(ss, 16);
;           ss += __shfl_xor(ss, 32);
;           const float rinv = rsqrtf(ss * (1.f / 64.f) + EPSV);
;           float o1[8], o2[8];
; #pragma unroll
;           for (int n = 0; n < 2; ++n) {
;             f32x4 cs0 = (f32x4){1.f, 0.f, 1.f, 0.f}, cs1 = cs0;
;             if (ropeT) { cs0 = csr[m & 1][n][0]; cs1 = csr[m & 1][n][1]; }
; #pragma unroll
;             for (int e = 0; e < 4; ++e) {
;               float x1 = acc[ai][0][m][n][e] * (rinv * qs) * g4[0][n][e];
;               float x2 = acc[ai][1][m][n][e] * (rinv * qs) * g4[1][n][e];
;               float c = (e < 2) ? cs0[2 * e] : cs1[2 * (e - 2)], s = (e < 2) ? cs0[2 * e + 1] : cs1[2 * (e - 2) + 1];
;               o1[n * 4 + e] = x1 * c - x2 * s;
;               o2[n * 4 + e] = x2 * c + x1 * s;
;             }
;           }
;           u16* dst = base + (size_t)pos * 64 + 8 * fq;
;           *(uint4*)(dst) = make_uint4(pack_bf16(o1[0], o1[1]), pack_bf16(o1[2], o1[3]), pack_bf16(o1[4], o1[5]), pack_bf16(o1[6], o1[7]));
;           *(uint4*)(dst + 32) = make_uint4(pack_bf16(o2[0], o2[1]), pack_bf16(o2[2], o2[3]), pack_bf16(o2[4], o2[5]), pack_bf16(o2[6], o2[7]));
.LBB0_550:
	s_add_i32 s50, s50, s44
	s_and_b32 s2, s50, 0xff0
	v_or_b32_e32 v130, s2, v214
	s_ashr_i32 s2, s50, 7
	s_andn2_b32 s2, s2, 31
	s_add_i32 s2, s2, s48
	s_mul_hi_i32 s3, s2, 0x88000
	s_mul_i32 s2, s2, 0x88000
	s_add_u32 s2, s88, s2
	s_addc_u32 s3, s89, s3
	s_and_b64 vcc, exec, s[8:9]
	s_mov_b64 s[22:23], -1
	s_cbranch_vccnz .LBB0_552
	v_mul_f32_e32 v0, v111, v111
	v_fmac_f32_e32 v0, v110, v110
	v_fmac_f32_e32 v0, v112, v112
	v_fmac_f32_e32 v0, v113, v113
	v_fmac_f32_e32 v0, v106, v106
	v_fmac_f32_e32 v0, v107, v107
	v_fmac_f32_e32 v0, v108, v108
	v_fmac_f32_e32 v0, v109, v109
	v_pk_mul_f32 v[134:135], v[102:103], v[102:103]
	v_pk_mul_f32 v[132:133], v[104:105], v[104:105]
	v_add_f32_e32 v0, v134, v0
	v_add_f32_e32 v0, v135, v0
	v_add_f32_e32 v0, v132, v0
	v_add_f32_e32 v0, v133, v0
	v_pk_mul_f32 v[134:135], v[90:91], v[90:91]
	v_pk_mul_f32 v[132:133], v[92:93], v[92:93]
	v_add_f32_e32 v0, v134, v0
	v_add_f32_e32 v0, v135, v0
	v_add_f32_e32 v0, v132, v0
	v_add_f32_e32 v0, v133, v0
	s_mov_b32 s22, 0x800000
	v_mov_b32_e32 v131, v0
	s_nop 1
	v_permlane16_swap_b32_e32 v0, v131
	v_mov_b32_e32 v140, v110
	v_mov_b32_e32 v141, v103
	v_mov_b32_e32 v142, v74
	v_mov_b32_e32 v143, v79
	s_waitcnt lgkmcnt(0)
	v_add_f32_e32 v0, v0, v131
	v_mov_b32_e32 v144, v78
	v_mov_b32_e32 v145, v75
	v_mov_b32_e32 v131, v0
	s_nop 1
	v_permlane32_swap_b32_e32 v0, v131
	v_cndmask_b32_e64 v133, 0, v97, s[6:7]
	v_cndmask_b32_e64 v132, 1.0, v94, s[6:7]
	v_cndmask_b32_e64 v135, 1.0, v96, s[6:7]
	v_cndmask_b32_e64 v134, 0, v95, s[6:7]
	s_waitcnt lgkmcnt(0)
	v_add_f32_e32 v0, v0, v131
	v_fmamk_f32 v0, v0, 0x3c800000, v210
	v_mul_f32_e32 v131, 0x4b800000, v0
	v_cmp_gt_f32_e32 vcc, s22, v0
	v_mov_b32_e32 v147, v135
	v_mov_b32_e32 v146, v132
	v_cndmask_b32_e32 v0, v0, v131, vcc
	v_rsq_f32_e32 v0, v0
	v_cndmask_b32_e64 v137, 0, v101, s[6:7]
	v_cndmask_b32_e64 v136, 1.0, v98, s[6:7]
	v_cndmask_b32_e64 v139, 1.0, v100, s[6:7]
	v_mul_f32_e32 v131, 0x45800000, v0
	v_cndmask_b32_e32 v0, v0, v131, vcc
	v_mul_f32_e32 v0, v217, v0
	v_pk_mul_f32 v[140:141], v[140:141], v[0:1] op_sel_hi:[1,0]
	v_cndmask_b32_e64 v138, 0, v99, s[6:7]
	v_pk_mul_f32 v[140:141], v[142:143], v[140:141]
	v_mov_b32_e32 v142, v102
	v_mov_b32_e32 v143, v111
	v_pk_mul_f32 v[142:143], v[142:143], v[0:1] op_sel_hi:[1,0]
	v_mov_b32_e32 v148, v140
	v_pk_mul_f32 v[142:143], v[144:145], v[142:143]
	v_mov_b32_e32 v150, v66
	v_pk_mul_f32 v[144:145], v[132:133], v[142:143]
	v_mov_b32_e32 v149, v143
	v_pk_fma_f32 v[144:145], v[134:135], v[140:141], v[144:145]
	v_mov_b32_e32 v135, v133
	v_mov_b32_e32 v143, v141
	v_pk_mul_f32 v[132:133], v[134:135], v[142:143]
	v_mov_b32_e32 v134, v112
	v_mov_b32_e32 v135, v105
	v_pk_mul_f32 v[134:135], v[134:135], v[0:1] op_sel_hi:[1,0]
	v_mov_b32_e32 v140, v76
	v_mov_b32_e32 v141, v81
	v_pk_mul_f32 v[134:135], v[140:141], v[134:135]
	v_mov_b32_e32 v140, v104
	v_mov_b32_e32 v141, v113
	v_pk_mul_f32 v[140:141], v[140:141], v[0:1] op_sel_hi:[1,0]
	v_mov_b32_e32 v142, v80
	v_mov_b32_e32 v143, v77
	v_pk_mul_f32 v[140:141], v[142:143], v[140:141]
	v_pk_fma_f32 v[132:133], v[146:147], v[148:149], v[132:133] neg_lo:[0,0,1] neg_hi:[0,0,1]
	v_pk_mul_f32 v[142:143], v[136:137], v[140:141]
	v_mov_b32_e32 v147, v139
	v_pk_fma_f32 v[142:143], v[138:139], v[134:135], v[142:143]
	v_mov_b32_e32 v149, v141
	v_mov_b32_e32 v139, v137
	v_mov_b32_e32 v141, v135
	v_mov_b32_e32 v146, v136
	v_mov_b32_e32 v148, v134
	v_pk_mul_f32 v[134:135], v[138:139], v[140:141]
	v_mov_b32_e32 v151, v71
	v_pk_fma_f32 v[134:135], v[146:147], v[148:149], v[134:135] neg_lo:[0,0,1] neg_hi:[0,0,1]
	v_mov_b32_e32 v148, v106
	v_mov_b32_e32 v149, v91
	v_pk_mul_f32 v[148:149], v[148:149], v[0:1] op_sel_hi:[1,0]
	v_mov_b32_e32 v152, v70
	v_pk_mul_f32 v[148:149], v[150:151], v[148:149]
	v_mov_b32_e32 v150, v90
	v_mov_b32_e32 v151, v107
	v_pk_mul_f32 v[150:151], v[150:151], v[0:1] op_sel_hi:[1,0]
	v_mov_b32_e32 v153, v67
	v_cndmask_b32_e64 v137, 0, v89, s[6:7]
	v_cndmask_b32_e64 v136, 1.0, v86, s[6:7]
	v_pk_mul_f32 v[150:151], v[152:153], v[150:151]
	v_cndmask_b32_e64 v139, 1.0, v88, s[6:7]
	v_cndmask_b32_e64 v138, 0, v87, s[6:7]
	v_pk_mul_f32 v[152:153], v[136:137], v[150:151]
	v_mov_b32_e32 v155, v139
	v_pk_fma_f32 v[152:153], v[138:139], v[148:149], v[152:153]
	v_mov_b32_e32 v157, v151
	v_mov_b32_e32 v139, v137
	v_mov_b32_e32 v151, v149
	v_mov_b32_e32 v154, v136
	v_pk_mul_f32 v[136:137], v[138:139], v[150:151]
	v_mov_b32_e32 v138, v108
	v_mov_b32_e32 v139, v93
	v_mov_b32_e32 v156, v148
	v_pk_mul_f32 v[138:139], v[138:139], v[0:1] op_sel_hi:[1,0]
	v_mov_b32_e32 v148, v68
	v_mov_b32_e32 v149, v73
	v_pk_mul_f32 v[138:139], v[148:149], v[138:139]
	v_mov_b32_e32 v148, v92
	v_mov_b32_e32 v149, v109
	v_pk_mul_f32 v[148:149], v[148:149], v[0:1] op_sel_hi:[1,0]
	v_mov_b32_e32 v150, v72
	v_mov_b32_e32 v151, v69
	v_cndmask_b32_e64 v141, 0, v85, s[6:7]
	v_cndmask_b32_e64 v140, 1.0, v82, s[6:7]
	v_pk_mul_f32 v[148:149], v[150:151], v[148:149]
	v_cndmask_b32_e64 v147, 1.0, v84, s[6:7]
	v_cndmask_b32_e64 v146, 0, v83, s[6:7]
	v_pk_mul_f32 v[150:151], v[140:141], v[148:149]
	v_pk_fma_f32 v[136:137], v[154:155], v[156:157], v[136:137] neg_lo:[0,0,1] neg_hi:[0,0,1]
	v_pk_fma_f32 v[150:151], v[146:147], v[138:139], v[150:151]
	v_mov_b32_e32 v155, v147
	v_mov_b32_e32 v157, v149
	v_mov_b32_e32 v147, v141
	v_mov_b32_e32 v149, v139
	v_mov_b32_e32 v154, v140
	v_mov_b32_e32 v156, v138
	v_pk_mul_f32 v[138:139], v[146:147], v[148:149]
	v_lshlrev_b32_e32 v0, 7, v130
	v_pk_fma_f32 v[138:139], v[154:155], v[156:157], v[138:139] neg_lo:[0,0,1] neg_hi:[0,0,1]
	v_lshl_add_u64 v[140:141], s[2:3], 0, v[0:1]
	v_mov_b32_e32 v207, v1
	v_lshl_add_u64 v[140:141], v[140:141], 0, v[206:207]
	v_cvt_pk_bf16_f32 v132, v132, v133
	v_cvt_pk_bf16_f32 v133, v134, v135
	v_cvt_pk_bf16_f32 v134, v136, v137
	v_cvt_pk_bf16_f32 v135, v138, v139
	global_store_dwordx4 v[140:141], v[132:135], off sc1
	s_mov_b64 s[22:23], 0
	s_nop 0
	v_cvt_pk_bf16_f32 v132, v144, v145
	v_cvt_pk_bf16_f32 v133, v142, v143
	v_cvt_pk_bf16_f32 v134, v152, v153
	v_cvt_pk_bf16_f32 v135, v150, v151
	global_store_dwordx4 v[140:141], v[132:135], off offset:64 sc1

; DI u16 f2bf(float a) { return (u16)(pack_bf16(a, 0.f) & 0xffffu); }
;   DI void operator()(const f32x4 (&acc)[2][2][4][2], const Unit& u, int wr, int wc, int fr, int fq) const {
;     ...
;         const int t = u.pm * BM + ai * HALF + wr * 64 + m * 16 + fr;
;         int b, pos;
;         if (rowbase == 0) { b = t >> 12; pos = t & 4095; } else { b = t >> 8; pos = 4096 + (t & 255); }
;         u16* base = qkv + (size_t)(b * 32 + chunk) * LTOT * 64;
;         if (isV) {
; #pragma unroll
;           for (int bj = 0; bj < 2; ++bj)
; #pragma unroll
;             for (int n = 0; n < 2; ++n)
; #pragma unroll
;               for (int e = 0; e < 4; ++e) {
;                 int d = 32 * bj + 8 * fq + 4 * n + e;
;                 base[(size_t)d * LTOT + pos] = f2bf(acc[ai][bj][m][n][e]);
;               }
;         } else {
;           float ss = 0.f;
; #pragma unroll
;           for (int bj = 0; bj < 2; ++bj)
; #pragma unroll
;             for (int n = 0; n < 2; ++n)
; #pragma unroll
;               for (int e = 0; e < 4; ++e) ss += acc[ai][bj][m][n][e] * acc[ai][bj][m][n][e];
;           ss += __shfl_xor(ss, 16);
;           ss += __shfl_xor(ss, 32);
;           const float rinv = rsqrtf(ss * (1.f / 64.f) + EPSV);
;           float o1[8], o2[8];
; #pragma unroll
;           for (int n = 0; n < 2; ++n) {
;             f32x4 cs0 = (f32x4){1.f, 0.f, 1.f, 0.f}, cs1 = cs0;
;             if (ropeT) { cs0 = csr[m & 1][n][0]; cs1 = csr[m & 1][n][1]; }
; #pragma unroll
;             for (int e = 0; e < 4; ++e) {
;               float x1 = acc[ai][0][m][n][e] * (rinv * qs) * g4[0][n][e];
;               float x2 = acc[ai][1][m][n][e] * (rinv * qs) * g4[1][n][e];
;               float c = (e < 2) ? cs0[2 * e] : cs1[2 * (e - 2)], s = (e < 2) ? cs0[2 * e + 1] : cs1[2 * (e - 2) + 1];
;               o1[n * 4 + e] = x1 * c - x2 * s;
;               o2[n * 4 + e] = x2 * c + x1 * s;
;             }
;           }
;           u16* dst = base + (size_t)pos * 64 + 8 * fq;
;           *(uint4*)(dst) = make_uint4(pack_bf16(o1[0], o1[1]), pack_bf16(o1[2], o1[3]), pack_bf16(o1[4], o1[5]), pack_bf16(o1[6], o1[7]));
;           *(uint4*)(dst + 32) = make_uint4(pack_bf16(o2[0], o2[1]), pack_bf16(o2[2], o2[3]), pack_bf16(o2[4], o2[5]), pack_bf16(o2[6], o2[7]));
.LBB0_556:
	s_ashr_i32 s2, s2, 7
	s_andn2_b32 s2, s2, 31
	s_add_i32 s2, s2, s48
	s_mul_hi_i32 s3, s2, 0x88000
	s_mul_i32 s2, s2, 0x88000
	s_add_u32 s2, s88, s2
	s_addc_u32 s3, s89, s3
	s_and_b64 vcc, exec, s[8:9]
	s_mov_b64 s[22:23], -1
	s_cbranch_vccnz .LBB0_558
	v_mul_f32_e32 v91, v63, v63
	v_fmac_f32_e32 v91, v62, v62
	v_fmac_f32_e32 v91, v64, v64
	v_fmac_f32_e32 v91, v65, v65
	v_fmac_f32_e32 v91, v58, v58
	v_fmac_f32_e32 v91, v59, v59
	v_fmac_f32_e32 v91, v60, v60
	v_fmac_f32_e32 v91, v61, v61
	v_pk_mul_f32 v[102:103], v[54:55], v[54:55]
	v_pk_mul_f32 v[92:93], v[56:57], v[56:57]
	v_add_f32_e32 v91, v102, v91
	v_add_f32_e32 v91, v103, v91
	v_add_f32_e32 v91, v92, v91
	v_add_f32_e32 v91, v93, v91
	v_pk_mul_f32 v[102:103], v[50:51], v[50:51]
	v_pk_mul_f32 v[92:93], v[52:53], v[52:53]
	v_add_f32_e32 v91, v102, v91
	v_add_f32_e32 v91, v103, v91
	v_add_f32_e32 v91, v92, v91
	v_add_f32_e32 v91, v93, v91
	s_mov_b32 s22, 0x800000
	v_mov_b32_e32 v110, v62
	v_mov_b32_e32 v92, v91
	s_nop 1
	v_permlane16_swap_b32_e32 v91, v92
	v_mov_b32_e32 v111, v55
	s_waitcnt vmcnt(0)
	v_mov_b32_e32 v112, v74
	v_mov_b32_e32 v113, v79
	v_mov_b32_e32 v130, v78
	s_waitcnt lgkmcnt(0)
	v_add_f32_e32 v91, v91, v92
	v_mov_b32_e32 v131, v75
	v_cndmask_b32_e64 v103, 0, v129, s[6:7]
	v_mov_b32_e32 v92, v91
	s_nop 1
	v_permlane32_swap_b32_e32 v91, v92
	v_cndmask_b32_e64 v102, 1.0, v126, s[6:7]
	v_cndmask_b32_e64 v105, 1.0, v128, s[6:7]
	v_cndmask_b32_e64 v104, 0, v127, s[6:7]
	v_mov_b32_e32 v133, v105
	s_waitcnt lgkmcnt(0)
	v_add_f32_e32 v91, v91, v92
	v_fmamk_f32 v91, v91, 0x3c800000, v210
	v_mul_f32_e32 v92, 0x4b800000, v91
	v_cmp_gt_f32_e32 vcc, s22, v91
	v_mov_b32_e32 v132, v102
	v_cndmask_b32_e64 v107, 0, v125, s[6:7]
	v_cndmask_b32_e32 v91, v91, v92, vcc
	v_rsq_f32_e32 v91, v91
	v_cndmask_b32_e64 v106, 1.0, v122, s[6:7]
	v_cndmask_b32_e64 v109, 1.0, v124, s[6:7]
	v_cndmask_b32_e64 v108, 0, v123, s[6:7]
	v_mul_f32_e32 v92, 0x45800000, v91
	v_cndmask_b32_e32 v91, v91, v92, vcc
	v_mul_f32_e32 v92, v217, v91
	v_pk_mul_f32 v[110:111], v[110:111], v[92:93] op_sel_hi:[1,0]
	v_mov_b32_e32 v136, v66
	v_pk_mul_f32 v[110:111], v[112:113], v[110:111]
	v_mov_b32_e32 v112, v54
	v_mov_b32_e32 v113, v63
	v_pk_mul_f32 v[112:113], v[112:113], v[92:93] op_sel_hi:[1,0]
	v_mov_b32_e32 v134, v110
	v_pk_mul_f32 v[112:113], v[130:131], v[112:113]
	v_mov_b32_e32 v137, v71
	v_pk_mul_f32 v[130:131], v[102:103], v[112:113]
	v_mov_b32_e32 v135, v113
	v_pk_fma_f32 v[130:131], v[104:105], v[110:111], v[130:131]
	v_mov_b32_e32 v105, v103
	v_mov_b32_e32 v113, v111
	v_pk_mul_f32 v[102:103], v[104:105], v[112:113]
	v_mov_b32_e32 v104, v64
	v_mov_b32_e32 v105, v57
	v_pk_mul_f32 v[104:105], v[104:105], v[92:93] op_sel_hi:[1,0]
	v_mov_b32_e32 v110, v76
	v_mov_b32_e32 v111, v81
	v_pk_mul_f32 v[104:105], v[110:111], v[104:105]
	v_mov_b32_e32 v110, v56
	v_mov_b32_e32 v111, v65
	v_pk_mul_f32 v[110:111], v[110:111], v[92:93] op_sel_hi:[1,0]
	v_mov_b32_e32 v112, v80
	v_mov_b32_e32 v113, v77
	v_pk_mul_f32 v[110:111], v[112:113], v[110:111]
	v_pk_fma_f32 v[102:103], v[132:133], v[134:135], v[102:103] neg_lo:[0,0,1] neg_hi:[0,0,1]
	v_pk_mul_f32 v[112:113], v[106:107], v[110:111]
	v_mov_b32_e32 v133, v109
	v_pk_fma_f32 v[112:113], v[108:109], v[104:105], v[112:113]
	v_mov_b32_e32 v135, v111
	v_mov_b32_e32 v109, v107
	v_mov_b32_e32 v111, v105
	v_mov_b32_e32 v132, v106
	v_mov_b32_e32 v134, v104
	v_pk_mul_f32 v[104:105], v[108:109], v[110:111]
	v_mov_b32_e32 v138, v70
	v_pk_fma_f32 v[104:105], v[132:133], v[134:135], v[104:105] neg_lo:[0,0,1] neg_hi:[0,0,1]
	v_mov_b32_e32 v134, v58
	v_mov_b32_e32 v135, v51
	v_pk_mul_f32 v[134:135], v[134:135], v[92:93] op_sel_hi:[1,0]
	v_mov_b32_e32 v139, v67
	v_pk_mul_f32 v[134:135], v[136:137], v[134:135]
	v_mov_b32_e32 v136, v50
	v_mov_b32_e32 v137, v59
	v_pk_mul_f32 v[136:137], v[136:137], v[92:93] op_sel_hi:[1,0]
	v_cndmask_b32_e64 v107, 0, v121, s[6:7]
	v_cndmask_b32_e64 v106, 1.0, v118, s[6:7]
	v_pk_mul_f32 v[136:137], v[138:139], v[136:137]
	v_cndmask_b32_e64 v109, 1.0, v120, s[6:7]
	v_cndmask_b32_e64 v108, 0, v119, s[6:7]
	v_pk_mul_f32 v[138:139], v[106:107], v[136:137]
	v_mov_b32_e32 v141, v109
	v_pk_fma_f32 v[138:139], v[108:109], v[134:135], v[138:139]
	v_mov_b32_e32 v143, v137
	v_mov_b32_e32 v109, v107
	v_mov_b32_e32 v137, v135
	v_mov_b32_e32 v140, v106
	v_pk_mul_f32 v[106:107], v[108:109], v[136:137]
	v_mov_b32_e32 v108, v60
	v_mov_b32_e32 v109, v53
	v_mov_b32_e32 v142, v134
	v_pk_mul_f32 v[108:109], v[108:109], v[92:93] op_sel_hi:[1,0]
	v_mov_b32_e32 v134, v68
	v_mov_b32_e32 v135, v73
	v_pk_mul_f32 v[108:109], v[134:135], v[108:109]
	v_mov_b32_e32 v134, v52
	v_mov_b32_e32 v135, v61
	v_pk_mul_f32 v[92:93], v[134:135], v[92:93] op_sel_hi:[1,0]
	v_mov_b32_e32 v134, v72
	v_mov_b32_e32 v135, v69
	v_cndmask_b32_e64 v111, 0, v117, s[6:7]
	v_cndmask_b32_e64 v110, 1.0, v114, s[6:7]
	v_pk_mul_f32 v[92:93], v[134:135], v[92:93]
	v_cndmask_b32_e64 v133, 1.0, v116, s[6:7]
	v_cndmask_b32_e64 v132, 0, v115, s[6:7]
	v_pk_mul_f32 v[134:135], v[110:111], v[92:93]
	v_pk_fma_f32 v[106:107], v[140:141], v[142:143], v[106:107] neg_lo:[0,0,1] neg_hi:[0,0,1]
	v_pk_fma_f32 v[134:135], v[132:133], v[108:109], v[134:135]
	v_mov_b32_e32 v137, v133
	v_mov_b32_e32 v141, v93
	v_mov_b32_e32 v133, v111
	v_mov_b32_e32 v93, v109
	v_mov_b32_e32 v136, v110
	v_mov_b32_e32 v140, v108
	v_pk_mul_f32 v[92:93], v[132:133], v[92:93]
	v_lshlrev_b32_e32 v108, 7, v90
	v_mov_b32_e32 v109, v1
	v_pk_fma_f32 v[92:93], v[136:137], v[140:141], v[92:93] neg_lo:[0,0,1] neg_hi:[0,0,1]
	v_lshl_add_u64 v[108:109], s[2:3], 0, v[108:109]
	v_mov_b32_e32 v207, v1
	v_lshl_add_u64 v[108:109], v[108:109], 0, v[206:207]
	v_cvt_pk_bf16_f32 v102, v102, v103
	v_cvt_pk_bf16_f32 v103, v104, v105
	v_cvt_pk_bf16_f32 v104, v106, v107
	v_cvt_pk_bf16_f32 v105, v92, v93
	global_store_dwordx4 v[108:109], v[102:105], off sc1
	s_mov_b64 s[22:23], 0
	s_nop 0
	v_cvt_pk_bf16_f32 v102, v130, v131
	v_cvt_pk_bf16_f32 v103, v112, v113
	v_cvt_pk_bf16_f32 v104, v138, v139
	v_cvt_pk_bf16_f32 v105, v134, v135
	global_store_dwordx4 v[108:109], v[102:105], off offset:64 sc1

; DI u16 f2bf(float a) { return (u16)(pack_bf16(a, 0.f) & 0xffffu); }
;   DI void operator()(const f32x4 (&acc)[2][2][4][2], const Unit& u, int wr, int wc, int fr, int fq) const {
;     ...
;         const int t = u.pm * BM + ai * HALF + wr * 64 + m * 16 + fr;
;         int b, pos;
;         if (rowbase == 0) { b = t >> 12; pos = t & 4095; } else { b = t >> 8; pos = 4096 + (t & 255); }
;         u16* base = qkv + (size_t)(b * 32 + chunk) * LTOT * 64;
;         if (isV) {
; #pragma unroll
;           for (int bj = 0; bj < 2; ++bj)
; #pragma unroll
;             for (int n = 0; n < 2; ++n)
; #pragma unroll
;               for (int e = 0; e < 4; ++e) {
;                 int d = 32 * bj + 8 * fq + 4 * n + e;
;                 base[(size_t)d * LTOT + pos] = f2bf(acc[ai][bj][m][n][e]);
;               }
;         } else {
;           float ss = 0.f;
; #pragma unroll
;           for (int bj = 0; bj < 2; ++bj)
; #pragma unroll
;             for (int n = 0; n < 2; ++n)
; #pragma unroll
;               for (int e = 0; e < 4; ++e) ss += acc[ai][bj][m][n][e] * acc[ai][bj][m][n][e];
;           ss += __shfl_xor(ss, 16);
;           ss += __shfl_xor(ss, 32);
;           const float rinv = rsqrtf(ss * (1.f / 64.f) + EPSV);
;           float o1[8], o2[8];
; #pragma unroll
;           for (int n = 0; n < 2; ++n) {
;             f32x4 cs0 = (f32x4){1.f, 0.f, 1.f, 0.f}, cs1 = cs0;
;             if (ropeT) { cs0 = csr[m & 1][n][0]; cs1 = csr[m & 1][n][1]; }
; #pragma unroll
;             for (int e = 0; e < 4; ++e) {
;               float x1 = acc[ai][0][m][n][e] * (rinv * qs) * g4[0][n][e];
;               float x2 = acc[ai][1][m][n][e] * (rinv * qs) * g4[1][n][e];
;               float c = (e < 2) ? cs0[2 * e] : cs1[2 * (e - 2)], s = (e < 2) ? cs0[2 * e + 1] : cs1[2 * (e - 2) + 1];
;               o1[n * 4 + e] = x1 * c - x2 * s;
;               o2[n * 4 + e] = x2 * c + x1 * s;
;             }
;           }
;           u16* dst = base + (size_t)pos * 64 + 8 * fq;
;           *(uint4*)(dst) = make_uint4(pack_bf16(o1[0], o1[1]), pack_bf16(o1[2], o1[3]), pack_bf16(o1[4], o1[5]), pack_bf16(o1[6], o1[7]));
;           *(uint4*)(dst + 32) = make_uint4(pack_bf16(o2[0], o2[1]), pack_bf16(o2[2], o2[3]), pack_bf16(o2[4], o2[5]), pack_bf16(o2[6], o2[7]));
.LBB0_560:
	s_add_i32 s2, s49, 0x90
	s_and_b32 s3, s2, 0xfd0
	s_ashr_i32 s2, s2, 7
	s_andn2_b32 s2, s2, 31
	s_add_i32 s2, s2, s48
	v_or_b32_e32 v50, s3, v214
	s_mul_hi_i32 s3, s2, 0x88000
	s_mul_i32 s2, s2, 0x88000
	s_add_u32 s2, s88, s2
	s_addc_u32 s3, s89, s3
	s_and_b64 vcc, exec, s[8:9]
	s_mov_b64 s[22:23], -1
	s_cbranch_vccnz .LBB0_572
	v_mul_f32_e32 v51, v47, v47
	v_fmac_f32_e32 v51, v46, v46
	v_fmac_f32_e32 v51, v48, v48
	v_fmac_f32_e32 v51, v49, v49
	v_fmac_f32_e32 v51, v42, v42
	v_fmac_f32_e32 v51, v43, v43
	v_fmac_f32_e32 v51, v44, v44
	v_fmac_f32_e32 v51, v45, v45
	v_pk_mul_f32 v[54:55], v[38:39], v[38:39]
	v_pk_mul_f32 v[52:53], v[40:41], v[40:41]
	v_add_f32_e32 v51, v54, v51
	v_add_f32_e32 v51, v55, v51
	v_add_f32_e32 v51, v52, v51
	v_add_f32_e32 v51, v53, v51
	v_pk_mul_f32 v[54:55], v[34:35], v[34:35]
	v_pk_mul_f32 v[52:53], v[36:37], v[36:37]
	v_add_f32_e32 v51, v54, v51
	v_add_f32_e32 v51, v55, v51
	v_add_f32_e32 v51, v52, v51
	v_add_f32_e32 v51, v53, v51
	s_mov_b32 s22, 0x800000
	v_mov_b32_e32 v62, v46
	v_mov_b32_e32 v52, v51
	s_nop 1
	v_permlane16_swap_b32_e32 v51, v52
	v_mov_b32_e32 v63, v39
	v_mov_b32_e32 v64, v74
	v_mov_b32_e32 v65, v79
	v_mov_b32_e32 v90, v78
	s_waitcnt lgkmcnt(0)
	v_add_f32_e32 v51, v51, v52
	v_mov_b32_e32 v91, v75
	v_cndmask_b32_e64 v55, 0, v97, s[6:7]
	v_mov_b32_e32 v52, v51
	s_nop 1
	v_permlane32_swap_b32_e32 v51, v52
	v_cndmask_b32_e64 v54, 1.0, v94, s[6:7]
	v_cndmask_b32_e64 v57, 1.0, v96, s[6:7]
	v_cndmask_b32_e64 v56, 0, v95, s[6:7]
	v_mov_b32_e32 v93, v57
	s_waitcnt lgkmcnt(0)
	v_add_f32_e32 v51, v51, v52
	v_fmamk_f32 v51, v51, 0x3c800000, v210
	v_mul_f32_e32 v52, 0x4b800000, v51
	v_cmp_gt_f32_e32 vcc, s22, v51
	v_mov_b32_e32 v92, v54
	v_cndmask_b32_e64 v59, 0, v101, s[6:7]
	v_cndmask_b32_e32 v51, v51, v52, vcc
	v_rsq_f32_e32 v51, v51
	v_cndmask_b32_e64 v58, 1.0, v98, s[6:7]
	v_cndmask_b32_e64 v61, 1.0, v100, s[6:7]
	v_cndmask_b32_e64 v60, 0, v99, s[6:7]
	v_mul_f32_e32 v52, 0x45800000, v51
	v_cndmask_b32_e32 v51, v51, v52, vcc
	v_mul_f32_e32 v52, v217, v51
	v_pk_mul_f32 v[62:63], v[62:63], v[52:53] op_sel_hi:[1,0]
	v_mov_b32_e32 v104, v66
	v_pk_mul_f32 v[62:63], v[64:65], v[62:63]
	v_mov_b32_e32 v64, v38
	v_mov_b32_e32 v65, v47
	v_pk_mul_f32 v[64:65], v[64:65], v[52:53] op_sel_hi:[1,0]
	v_mov_b32_e32 v102, v62
	v_pk_mul_f32 v[64:65], v[90:91], v[64:65]
	v_mov_b32_e32 v105, v71
	v_pk_mul_f32 v[90:91], v[54:55], v[64:65]
	v_mov_b32_e32 v103, v65
	v_pk_fma_f32 v[90:91], v[56:57], v[62:63], v[90:91]
	v_mov_b32_e32 v57, v55
	v_mov_b32_e32 v65, v63
	v_pk_mul_f32 v[54:55], v[56:57], v[64:65]
	v_mov_b32_e32 v56, v48
	v_mov_b32_e32 v57, v41
	v_pk_mul_f32 v[56:57], v[56:57], v[52:53] op_sel_hi:[1,0]
	v_mov_b32_e32 v62, v76
	v_mov_b32_e32 v63, v81
	v_pk_mul_f32 v[56:57], v[62:63], v[56:57]
	v_mov_b32_e32 v62, v40
	v_mov_b32_e32 v63, v49
	v_pk_mul_f32 v[62:63], v[62:63], v[52:53] op_sel_hi:[1,0]
	v_mov_b32_e32 v64, v80
	v_mov_b32_e32 v65, v77
	v_pk_mul_f32 v[62:63], v[64:65], v[62:63]
	v_pk_fma_f32 v[54:55], v[92:93], v[102:103], v[54:55] neg_lo:[0,0,1] neg_hi:[0,0,1]
	v_pk_mul_f32 v[64:65], v[58:59], v[62:63]
	v_mov_b32_e32 v93, v61
	v_pk_fma_f32 v[64:65], v[60:61], v[56:57], v[64:65]
	v_mov_b32_e32 v103, v63
	v_mov_b32_e32 v61, v59
	v_mov_b32_e32 v63, v57
	v_mov_b32_e32 v92, v58
	v_mov_b32_e32 v102, v56
	v_pk_mul_f32 v[56:57], v[60:61], v[62:63]
	v_mov_b32_e32 v106, v70
	v_pk_fma_f32 v[56:57], v[92:93], v[102:103], v[56:57] neg_lo:[0,0,1] neg_hi:[0,0,1]
	v_mov_b32_e32 v102, v42
	v_mov_b32_e32 v103, v35
	v_pk_mul_f32 v[102:103], v[102:103], v[52:53] op_sel_hi:[1,0]
	v_mov_b32_e32 v107, v67
	v_pk_mul_f32 v[102:103], v[104:105], v[102:103]
	v_mov_b32_e32 v104, v34
	v_mov_b32_e32 v105, v43
	v_pk_mul_f32 v[104:105], v[104:105], v[52:53] op_sel_hi:[1,0]
	v_cndmask_b32_e64 v59, 0, v89, s[6:7]
	v_cndmask_b32_e64 v58, 1.0, v86, s[6:7]
	v_pk_mul_f32 v[104:105], v[106:107], v[104:105]
	v_cndmask_b32_e64 v61, 1.0, v88, s[6:7]
	v_cndmask_b32_e64 v60, 0, v87, s[6:7]
	v_pk_mul_f32 v[106:107], v[58:59], v[104:105]
	v_mov_b32_e32 v109, v61
	v_pk_fma_f32 v[106:107], v[60:61], v[102:103], v[106:107]
	v_mov_b32_e32 v111, v105
	v_mov_b32_e32 v61, v59
	v_mov_b32_e32 v105, v103
	v_mov_b32_e32 v108, v58
	v_pk_mul_f32 v[58:59], v[60:61], v[104:105]
	v_mov_b32_e32 v60, v44
	v_mov_b32_e32 v61, v37
	v_mov_b32_e32 v110, v102
	v_pk_mul_f32 v[60:61], v[60:61], v[52:53] op_sel_hi:[1,0]
	v_mov_b32_e32 v102, v68
	v_mov_b32_e32 v103, v73
	v_pk_mul_f32 v[60:61], v[102:103], v[60:61]
	v_mov_b32_e32 v102, v36
	v_mov_b32_e32 v103, v45
	v_pk_mul_f32 v[52:53], v[102:103], v[52:53] op_sel_hi:[1,0]
	v_mov_b32_e32 v102, v72
	v_mov_b32_e32 v103, v69
	v_cndmask_b32_e64 v63, 0, v85, s[6:7]
	v_cndmask_b32_e64 v62, 1.0, v82, s[6:7]
	v_pk_mul_f32 v[52:53], v[102:103], v[52:53]
	v_cndmask_b32_e64 v93, 1.0, v84, s[6:7]
	v_cndmask_b32_e64 v92, 0, v83, s[6:7]
	v_pk_mul_f32 v[102:103], v[62:63], v[52:53]
	v_pk_fma_f32 v[58:59], v[108:109], v[110:111], v[58:59] neg_lo:[0,0,1] neg_hi:[0,0,1]
	v_pk_fma_f32 v[102:103], v[92:93], v[60:61], v[102:103]
	v_mov_b32_e32 v105, v93
	v_mov_b32_e32 v109, v53
	v_mov_b32_e32 v93, v63
	v_mov_b32_e32 v53, v61
	v_mov_b32_e32 v104, v62
	v_mov_b32_e32 v108, v60
	v_pk_mul_f32 v[52:53], v[92:93], v[52:53]
	v_mov_b32_e32 v207, v1
	v_pk_fma_f32 v[60:61], v[104:105], v[108:109], v[52:53] neg_lo:[0,0,1] neg_hi:[0,0,1]
	v_lshlrev_b32_e32 v52, 7, v50
	v_mov_b32_e32 v53, v1
	v_lshl_add_u64 v[52:53], s[2:3], 0, v[52:53]
	v_lshl_add_u64 v[62:63], v[52:53], 0, v[206:207]
	v_cvt_pk_bf16_f32 v52, v54, v55
	v_cvt_pk_bf16_f32 v53, v56, v57
	v_cvt_pk_bf16_f32 v54, v58, v59
	v_cvt_pk_bf16_f32 v55, v60, v61
	global_store_dwordx4 v[62:63], v[52:55], off sc1
	s_nop 1
	v_cvt_pk_bf16_f32 v52, v90, v91
	v_cvt_pk_bf16_f32 v53, v64, v65
	v_cvt_pk_bf16_f32 v54, v106, v107
	v_cvt_pk_bf16_f32 v55, v102, v103
	global_store_dwordx4 v[62:63], v[52:55], off offset:64 sc1
	s_cbranch_execz .LBB0_573

; DI u16 f2bf(float a) { return (u16)(pack_bf16(a, 0.f) & 0xffffu); }
;   DI void operator()(const f32x4 (&acc)[2][2][4][2], const Unit& u, int wr, int wc, int fr, int fq) const {
;     ...
;         const int t = u.pm * BM + ai * HALF + wr * 64 + m * 16 + fr;
;         int b, pos;
;         if (rowbase == 0) { b = t >> 12; pos = t & 4095; } else { b = t >> 8; pos = 4096 + (t & 255); }
;         u16* base = qkv + (size_t)(b * 32 + chunk) * LTOT * 64;
;         if (isV) {
; #pragma unroll
;           for (int bj = 0; bj < 2; ++bj)
; #pragma unroll
;             for (int n = 0; n < 2; ++n)
; #pragma unroll
;               for (int e = 0; e < 4; ++e) {
;                 int d = 32 * bj + 8 * fq + 4 * n + e;
;                 base[(size_t)d * LTOT + pos] = f2bf(acc[ai][bj][m][n][e]);
;               }
;         } else {
;           float ss = 0.f;
; #pragma unroll
;           for (int bj = 0; bj < 2; ++bj)
; #pragma unroll
;             for (int n = 0; n < 2; ++n)
; #pragma unroll
;               for (int e = 0; e < 4; ++e) ss += acc[ai][bj][m][n][e] * acc[ai][bj][m][n][e];
;           ss += __shfl_xor(ss, 16);
;           ss += __shfl_xor(ss, 32);
;           const float rinv = rsqrtf(ss * (1.f / 64.f) + EPSV);
;           float o1[8], o2[8];
; #pragma unroll
;           for (int n = 0; n < 2; ++n) {
;             f32x4 cs0 = (f32x4){1.f, 0.f, 1.f, 0.f}, cs1 = cs0;
;             if (ropeT) { cs0 = csr[m & 1][n][0]; cs1 = csr[m & 1][n][1]; }
; #pragma unroll
;             for (int e = 0; e < 4; ++e) {
;               float x1 = acc[ai][0][m][n][e] * (rinv * qs) * g4[0][n][e];
;               float x2 = acc[ai][1][m][n][e] * (rinv * qs) * g4[1][n][e];
;               float c = (e < 2) ? cs0[2 * e] : cs1[2 * (e - 2)], s = (e < 2) ? cs0[2 * e + 1] : cs1[2 * (e - 2) + 1];
;               o1[n * 4 + e] = x1 * c - x2 * s;
;               o2[n * 4 + e] = x2 * c + x1 * s;
;             }
;           }
;           u16* dst = base + (size_t)pos * 64 + 8 * fq;
;           *(uint4*)(dst) = make_uint4(pack_bf16(o1[0], o1[1]), pack_bf16(o1[2], o1[3]), pack_bf16(o1[4], o1[5]), pack_bf16(o1[6], o1[7]));
;           *(uint4*)(dst + 32) = make_uint4(pack_bf16(o2[0], o2[1]), pack_bf16(o2[2], o2[3]), pack_bf16(o2[4], o2[5]), pack_bf16(o2[6], o2[7]));
.LBB0_564:
	s_add_i32 s2, s49, 0xa0
	s_and_b32 s3, s2, 0xfe0
	s_ashr_i32 s2, s2, 7
	s_andn2_b32 s2, s2, 31
	s_add_i32 s2, s2, s48
	v_or_b32_e32 v34, s3, v214
	s_mul_hi_i32 s3, s2, 0x88000
	s_mul_i32 s2, s2, 0x88000
	s_add_u32 s2, s88, s2
	s_addc_u32 s3, s89, s3
	s_and_b64 vcc, exec, s[8:9]
	s_mov_b64 s[10:11], -1
	s_cbranch_vccnz .LBB0_566
	v_mul_f32_e32 v0, v31, v31
	v_fmac_f32_e32 v0, v30, v30
	v_fmac_f32_e32 v0, v32, v32
	v_fmac_f32_e32 v0, v33, v33
	v_fmac_f32_e32 v0, v26, v26
	v_fmac_f32_e32 v0, v27, v27
	v_fmac_f32_e32 v0, v28, v28
	v_fmac_f32_e32 v0, v29, v29
	v_pk_mul_f32 v[38:39], v[22:23], v[22:23]
	v_pk_mul_f32 v[36:37], v[24:25], v[24:25]
	v_add_f32_e32 v0, v38, v0
	v_add_f32_e32 v0, v39, v0
	v_add_f32_e32 v0, v36, v0
	v_add_f32_e32 v0, v37, v0
	v_pk_mul_f32 v[38:39], v[18:19], v[18:19]
	v_pk_mul_f32 v[36:37], v[20:21], v[20:21]
	v_add_f32_e32 v0, v38, v0
	v_add_f32_e32 v0, v39, v0
	v_add_f32_e32 v0, v36, v0
	v_add_f32_e32 v0, v37, v0
	s_mov_b32 s10, 0x800000
	v_mov_b32_e32 v35, v0
	s_nop 1
	v_permlane16_swap_b32_e32 v0, v35
	v_mov_b32_e32 v44, v30
	v_mov_b32_e32 v45, v23
	s_waitcnt vmcnt(0)
	v_mov_b32_e32 v46, v74
	v_mov_b32_e32 v47, v79
	s_waitcnt lgkmcnt(0)
	v_add_f32_e32 v0, v0, v35
	v_mov_b32_e32 v48, v78
	v_mov_b32_e32 v49, v75
	v_mov_b32_e32 v35, v0
	s_nop 1
	v_permlane32_swap_b32_e32 v0, v35
	v_cndmask_b32_e64 v37, 0, v129, s[6:7]
	v_cndmask_b32_e64 v36, 1.0, v126, s[6:7]
	v_cndmask_b32_e64 v39, 1.0, v128, s[6:7]
	v_cndmask_b32_e64 v38, 0, v127, s[6:7]
	s_waitcnt lgkmcnt(0)
	v_add_f32_e32 v0, v0, v35
	v_fmamk_f32 v0, v0, 0x3c800000, v210
	v_mul_f32_e32 v35, 0x4b800000, v0
	v_cmp_gt_f32_e32 vcc, s10, v0
	v_mov_b32_e32 v51, v39
	v_mov_b32_e32 v50, v36
	v_cndmask_b32_e32 v0, v0, v35, vcc
	v_rsq_f32_e32 v0, v0
	v_cndmask_b32_e64 v41, 0, v125, s[6:7]
	v_cndmask_b32_e64 v40, 1.0, v122, s[6:7]
	v_cndmask_b32_e64 v43, 1.0, v124, s[6:7]
	v_mul_f32_e32 v35, 0x45800000, v0
	v_cndmask_b32_e32 v0, v0, v35, vcc
	v_mul_f32_e32 v0, v217, v0
	v_pk_mul_f32 v[44:45], v[44:45], v[0:1] op_sel_hi:[1,0]
	v_cndmask_b32_e64 v42, 0, v123, s[6:7]
	v_pk_mul_f32 v[44:45], v[46:47], v[44:45]
	v_mov_b32_e32 v46, v22
	v_mov_b32_e32 v47, v31
	v_pk_mul_f32 v[46:47], v[46:47], v[0:1] op_sel_hi:[1,0]
	v_mov_b32_e32 v52, v44
	v_pk_mul_f32 v[46:47], v[48:49], v[46:47]
	v_mov_b32_e32 v54, v66
	v_pk_mul_f32 v[48:49], v[36:37], v[46:47]
	v_mov_b32_e32 v53, v47
	v_pk_fma_f32 v[48:49], v[38:39], v[44:45], v[48:49]
	v_mov_b32_e32 v39, v37
	v_mov_b32_e32 v47, v45
	v_pk_mul_f32 v[36:37], v[38:39], v[46:47]
	v_mov_b32_e32 v38, v32
	v_mov_b32_e32 v39, v25
	v_pk_mul_f32 v[38:39], v[38:39], v[0:1] op_sel_hi:[1,0]
	v_mov_b32_e32 v44, v76
	v_mov_b32_e32 v45, v81
	v_pk_mul_f32 v[38:39], v[44:45], v[38:39]
	v_mov_b32_e32 v44, v24
	v_mov_b32_e32 v45, v33
	v_pk_mul_f32 v[44:45], v[44:45], v[0:1] op_sel_hi:[1,0]
	v_mov_b32_e32 v46, v80
	v_mov_b32_e32 v47, v77
	v_pk_mul_f32 v[44:45], v[46:47], v[44:45]
	v_pk_fma_f32 v[36:37], v[50:51], v[52:53], v[36:37] neg_lo:[0,0,1] neg_hi:[0,0,1]
	v_pk_mul_f32 v[46:47], v[40:41], v[44:45]
	v_mov_b32_e32 v51, v43
	v_pk_fma_f32 v[46:47], v[42:43], v[38:39], v[46:47]
	v_mov_b32_e32 v53, v45
	v_mov_b32_e32 v43, v41
	v_mov_b32_e32 v45, v39
	v_mov_b32_e32 v50, v40
	v_mov_b32_e32 v52, v38
	v_pk_mul_f32 v[38:39], v[42:43], v[44:45]
	v_mov_b32_e32 v55, v71
	v_pk_fma_f32 v[38:39], v[50:51], v[52:53], v[38:39] neg_lo:[0,0,1] neg_hi:[0,0,1]
	v_mov_b32_e32 v52, v26
	v_mov_b32_e32 v53, v19
	v_pk_mul_f32 v[52:53], v[52:53], v[0:1] op_sel_hi:[1,0]
	v_mov_b32_e32 v56, v70
	v_pk_mul_f32 v[52:53], v[54:55], v[52:53]
	v_mov_b32_e32 v54, v18
	v_mov_b32_e32 v55, v27
	v_pk_mul_f32 v[54:55], v[54:55], v[0:1] op_sel_hi:[1,0]
	v_mov_b32_e32 v57, v67
	v_cndmask_b32_e64 v41, 0, v121, s[6:7]
	v_cndmask_b32_e64 v40, 1.0, v118, s[6:7]
	v_pk_mul_f32 v[54:55], v[56:57], v[54:55]
	v_cndmask_b32_e64 v43, 1.0, v120, s[6:7]
	v_cndmask_b32_e64 v42, 0, v119, s[6:7]
	v_pk_mul_f32 v[56:57], v[40:41], v[54:55]
	v_mov_b32_e32 v59, v43
	v_pk_fma_f32 v[56:57], v[42:43], v[52:53], v[56:57]
	v_mov_b32_e32 v61, v55
	v_mov_b32_e32 v43, v41
	v_mov_b32_e32 v55, v53
	v_mov_b32_e32 v58, v40
	v_pk_mul_f32 v[40:41], v[42:43], v[54:55]
	v_mov_b32_e32 v42, v28
	v_mov_b32_e32 v43, v21
	v_mov_b32_e32 v60, v52
	v_pk_mul_f32 v[42:43], v[42:43], v[0:1] op_sel_hi:[1,0]
	v_mov_b32_e32 v52, v68
	v_mov_b32_e32 v53, v73
	v_pk_mul_f32 v[42:43], v[52:53], v[42:43]
	v_mov_b32_e32 v52, v20
	v_mov_b32_e32 v53, v29
	v_pk_mul_f32 v[52:53], v[52:53], v[0:1] op_sel_hi:[1,0]
	v_mov_b32_e32 v54, v72
	v_mov_b32_e32 v55, v69
	v_cndmask_b32_e64 v45, 0, v117, s[6:7]
	v_cndmask_b32_e64 v44, 1.0, v114, s[6:7]
	v_pk_mul_f32 v[52:53], v[54:55], v[52:53]
	v_cndmask_b32_e64 v51, 1.0, v116, s[6:7]
	v_cndmask_b32_e64 v50, 0, v115, s[6:7]
	v_pk_mul_f32 v[54:55], v[44:45], v[52:53]
	v_pk_fma_f32 v[40:41], v[58:59], v[60:61], v[40:41] neg_lo:[0,0,1] neg_hi:[0,0,1]
	v_pk_fma_f32 v[54:55], v[50:51], v[42:43], v[54:55]
	v_mov_b32_e32 v59, v51
	v_mov_b32_e32 v61, v53
	v_mov_b32_e32 v51, v45
	v_mov_b32_e32 v53, v43
	v_mov_b32_e32 v58, v44
	v_mov_b32_e32 v60, v42
	v_pk_mul_f32 v[42:43], v[50:51], v[52:53]
	v_lshlrev_b32_e32 v0, 7, v34
	v_pk_fma_f32 v[42:43], v[58:59], v[60:61], v[42:43] neg_lo:[0,0,1] neg_hi:[0,0,1]
	v_lshl_add_u64 v[44:45], s[2:3], 0, v[0:1]
	v_mov_b32_e32 v207, v1
	v_lshl_add_u64 v[44:45], v[44:45], 0, v[206:207]
	v_cvt_pk_bf16_f32 v36, v36, v37
	v_cvt_pk_bf16_f32 v37, v38, v39
	v_cvt_pk_bf16_f32 v38, v40, v41
	v_cvt_pk_bf16_f32 v39, v42, v43
	global_store_dwordx4 v[44:45], v[36:39], off sc1
	s_mov_b64 s[10:11], 0
	s_nop 0
	v_cvt_pk_bf16_f32 v36, v48, v49
	v_cvt_pk_bf16_f32 v37, v46, v47
	v_cvt_pk_bf16_f32 v38, v56, v57
	v_cvt_pk_bf16_f32 v39, v54, v55
	global_store_dwordx4 v[44:45], v[36:39], off offset:64 sc1

; DI u16 f2bf(float a) { return (u16)(pack_bf16(a, 0.f) & 0xffffu); }
;   DI void operator()(const f32x4 (&acc)[2][2][4][2], const Unit& u, int wr, int wc, int fr, int fq) const {
;     ...
;         const int t = u.pm * BM + ai * HALF + wr * 64 + m * 16 + fr;
;         int b, pos;
;         if (rowbase == 0) { b = t >> 12; pos = t & 4095; } else { b = t >> 8; pos = 4096 + (t & 255); }
;         u16* base = qkv + (size_t)(b * 32 + chunk) * LTOT * 64;
;         if (isV) {
; #pragma unroll
;           for (int bj = 0; bj < 2; ++bj)
; #pragma unroll
;             for (int n = 0; n < 2; ++n)
; #pragma unroll
;               for (int e = 0; e < 4; ++e) {
;                 int d = 32 * bj + 8 * fq + 4 * n + e;
;                 base[(size_t)d * LTOT + pos] = f2bf(acc[ai][bj][m][n][e]);
;               }
;         } else {
;           float ss = 0.f;
; #pragma unroll
;           for (int bj = 0; bj < 2; ++bj)
; #pragma unroll
;             for (int n = 0; n < 2; ++n)
; #pragma unroll
;               for (int e = 0; e < 4; ++e) ss += acc[ai][bj][m][n][e] * acc[ai][bj][m][n][e];
;           ss += __shfl_xor(ss, 16);
;           ss += __shfl_xor(ss, 32);
;           const float rinv = rsqrtf(ss * (1.f / 64.f) + EPSV);
;           float o1[8], o2[8];
; #pragma unroll
;           for (int n = 0; n < 2; ++n) {
;             f32x4 cs0 = (f32x4){1.f, 0.f, 1.f, 0.f}, cs1 = cs0;
;             if (ropeT) { cs0 = csr[m & 1][n][0]; cs1 = csr[m & 1][n][1]; }
; #pragma unroll
;             for (int e = 0; e < 4; ++e) {
;               float x1 = acc[ai][0][m][n][e] * (rinv * qs) * g4[0][n][e];
;               float x2 = acc[ai][1][m][n][e] * (rinv * qs) * g4[1][n][e];
;               float c = (e < 2) ? cs0[2 * e] : cs1[2 * (e - 2)], s = (e < 2) ? cs0[2 * e + 1] : cs1[2 * (e - 2) + 1];
;               o1[n * 4 + e] = x1 * c - x2 * s;
;               o2[n * 4 + e] = x2 * c + x1 * s;
;             }
;           }
;           u16* dst = base + (size_t)pos * 64 + 8 * fq;
;           *(uint4*)(dst) = make_uint4(pack_bf16(o1[0], o1[1]), pack_bf16(o1[2], o1[3]), pack_bf16(o1[4], o1[5]), pack_bf16(o1[6], o1[7]));
;           *(uint4*)(dst + 32) = make_uint4(pack_bf16(o2[0], o2[1]), pack_bf16(o2[2], o2[3]), pack_bf16(o2[4], o2[5]), pack_bf16(o2[6], o2[7]));
.LBB0_568:
	s_addk_i32 s49, 0xb0
	s_and_b32 s2, s49, 0xff0
	v_or_b32_e32 v18, s2, v214
	s_ashr_i32 s2, s49, 7
	s_andn2_b32 s2, s2, 31
	s_add_i32 s2, s2, s48
	s_mul_hi_i32 s3, s2, 0x88000
	s_mul_i32 s2, s2, 0x88000
	s_add_u32 s2, s88, s2
	s_addc_u32 s3, s89, s3
	s_and_b64 vcc, exec, s[8:9]
	s_mov_b64 s[8:9], -1
	s_cbranch_vccnz .LBB0_570
	v_mul_f32_e32 v0, v15, v15
	v_fmac_f32_e32 v0, v14, v14
	v_fmac_f32_e32 v0, v16, v16
	v_fmac_f32_e32 v0, v17, v17
	v_fmac_f32_e32 v0, v10, v10
	v_fmac_f32_e32 v0, v11, v11
	v_fmac_f32_e32 v0, v12, v12
	v_fmac_f32_e32 v0, v13, v13
	v_pk_mul_f32 v[22:23], v[6:7], v[6:7]
	v_pk_mul_f32 v[20:21], v[8:9], v[8:9]
	v_add_f32_e32 v0, v22, v0
	v_add_f32_e32 v0, v23, v0
	v_add_f32_e32 v0, v20, v0
	v_add_f32_e32 v0, v21, v0
	v_pk_mul_f32 v[22:23], v[2:3], v[2:3]
	v_pk_mul_f32 v[20:21], v[4:5], v[4:5]
	v_add_f32_e32 v0, v22, v0
	v_add_f32_e32 v0, v23, v0
	v_add_f32_e32 v0, v20, v0
	v_add_f32_e32 v0, v21, v0
	s_mov_b32 s8, 0x800000
	v_mov_b32_e32 v19, v0
	s_nop 1
	v_permlane16_swap_b32_e32 v0, v19
	v_mov_b32_e32 v28, v14
	v_mov_b32_e32 v29, v7
	v_mov_b32_e32 v30, v74
	v_mov_b32_e32 v31, v79
	s_waitcnt lgkmcnt(0)
	v_add_f32_e32 v0, v0, v19
	v_mov_b32_e32 v79, v75
	v_cndmask_b32_e64 v21, 0, v97, s[6:7]
	v_mov_b32_e32 v19, v0
	s_nop 1
	v_permlane32_swap_b32_e32 v0, v19
	v_cndmask_b32_e64 v20, 1.0, v94, s[6:7]
	v_cndmask_b32_e64 v23, 1.0, v96, s[6:7]
	v_cndmask_b32_e64 v22, 0, v95, s[6:7]
	v_mov_b32_e32 v35, v23
	s_waitcnt lgkmcnt(0)
	v_add_f32_e32 v0, v0, v19
	v_fmamk_f32 v0, v0, 0x3c800000, v210
	v_mul_f32_e32 v19, 0x4b800000, v0
	v_cmp_gt_f32_e32 vcc, s8, v0
	v_mov_b32_e32 v34, v20
	v_cndmask_b32_e64 v25, 0, v101, s[6:7]
	v_cndmask_b32_e32 v0, v0, v19, vcc
	v_rsq_f32_e32 v0, v0
	v_cndmask_b32_e64 v24, 1.0, v98, s[6:7]
	v_cndmask_b32_e64 v27, 1.0, v100, s[6:7]
	v_cndmask_b32_e64 v26, 0, v99, s[6:7]
	v_mul_f32_e32 v19, 0x45800000, v0
	v_cndmask_b32_e32 v0, v0, v19, vcc
	v_mul_f32_e32 v0, v217, v0
	v_pk_mul_f32 v[28:29], v[28:29], v[0:1] op_sel_hi:[1,0]
	v_mov_b32_e32 v38, v66
	v_pk_mul_f32 v[28:29], v[30:31], v[28:29]
	v_mov_b32_e32 v30, v6
	v_mov_b32_e32 v31, v15
	v_pk_mul_f32 v[30:31], v[30:31], v[0:1] op_sel_hi:[1,0]
	v_mov_b32_e32 v36, v28
	v_pk_mul_f32 v[30:31], v[78:79], v[30:31]
	v_mov_b32_e32 v39, v71
	v_pk_mul_f32 v[32:33], v[20:21], v[30:31]
	v_mov_b32_e32 v37, v31
	v_pk_fma_f32 v[32:33], v[22:23], v[28:29], v[32:33]
	v_mov_b32_e32 v23, v21
	v_mov_b32_e32 v31, v29
	v_pk_mul_f32 v[20:21], v[22:23], v[30:31]
	v_mov_b32_e32 v22, v16
	v_mov_b32_e32 v23, v9
	v_pk_mul_f32 v[22:23], v[22:23], v[0:1] op_sel_hi:[1,0]
	v_mov_b32_e32 v28, v76
	v_mov_b32_e32 v29, v81
	v_pk_mul_f32 v[22:23], v[28:29], v[22:23]
	v_mov_b32_e32 v28, v8
	v_mov_b32_e32 v29, v17
	v_pk_mul_f32 v[28:29], v[28:29], v[0:1] op_sel_hi:[1,0]
	v_mov_b32_e32 v81, v77
	v_pk_mul_f32 v[28:29], v[80:81], v[28:29]
	v_pk_fma_f32 v[20:21], v[34:35], v[36:37], v[20:21] neg_lo:[0,0,1] neg_hi:[0,0,1]
	v_pk_mul_f32 v[30:31], v[24:25], v[28:29]
	v_mov_b32_e32 v35, v27
	v_pk_fma_f32 v[30:31], v[26:27], v[22:23], v[30:31]
	v_mov_b32_e32 v37, v29
	v_mov_b32_e32 v27, v25
	v_mov_b32_e32 v29, v23
	v_mov_b32_e32 v34, v24
	v_mov_b32_e32 v36, v22
	v_pk_mul_f32 v[22:23], v[26:27], v[28:29]
	v_mov_b32_e32 v71, v67
	v_pk_fma_f32 v[22:23], v[34:35], v[36:37], v[22:23] neg_lo:[0,0,1] neg_hi:[0,0,1]
	v_mov_b32_e32 v36, v10
	v_mov_b32_e32 v37, v3
	v_pk_mul_f32 v[36:37], v[36:37], v[0:1] op_sel_hi:[1,0]
	v_cndmask_b32_e64 v25, 0, v89, s[6:7]
	v_pk_mul_f32 v[36:37], v[38:39], v[36:37]
	v_mov_b32_e32 v38, v2
	v_mov_b32_e32 v39, v11
	v_pk_mul_f32 v[38:39], v[38:39], v[0:1] op_sel_hi:[1,0]
	v_cndmask_b32_e64 v24, 1.0, v86, s[6:7]
	v_pk_mul_f32 v[38:39], v[70:71], v[38:39]
	v_cndmask_b32_e64 v27, 1.0, v88, s[6:7]
	v_cndmask_b32_e64 v26, 0, v87, s[6:7]
	v_pk_mul_f32 v[40:41], v[24:25], v[38:39]
	v_mov_b32_e32 v43, v27
	v_pk_fma_f32 v[40:41], v[26:27], v[36:37], v[40:41]
	v_mov_b32_e32 v45, v39
	v_mov_b32_e32 v27, v25
	v_mov_b32_e32 v39, v37
	v_mov_b32_e32 v42, v24
	v_pk_mul_f32 v[24:25], v[26:27], v[38:39]
	v_mov_b32_e32 v26, v12
	v_mov_b32_e32 v27, v5
	v_mov_b32_e32 v44, v36
	v_pk_mul_f32 v[26:27], v[26:27], v[0:1] op_sel_hi:[1,0]
	v_mov_b32_e32 v36, v68
	v_mov_b32_e32 v37, v73
	v_pk_mul_f32 v[26:27], v[36:37], v[26:27]
	v_mov_b32_e32 v36, v4
	v_mov_b32_e32 v37, v13
	v_pk_mul_f32 v[36:37], v[36:37], v[0:1] op_sel_hi:[1,0]
	v_mov_b32_e32 v73, v69
	v_cndmask_b32_e64 v29, 0, v85, s[6:7]
	v_cndmask_b32_e64 v28, 1.0, v82, s[6:7]
	v_pk_mul_f32 v[36:37], v[72:73], v[36:37]
	v_cndmask_b32_e64 v35, 1.0, v84, s[6:7]
	v_cndmask_b32_e64 v34, 0, v83, s[6:7]
	v_pk_mul_f32 v[38:39], v[28:29], v[36:37]
	v_pk_fma_f32 v[24:25], v[42:43], v[44:45], v[24:25] neg_lo:[0,0,1] neg_hi:[0,0,1]
	v_pk_fma_f32 v[38:39], v[34:35], v[26:27], v[38:39]
	v_mov_b32_e32 v43, v35
	v_mov_b32_e32 v45, v37
	v_mov_b32_e32 v35, v29
	v_mov_b32_e32 v37, v27
	v_mov_b32_e32 v42, v28
	v_mov_b32_e32 v44, v26
	v_pk_mul_f32 v[26:27], v[34:35], v[36:37]
	v_lshlrev_b32_e32 v0, 7, v18
	v_pk_fma_f32 v[26:27], v[42:43], v[44:45], v[26:27] neg_lo:[0,0,1] neg_hi:[0,0,1]
	v_lshl_add_u64 v[28:29], s[2:3], 0, v[0:1]
	v_mov_b32_e32 v207, v1
	v_lshl_add_u64 v[28:29], v[28:29], 0, v[206:207]
	v_cvt_pk_bf16_f32 v20, v20, v21
	v_cvt_pk_bf16_f32 v21, v22, v23
	v_cvt_pk_bf16_f32 v22, v24, v25
	v_cvt_pk_bf16_f32 v23, v26, v27
	global_store_dwordx4 v[28:29], v[20:23], off sc1
	s_mov_b64 s[8:9], 0
	s_nop 0
	v_cvt_pk_bf16_f32 v20, v32, v33
	v_cvt_pk_bf16_f32 v21, v30, v31
	v_cvt_pk_bf16_f32 v22, v40, v41
	v_cvt_pk_bf16_f32 v23, v38, v39
	global_store_dwordx4 v[28:29], v[20:23], off offset:64 sc1

;   DI void operator()(const f32x4 (&acc)[2][2][4][2], const Unit& u, int wr, int wc, int fr, int fq) const {
;     ...
;     const float* gam = qkn + gi * 64;
;     const float qs = (gi == 0 || gi == 2 || gi == 4) ? 0.125f * LOG2E : 1.f;
;     f32x4 g4[2][2];
; #pragma unroll
;     for (int bj = 0; bj < 2; ++bj)
; #pragma unroll
;       for (int n = 0; n < 2; ++n) g4[bj][n] = *(const f32x4*)(gam + 32 * bj + 8 * fq + 4 * n);
;     ...
;         const int t = u.pm * BM + ai * HALF + wr * 64 + m * 16 + fr;
;         int b, pos;
;         if (rowbase == 0) { b = t >> 12; pos = t & 4095; } else { b = t >> 8; pos = 4096 + (t & 255); }
;         u16* base = qkv + (size_t)(b * 32 + chunk) * LTOT * 64;
;         if (isV) {
; #pragma unroll
;           for (int bj = 0; bj < 2; ++bj)
; #pragma unroll
;             for (int n = 0; n < 2; ++n)
; #pragma unroll
;               for (int e = 0; e < 4; ++e) {
;                 int d = 32 * bj + 8 * fq + 4 * n + e;
;                 base[(size_t)d * LTOT + pos] = f2bf(acc[ai][bj][m][n][e]);
;               }
;         } else {
;           float ss = 0.f;
; #pragma unroll
;           for (int bj = 0; bj < 2; ++bj)
; #pragma unroll
;             for (int n = 0; n < 2; ++n)
; #pragma unroll
;               for (int e = 0; e < 4; ++e) ss += acc[ai][bj][m][n][e] * acc[ai][bj][m][n][e];
;           ss += __shfl_xor(ss, 16);
;           ss += __shfl_xor(ss, 32);
;           const float rinv = rsqrtf(ss * (1.f / 64.f) + EPSV);
;           float o1[8], o2[8];
; #pragma unroll
;           for (int n = 0; n < 2; ++n) {
;             f32x4 cs0 = (f32x4){1.f, 0.f, 1.f, 0.f}, cs1 = cs0;
;             if (ropeT) { cs0 = csr[m & 1][n][0]; cs1 = csr[m & 1][n][1]; }
; #pragma unroll
;             for (int e = 0; e < 4; ++e) {
;               float x1 = acc[ai][0][m][n][e] * (rinv * qs) * g4[0][n][e];
;               float x2 = acc[ai][1][m][n][e] * (rinv * qs) * g4[1][n][e];
;               float c = (e < 2) ? cs0[2 * e] : cs1[2 * (e - 2)], s = (e < 2) ? cs0[2 * e + 1] : cs1[2 * (e - 2) + 1];
;               o1[n * 4 + e] = x1 * c - x2 * s;
;               o2[n * 4 + e] = x2 * c + x1 * s;
;             }
;           }
;           u16* dst = base + (size_t)pos * 64 + 8 * fq;
;           *(uint4*)(dst) = make_uint4(pack_bf16(o1[0], o1[1]), pack_bf16(o1[2], o1[3]), pack_bf16(o1[4], o1[5]), pack_bf16(o1[6], o1[7]));
.LBB0_841:
	v_readlane_b32 s7, v254, 39
	v_readlane_b32 s16, v252, 0
	s_mulk_i32 s7, 0x600
	v_readlane_b32 s18, v252, 2
	v_readlane_b32 s19, v252, 3
	s_add_u32 s7, s18, s7
	s_addc_u32 s9, s19, 0
	s_lshl_b32 s6, s6, 2
	s_add_u32 s6, s7, s6
	s_addc_u32 s7, s9, 0
	v_lshlrev_b32_e32 v0, 5, v148
	global_load_dwordx4 v[82:85], v0, s[6:7] offset:16
	global_load_dwordx4 v[90:93], v0, s[6:7]
	global_load_dwordx4 v[86:89], v0, s[6:7] offset:144
	global_load_dwordx4 v[94:97], v0, s[6:7] offset:128
	s_or_b64 vcc, s[0:1], s[4:5]
	s_add_i32 s0, s15, s10
	s_ashr_i32 s0, s0, 3
	s_andn2_b32 s0, s0, 31
	s_and_b32 s1, s15, 0xc0
	s_add_i32 s0, s0, s8
	v_or_b32_e32 v152, s1, v150
	s_mul_hi_i32 s1, s0, 0x88000
	s_mul_i32 s0, s0, 0x88000
	v_lshlrev_b32_e32 v0, 3, v148
	s_add_u32 s0, s88, s0
	v_cndmask_b32_e64 v146, 0, 1, s[2:3]
	v_cndmask_b32_e32 v151, 1.0, v248, vcc
	v_or_b32_e32 v149, 0x1000, v152
	s_addc_u32 s1, s89, s1
	s_mov_b64 s[6:7], -1
	v_cmp_ne_u32_e64 s[4:5], 1, v146
	s_andn2_b64 vcc, exec, s[2:3]
	v_lshlrev_b32_e32 v146, 1, v0
	v_readlane_b32 s17, v252, 1
	v_readlane_b32 s20, v252, 4
	v_readlane_b32 s21, v252, 5
	v_readlane_b32 s22, v252, 6
	v_readlane_b32 s23, v252, 7
	v_readlane_b32 s24, v252, 8
	v_readlane_b32 s25, v252, 9
	v_readlane_b32 s26, v252, 10
	v_readlane_b32 s27, v252, 11
	v_readlane_b32 s28, v252, 12
	v_readlane_b32 s29, v252, 13
	v_readlane_b32 s30, v252, 14
	v_readlane_b32 s31, v252, 15
	s_cbranch_vccnz .LBB0_843
	v_mul_f32_e32 v0, v143, v143
	v_fmac_f32_e32 v0, v142, v142
	v_fmac_f32_e32 v0, v144, v144
	v_fmac_f32_e32 v0, v145, v145
	v_fmac_f32_e32 v0, v138, v138
	v_fmac_f32_e32 v0, v139, v139
	v_fmac_f32_e32 v0, v140, v140
	v_fmac_f32_e32 v0, v141, v141
	v_pk_mul_f32 v[156:157], v[134:135], v[134:135]
	v_pk_mul_f32 v[154:155], v[136:137], v[136:137]
	v_add_f32_e32 v0, v156, v0
	v_add_f32_e32 v0, v157, v0
	v_add_f32_e32 v0, v154, v0
	v_add_f32_e32 v0, v155, v0
	v_pk_mul_f32 v[156:157], v[130:131], v[130:131]
	v_add_f32_e32 v0, v156, v0
	v_pk_mul_f32 v[154:155], v[132:133], v[132:133]
	v_add_f32_e32 v0, v157, v0
	v_add_f32_e32 v0, v154, v0
	v_add_f32_e32 v0, v155, v0
	v_mov_b32_e32 v147, v0
	s_nop 1
	v_permlane16_swap_b32_e32 v0, v147
	s_mov_b64 s[6:7], 0
	s_waitcnt lgkmcnt(0)
	v_add_f32_e32 v0, v0, v147
	s_nop 1
	v_mov_b32_e32 v147, v0
	s_nop 1
	v_permlane32_swap_b32_e32 v0, v147
	s_waitcnt lgkmcnt(0)
	v_add_f32_e32 v0, v0, v147
	v_fmamk_f32 v0, v0, 0x3c800000, v210
	v_mul_f32_e32 v147, 0x4b800000, v0
	v_cmp_gt_f32_e32 vcc, s11, v0
	s_nop 1
	v_cndmask_b32_e32 v0, v0, v147, vcc
	v_rsq_f32_e32 v0, v0
	s_nop 0
	v_mul_f32_e32 v147, 0x45800000, v0
	v_cndmask_b32_e32 v0, v0, v147, vcc
	v_mul_f32_e32 v0, v151, v0
	v_pk_mul_f32 v[154:155], v[134:135], v[0:1] op_sel_hi:[1,0]
	v_pk_mul_f32 v[156:157], v[142:143], v[0:1] op_sel_hi:[1,0]
	s_waitcnt vmcnt(0)
	v_pk_mul_f32 v[154:155], v[94:95], v[154:155]
	v_pk_mul_f32 v[156:157], v[90:91], v[156:157]
	v_pk_mul_f32 v[160:161], v[144:145], v[0:1] op_sel_hi:[1,0]
	v_pk_fma_f32 v[158:159], v[156:157], 0, v[154:155] op_sel_hi:[1,0,1]
	v_pk_fma_f32 v[154:155], v[154:155], 0, v[156:157] op_sel_hi:[1,0,1] neg_lo:[1,0,0] neg_hi:[1,0,0]
	v_pk_mul_f32 v[156:157], v[136:137], v[0:1] op_sel_hi:[1,0]
	v_pk_mul_f32 v[160:161], v[92:93], v[160:161]
	v_pk_mul_f32 v[156:157], v[96:97], v[156:157]
	v_pk_mul_f32 v[164:165], v[138:139], v[0:1] op_sel_hi:[1,0]
	v_pk_fma_f32 v[162:163], v[160:161], 0, v[156:157] op_sel_hi:[1,0,1]
	v_pk_fma_f32 v[156:157], v[156:157], 0, v[160:161] op_sel_hi:[1,0,1] neg_lo:[1,0,0] neg_hi:[1,0,0]
	v_pk_mul_f32 v[160:161], v[130:131], v[0:1] op_sel_hi:[1,0]
	v_pk_mul_f32 v[164:165], v[82:83], v[164:165]
	v_pk_mul_f32 v[160:161], v[86:87], v[160:161]
	v_pk_mul_f32 v[168:169], v[140:141], v[0:1] op_sel_hi:[1,0]
	v_pk_fma_f32 v[166:167], v[164:165], 0, v[160:161] op_sel_hi:[1,0,1]
	v_pk_fma_f32 v[160:161], v[160:161], 0, v[164:165] op_sel_hi:[1,0,1] neg_lo:[1,0,0] neg_hi:[1,0,0]
	v_pk_mul_f32 v[164:165], v[132:133], v[0:1] op_sel_hi:[1,0]
	v_pk_mul_f32 v[168:169], v[84:85], v[168:169]
	v_pk_mul_f32 v[164:165], v[88:89], v[164:165]
	v_lshlrev_b32_e32 v0, 7, v149
	v_pk_fma_f32 v[170:171], v[168:169], 0, v[164:165] op_sel_hi:[1,0,1]
	v_pk_fma_f32 v[164:165], v[164:165], 0, v[168:169] op_sel_hi:[1,0,1] neg_lo:[1,0,0] neg_hi:[1,0,0]
	v_lshl_add_u64 v[168:169], s[0:1], 0, v[0:1]
	v_mov_b32_e32 v147, v1
	v_lshl_add_u64 v[168:169], v[168:169], 0, v[146:147]
	v_cvt_pk_bf16_f32 v154, v154, v155
	v_cvt_pk_bf16_f32 v155, v156, v157
	v_cvt_pk_bf16_f32 v156, v160, v161
	v_cvt_pk_bf16_f32 v157, v164, v165
	global_store_dwordx4 v[168:169], v[154:157], off sc1
	s_nop 1
	v_cvt_pk_bf16_f32 v154, v158, v159
	v_cvt_pk_bf16_f32 v155, v162, v163
	v_cvt_pk_bf16_f32 v156, v166, v167
	v_cvt_pk_bf16_f32 v157, v170, v171
	global_store_dwordx4 v[168:169], v[154:157], off offset:64 sc1

; DI u16 f2bf(float a) { return (u16)(pack_bf16(a, 0.f) & 0xffffu); }
;   DI void operator()(const f32x4 (&acc)[2][2][4][2], const Unit& u, int wr, int wc, int fr, int fq) const {
;     ...
;         const int t = u.pm * BM + ai * HALF + wr * 64 + m * 16 + fr;
;         int b, pos;
;         if (rowbase == 0) { b = t >> 12; pos = t & 4095; } else { b = t >> 8; pos = 4096 + (t & 255); }
;         u16* base = qkv + (size_t)(b * 32 + chunk) * LTOT * 64;
;         if (isV) {
; #pragma unroll
;           for (int bj = 0; bj < 2; ++bj)
; #pragma unroll
;             for (int n = 0; n < 2; ++n)
; #pragma unroll
;               for (int e = 0; e < 4; ++e) {
;                 int d = 32 * bj + 8 * fq + 4 * n + e;
;                 base[(size_t)d * LTOT + pos] = f2bf(acc[ai][bj][m][n][e]);
;               }
;         } else {
;           float ss = 0.f;
; #pragma unroll
;           for (int bj = 0; bj < 2; ++bj)
; #pragma unroll
;             for (int n = 0; n < 2; ++n)
; #pragma unroll
;               for (int e = 0; e < 4; ++e) ss += acc[ai][bj][m][n][e] * acc[ai][bj][m][n][e];
;           ss += __shfl_xor(ss, 16);
;           ss += __shfl_xor(ss, 32);
;           const float rinv = rsqrtf(ss * (1.f / 64.f) + EPSV);
;           float o1[8], o2[8];
; #pragma unroll
;           for (int n = 0; n < 2; ++n) {
;             f32x4 cs0 = (f32x4){1.f, 0.f, 1.f, 0.f}, cs1 = cs0;
;             if (ropeT) { cs0 = csr[m & 1][n][0]; cs1 = csr[m & 1][n][1]; }
; #pragma unroll
;             for (int e = 0; e < 4; ++e) {
;               float x1 = acc[ai][0][m][n][e] * (rinv * qs) * g4[0][n][e];
;               float x2 = acc[ai][1][m][n][e] * (rinv * qs) * g4[1][n][e];
;               float c = (e < 2) ? cs0[2 * e] : cs1[2 * (e - 2)], s = (e < 2) ? cs0[2 * e + 1] : cs1[2 * (e - 2) + 1];
;               o1[n * 4 + e] = x1 * c - x2 * s;
;               o2[n * 4 + e] = x2 * c + x1 * s;
;             }
;           }
;           u16* dst = base + (size_t)pos * 64 + 8 * fq;
;           *(uint4*)(dst) = make_uint4(pack_bf16(o1[0], o1[1]), pack_bf16(o1[2], o1[3]), pack_bf16(o1[4], o1[5]), pack_bf16(o1[6], o1[7]));
;           *(uint4*)(dst + 32) = make_uint4(pack_bf16(o2[0], o2[1]), pack_bf16(o2[2], o2[3]), pack_bf16(o2[4], o2[5]), pack_bf16(o2[6], o2[7]));
.LBB0_845:
	v_or_b32_e32 v130, 0x1010, v152
	s_and_b64 vcc, exec, s[4:5]
	s_mov_b64 s[2:3], -1
	s_movk_i32 s28, 0x4000
	s_cbranch_vccnz .LBB0_851
	v_mul_f32_e32 v0, v127, v127
	v_fmac_f32_e32 v0, v126, v126
	v_fmac_f32_e32 v0, v128, v128
	v_fmac_f32_e32 v0, v129, v129
	v_fmac_f32_e32 v0, v122, v122
	v_fmac_f32_e32 v0, v123, v123
	v_fmac_f32_e32 v0, v124, v124
	v_fmac_f32_e32 v0, v125, v125
	v_pk_mul_f32 v[134:135], v[118:119], v[118:119]
	v_pk_mul_f32 v[132:133], v[120:121], v[120:121]
	v_add_f32_e32 v0, v134, v0
	v_add_f32_e32 v0, v135, v0
	v_add_f32_e32 v0, v132, v0
	v_add_f32_e32 v0, v133, v0
	v_pk_mul_f32 v[134:135], v[114:115], v[114:115]
	v_pk_mul_f32 v[132:133], v[116:117], v[116:117]
	v_add_f32_e32 v0, v134, v0
	v_add_f32_e32 v0, v135, v0
	v_add_f32_e32 v0, v132, v0
	v_add_f32_e32 v0, v133, v0
	v_mov_b32_e32 v147, v1
	v_mov_b32_e32 v131, v0
	s_nop 1
	v_permlane16_swap_b32_e32 v0, v131
	s_waitcnt lgkmcnt(0)
	v_add_f32_e32 v0, v0, v131
	s_nop 1
	v_mov_b32_e32 v131, v0
	s_nop 1
	v_permlane32_swap_b32_e32 v0, v131
	s_waitcnt lgkmcnt(0)
	v_add_f32_e32 v0, v0, v131
	v_fmamk_f32 v0, v0, 0x3c800000, v210
	v_mul_f32_e32 v131, 0x4b800000, v0
	v_cmp_gt_f32_e32 vcc, s11, v0
	s_nop 1
	v_cndmask_b32_e32 v0, v0, v131, vcc
	v_rsq_f32_e32 v0, v0
	s_nop 0
	v_mul_f32_e32 v131, 0x45800000, v0
	v_cndmask_b32_e32 v0, v0, v131, vcc
	v_mul_f32_e32 v0, v151, v0
	v_pk_mul_f32 v[132:133], v[118:119], v[0:1] op_sel_hi:[1,0]
	v_pk_mul_f32 v[134:135], v[126:127], v[0:1] op_sel_hi:[1,0]
	v_pk_mul_f32 v[132:133], v[94:95], v[132:133]
	v_pk_mul_f32 v[134:135], v[90:91], v[134:135]
	v_pk_mul_f32 v[138:139], v[128:129], v[0:1] op_sel_hi:[1,0]
	v_pk_fma_f32 v[136:137], v[134:135], 0, v[132:133] op_sel_hi:[1,0,1]
	v_pk_fma_f32 v[132:133], v[132:133], 0, v[134:135] op_sel_hi:[1,0,1] neg_lo:[1,0,0] neg_hi:[1,0,0]
	v_pk_mul_f32 v[134:135], v[120:121], v[0:1] op_sel_hi:[1,0]
	v_pk_mul_f32 v[138:139], v[92:93], v[138:139]
	v_pk_mul_f32 v[134:135], v[96:97], v[134:135]
	v_pk_mul_f32 v[142:143], v[122:123], v[0:1] op_sel_hi:[1,0]
	v_pk_fma_f32 v[140:141], v[138:139], 0, v[134:135] op_sel_hi:[1,0,1]
	v_pk_fma_f32 v[134:135], v[134:135], 0, v[138:139] op_sel_hi:[1,0,1] neg_lo:[1,0,0] neg_hi:[1,0,0]
	v_pk_mul_f32 v[138:139], v[114:115], v[0:1] op_sel_hi:[1,0]
	v_pk_mul_f32 v[142:143], v[82:83], v[142:143]
	v_pk_mul_f32 v[138:139], v[86:87], v[138:139]
	v_pk_mul_f32 v[154:155], v[124:125], v[0:1] op_sel_hi:[1,0]
	v_pk_fma_f32 v[144:145], v[142:143], 0, v[138:139] op_sel_hi:[1,0,1]
	v_pk_fma_f32 v[138:139], v[138:139], 0, v[142:143] op_sel_hi:[1,0,1] neg_lo:[1,0,0] neg_hi:[1,0,0]
	v_pk_mul_f32 v[142:143], v[116:117], v[0:1] op_sel_hi:[1,0]
	v_pk_mul_f32 v[154:155], v[84:85], v[154:155]
	v_pk_mul_f32 v[142:143], v[88:89], v[142:143]
	v_lshlrev_b32_e32 v0, 7, v130
	v_pk_fma_f32 v[156:157], v[154:155], 0, v[142:143] op_sel_hi:[1,0,1]
	v_pk_fma_f32 v[142:143], v[142:143], 0, v[154:155] op_sel_hi:[1,0,1] neg_lo:[1,0,0] neg_hi:[1,0,0]
	v_lshl_add_u64 v[154:155], s[0:1], 0, v[0:1]
	v_lshl_add_u64 v[154:155], v[154:155], 0, v[146:147]
	v_cvt_pk_bf16_f32 v132, v132, v133
	v_cvt_pk_bf16_f32 v133, v134, v135
	v_cvt_pk_bf16_f32 v134, v138, v139
	v_cvt_pk_bf16_f32 v135, v142, v143
	global_store_dwordx4 v[154:155], v[132:135], off sc1
	s_nop 1
	v_cvt_pk_bf16_f32 v132, v136, v137
	v_cvt_pk_bf16_f32 v133, v140, v141
	v_cvt_pk_bf16_f32 v134, v144, v145
	v_cvt_pk_bf16_f32 v135, v156, v157
	global_store_dwordx4 v[154:155], v[132:135], off offset:64 sc1
	s_cbranch_execz .LBB0_852

; DI u16 f2bf(float a) { return (u16)(pack_bf16(a, 0.f) & 0xffffu); }
;   DI void operator()(const f32x4 (&acc)[2][2][4][2], const Unit& u, int wr, int wc, int fr, int fq) const {
;     ...
;         const int t = u.pm * BM + ai * HALF + wr * 64 + m * 16 + fr;
;         int b, pos;
;         if (rowbase == 0) { b = t >> 12; pos = t & 4095; } else { b = t >> 8; pos = 4096 + (t & 255); }
;         u16* base = qkv + (size_t)(b * 32 + chunk) * LTOT * 64;
;         if (isV) {
; #pragma unroll
;           for (int bj = 0; bj < 2; ++bj)
; #pragma unroll
;             for (int n = 0; n < 2; ++n)
; #pragma unroll
;               for (int e = 0; e < 4; ++e) {
;                 int d = 32 * bj + 8 * fq + 4 * n + e;
;                 base[(size_t)d * LTOT + pos] = f2bf(acc[ai][bj][m][n][e]);
;               }
;         } else {
;           float ss = 0.f;
; #pragma unroll
;           for (int bj = 0; bj < 2; ++bj)
; #pragma unroll
;             for (int n = 0; n < 2; ++n)
; #pragma unroll
;               for (int e = 0; e < 4; ++e) ss += acc[ai][bj][m][n][e] * acc[ai][bj][m][n][e];
;           ss += __shfl_xor(ss, 16);
;           ss += __shfl_xor(ss, 32);
;           const float rinv = rsqrtf(ss * (1.f / 64.f) + EPSV);
;           float o1[8], o2[8];
; #pragma unroll
;           for (int n = 0; n < 2; ++n) {
;             f32x4 cs0 = (f32x4){1.f, 0.f, 1.f, 0.f}, cs1 = cs0;
;             if (ropeT) { cs0 = csr[m & 1][n][0]; cs1 = csr[m & 1][n][1]; }
; #pragma unroll
;             for (int e = 0; e < 4; ++e) {
;               float x1 = acc[ai][0][m][n][e] * (rinv * qs) * g4[0][n][e];
;               float x2 = acc[ai][1][m][n][e] * (rinv * qs) * g4[1][n][e];
;               float c = (e < 2) ? cs0[2 * e] : cs1[2 * (e - 2)], s = (e < 2) ? cs0[2 * e + 1] : cs1[2 * (e - 2) + 1];
;               o1[n * 4 + e] = x1 * c - x2 * s;
;               o2[n * 4 + e] = x2 * c + x1 * s;
;             }
;           }
;           u16* dst = base + (size_t)pos * 64 + 8 * fq;
;           *(uint4*)(dst) = make_uint4(pack_bf16(o1[0], o1[1]), pack_bf16(o1[2], o1[3]), pack_bf16(o1[4], o1[5]), pack_bf16(o1[6], o1[7]));
;           *(uint4*)(dst + 32) = make_uint4(pack_bf16(o2[0], o2[1]), pack_bf16(o2[2], o2[3]), pack_bf16(o2[4], o2[5]), pack_bf16(o2[6], o2[7]));
.LBB0_848:
	v_mul_f32_e32 v0, v111, v111
	v_fmac_f32_e32 v0, v110, v110
	v_fmac_f32_e32 v0, v112, v112
	v_fmac_f32_e32 v0, v113, v113
	v_fmac_f32_e32 v0, v106, v106
	v_fmac_f32_e32 v0, v107, v107
	v_fmac_f32_e32 v0, v108, v108
	v_fmac_f32_e32 v0, v109, v109
	v_pk_mul_f32 v[118:119], v[102:103], v[102:103]
	v_pk_mul_f32 v[116:117], v[104:105], v[104:105]
	v_add_f32_e32 v0, v118, v0
	v_add_f32_e32 v0, v119, v0
	v_add_f32_e32 v0, v116, v0
	v_add_f32_e32 v0, v117, v0
	v_pk_mul_f32 v[118:119], v[98:99], v[98:99]
	v_pk_mul_f32 v[116:117], v[100:101], v[100:101]
	v_add_f32_e32 v0, v118, v0
	v_add_f32_e32 v0, v119, v0
	v_add_f32_e32 v0, v116, v0
	v_add_f32_e32 v0, v117, v0
	v_mov_b32_e32 v147, v1
	v_mov_b32_e32 v115, v0
	s_nop 1
	v_permlane16_swap_b32_e32 v0, v115
	s_waitcnt lgkmcnt(0)
	v_add_f32_e32 v0, v0, v115
	s_nop 1
	v_mov_b32_e32 v115, v0
	s_nop 1
	v_permlane32_swap_b32_e32 v0, v115
	s_waitcnt lgkmcnt(0)
	v_add_f32_e32 v0, v0, v115
	v_fmamk_f32 v0, v0, 0x3c800000, v210
	v_mul_f32_e32 v115, 0x4b800000, v0
	v_cmp_gt_f32_e32 vcc, s11, v0
	s_nop 1
	v_cndmask_b32_e32 v0, v0, v115, vcc
	v_rsq_f32_e32 v0, v0
	s_nop 0
	v_mul_f32_e32 v115, 0x45800000, v0
	v_cndmask_b32_e32 v0, v0, v115, vcc
	v_mul_f32_e32 v0, v151, v0
	v_pk_mul_f32 v[116:117], v[102:103], v[0:1] op_sel_hi:[1,0]
	v_pk_mul_f32 v[118:119], v[110:111], v[0:1] op_sel_hi:[1,0]
	v_pk_mul_f32 v[116:117], v[94:95], v[116:117]
	v_pk_mul_f32 v[118:119], v[90:91], v[118:119]
	v_pk_mul_f32 v[122:123], v[112:113], v[0:1] op_sel_hi:[1,0]
	v_pk_fma_f32 v[120:121], v[118:119], 0, v[116:117] op_sel_hi:[1,0,1]
	v_pk_fma_f32 v[116:117], v[116:117], 0, v[118:119] op_sel_hi:[1,0,1] neg_lo:[1,0,0] neg_hi:[1,0,0]
	v_pk_mul_f32 v[118:119], v[104:105], v[0:1] op_sel_hi:[1,0]
	v_pk_mul_f32 v[122:123], v[92:93], v[122:123]
	v_pk_mul_f32 v[118:119], v[96:97], v[118:119]
	v_pk_mul_f32 v[126:127], v[106:107], v[0:1] op_sel_hi:[1,0]
	v_pk_fma_f32 v[124:125], v[122:123], 0, v[118:119] op_sel_hi:[1,0,1]
	v_pk_fma_f32 v[118:119], v[118:119], 0, v[122:123] op_sel_hi:[1,0,1] neg_lo:[1,0,0] neg_hi:[1,0,0]
	v_pk_mul_f32 v[122:123], v[98:99], v[0:1] op_sel_hi:[1,0]
	v_pk_mul_f32 v[126:127], v[82:83], v[126:127]
	v_pk_mul_f32 v[122:123], v[86:87], v[122:123]
	v_pk_mul_f32 v[130:131], v[108:109], v[0:1] op_sel_hi:[1,0]
	v_pk_fma_f32 v[128:129], v[126:127], 0, v[122:123] op_sel_hi:[1,0,1]
	v_pk_fma_f32 v[122:123], v[122:123], 0, v[126:127] op_sel_hi:[1,0,1] neg_lo:[1,0,0] neg_hi:[1,0,0]
	v_pk_mul_f32 v[126:127], v[100:101], v[0:1] op_sel_hi:[1,0]
	v_pk_mul_f32 v[130:131], v[84:85], v[130:131]
	v_pk_mul_f32 v[126:127], v[88:89], v[126:127]
	v_lshlrev_b32_e32 v0, 7, v114
	v_pk_fma_f32 v[132:133], v[130:131], 0, v[126:127] op_sel_hi:[1,0,1]
	v_pk_fma_f32 v[126:127], v[126:127], 0, v[130:131] op_sel_hi:[1,0,1] neg_lo:[1,0,0] neg_hi:[1,0,0]
	v_lshl_add_u64 v[130:131], s[0:1], 0, v[0:1]
	v_lshl_add_u64 v[130:131], v[130:131], 0, v[146:147]
	v_cvt_pk_bf16_f32 v116, v116, v117
	v_cvt_pk_bf16_f32 v117, v118, v119
	v_cvt_pk_bf16_f32 v118, v122, v123
	v_cvt_pk_bf16_f32 v119, v126, v127
	global_store_dwordx4 v[130:131], v[116:119], off sc1
	s_nop 1
	v_cvt_pk_bf16_f32 v116, v120, v121
	v_cvt_pk_bf16_f32 v117, v124, v125
	v_cvt_pk_bf16_f32 v118, v128, v129
	v_cvt_pk_bf16_f32 v119, v132, v133
	global_store_dwordx4 v[130:131], v[116:119], off offset:64 sc1
	s_cbranch_execz .LBB0_854

; DI u16 f2bf(float a) { return (u16)(pack_bf16(a, 0.f) & 0xffffu); }
;   DI void operator()(const f32x4 (&acc)[2][2][4][2], const Unit& u, int wr, int wc, int fr, int fq) const {
;     ...
;         const int t = u.pm * BM + ai * HALF + wr * 64 + m * 16 + fr;
;         int b, pos;
;         if (rowbase == 0) { b = t >> 12; pos = t & 4095; } else { b = t >> 8; pos = 4096 + (t & 255); }
;         u16* base = qkv + (size_t)(b * 32 + chunk) * LTOT * 64;
;         if (isV) {
; #pragma unroll
;           for (int bj = 0; bj < 2; ++bj)
; #pragma unroll
;             for (int n = 0; n < 2; ++n)
; #pragma unroll
;               for (int e = 0; e < 4; ++e) {
;                 int d = 32 * bj + 8 * fq + 4 * n + e;
;                 base[(size_t)d * LTOT + pos] = f2bf(acc[ai][bj][m][n][e]);
;               }
;         } else {
;           float ss = 0.f;
; #pragma unroll
;           for (int bj = 0; bj < 2; ++bj)
; #pragma unroll
;             for (int n = 0; n < 2; ++n)
; #pragma unroll
;               for (int e = 0; e < 4; ++e) ss += acc[ai][bj][m][n][e] * acc[ai][bj][m][n][e];
;           ss += __shfl_xor(ss, 16);
;           ss += __shfl_xor(ss, 32);
;           const float rinv = rsqrtf(ss * (1.f / 64.f) + EPSV);
;           float o1[8], o2[8];
; #pragma unroll
;           for (int n = 0; n < 2; ++n) {
;             f32x4 cs0 = (f32x4){1.f, 0.f, 1.f, 0.f}, cs1 = cs0;
;             if (ropeT) { cs0 = csr[m & 1][n][0]; cs1 = csr[m & 1][n][1]; }
; #pragma unroll
;             for (int e = 0; e < 4; ++e) {
;               float x1 = acc[ai][0][m][n][e] * (rinv * qs) * g4[0][n][e];
;               float x2 = acc[ai][1][m][n][e] * (rinv * qs) * g4[1][n][e];
;               float c = (e < 2) ? cs0[2 * e] : cs1[2 * (e - 2)], s = (e < 2) ? cs0[2 * e + 1] : cs1[2 * (e - 2) + 1];
;               o1[n * 4 + e] = x1 * c - x2 * s;
;               o2[n * 4 + e] = x2 * c + x1 * s;
;             }
;           }
;           u16* dst = base + (size_t)pos * 64 + 8 * fq;
;           *(uint4*)(dst) = make_uint4(pack_bf16(o1[0], o1[1]), pack_bf16(o1[2], o1[3]), pack_bf16(o1[4], o1[5]), pack_bf16(o1[6], o1[7]));
;           *(uint4*)(dst + 32) = make_uint4(pack_bf16(o2[0], o2[1]), pack_bf16(o2[2], o2[3]), pack_bf16(o2[4], o2[5]), pack_bf16(o2[6], o2[7]));
.LBB0_850:
	v_mul_f32_e32 v0, v79, v79
	v_fmac_f32_e32 v0, v78, v78
	v_fmac_f32_e32 v0, v80, v80
	v_fmac_f32_e32 v0, v81, v81
	v_fmac_f32_e32 v0, v74, v74
	v_fmac_f32_e32 v0, v75, v75
	v_fmac_f32_e32 v0, v76, v76
	v_fmac_f32_e32 v0, v77, v77
	v_pk_mul_f32 v[102:103], v[70:71], v[70:71]
	v_pk_mul_f32 v[100:101], v[72:73], v[72:73]
	v_add_f32_e32 v0, v102, v0
	v_add_f32_e32 v0, v103, v0
	v_add_f32_e32 v0, v100, v0
	v_add_f32_e32 v0, v101, v0
	v_pk_mul_f32 v[102:103], v[66:67], v[66:67]
	v_pk_mul_f32 v[100:101], v[68:69], v[68:69]
	v_add_f32_e32 v0, v102, v0
	v_add_f32_e32 v0, v103, v0
	v_add_f32_e32 v0, v100, v0
	v_add_f32_e32 v0, v101, v0
	v_mov_b32_e32 v147, v1
	v_mov_b32_e32 v99, v0
	s_nop 1
	v_permlane16_swap_b32_e32 v0, v99
	s_waitcnt lgkmcnt(0)
	v_add_f32_e32 v0, v0, v99
	s_nop 1
	v_mov_b32_e32 v99, v0
	s_nop 1
	v_permlane32_swap_b32_e32 v0, v99
	s_waitcnt lgkmcnt(0)
	v_add_f32_e32 v0, v0, v99
	v_fmamk_f32 v0, v0, 0x3c800000, v210
	v_mul_f32_e32 v99, 0x4b800000, v0
	v_cmp_gt_f32_e32 vcc, s11, v0
	s_nop 1
	v_cndmask_b32_e32 v0, v0, v99, vcc
	v_rsq_f32_e32 v0, v0
	s_nop 0
	v_mul_f32_e32 v99, 0x45800000, v0
	v_cndmask_b32_e32 v0, v0, v99, vcc
	v_mul_f32_e32 v0, v151, v0
	v_pk_mul_f32 v[100:101], v[70:71], v[0:1] op_sel_hi:[1,0]
	v_pk_mul_f32 v[102:103], v[78:79], v[0:1] op_sel_hi:[1,0]
	v_pk_mul_f32 v[100:101], v[94:95], v[100:101]
	v_pk_mul_f32 v[102:103], v[90:91], v[102:103]
	v_pk_mul_f32 v[106:107], v[80:81], v[0:1] op_sel_hi:[1,0]
	v_pk_fma_f32 v[104:105], v[102:103], 0, v[100:101] op_sel_hi:[1,0,1]
	v_pk_fma_f32 v[100:101], v[100:101], 0, v[102:103] op_sel_hi:[1,0,1] neg_lo:[1,0,0] neg_hi:[1,0,0]
	v_pk_mul_f32 v[102:103], v[72:73], v[0:1] op_sel_hi:[1,0]
	v_pk_mul_f32 v[106:107], v[92:93], v[106:107]
	v_pk_mul_f32 v[102:103], v[96:97], v[102:103]
	v_pk_mul_f32 v[110:111], v[74:75], v[0:1] op_sel_hi:[1,0]
	v_pk_fma_f32 v[108:109], v[106:107], 0, v[102:103] op_sel_hi:[1,0,1]
	v_pk_fma_f32 v[102:103], v[102:103], 0, v[106:107] op_sel_hi:[1,0,1] neg_lo:[1,0,0] neg_hi:[1,0,0]
	v_pk_mul_f32 v[106:107], v[66:67], v[0:1] op_sel_hi:[1,0]
	v_pk_mul_f32 v[110:111], v[82:83], v[110:111]
	v_pk_mul_f32 v[106:107], v[86:87], v[106:107]
	v_pk_mul_f32 v[114:115], v[76:77], v[0:1] op_sel_hi:[1,0]
	v_pk_fma_f32 v[112:113], v[110:111], 0, v[106:107] op_sel_hi:[1,0,1]
	v_pk_fma_f32 v[106:107], v[106:107], 0, v[110:111] op_sel_hi:[1,0,1] neg_lo:[1,0,0] neg_hi:[1,0,0]
	v_pk_mul_f32 v[110:111], v[68:69], v[0:1] op_sel_hi:[1,0]
	v_pk_mul_f32 v[114:115], v[84:85], v[114:115]
	v_pk_mul_f32 v[110:111], v[88:89], v[110:111]
	v_lshlrev_b32_e32 v0, 7, v98
	v_pk_fma_f32 v[116:117], v[114:115], 0, v[110:111] op_sel_hi:[1,0,1]
	v_pk_fma_f32 v[110:111], v[110:111], 0, v[114:115] op_sel_hi:[1,0,1] neg_lo:[1,0,0] neg_hi:[1,0,0]
	v_lshl_add_u64 v[114:115], s[0:1], 0, v[0:1]
	v_lshl_add_u64 v[114:115], v[114:115], 0, v[146:147]
	v_cvt_pk_bf16_f32 v100, v100, v101
	v_cvt_pk_bf16_f32 v101, v102, v103
	v_cvt_pk_bf16_f32 v102, v106, v107
	v_cvt_pk_bf16_f32 v103, v110, v111
	global_store_dwordx4 v[114:115], v[100:103], off sc1
	s_nop 1
	v_cvt_pk_bf16_f32 v100, v104, v105
	v_cvt_pk_bf16_f32 v101, v108, v109
	v_cvt_pk_bf16_f32 v102, v112, v113
	v_cvt_pk_bf16_f32 v103, v116, v117
	global_store_dwordx4 v[114:115], v[100:103], off offset:64 sc1
	s_cbranch_execz .LBB0_856
	s_branch .LBB0_857

; DI u16 f2bf(float a) { return (u16)(pack_bf16(a, 0.f) & 0xffffu); }
;   DI void operator()(const f32x4 (&acc)[2][2][4][2], const Unit& u, int wr, int wc, int fr, int fq) const {
;     ...
;         const int t = u.pm * BM + ai * HALF + wr * 64 + m * 16 + fr;
;         int b, pos;
;         if (rowbase == 0) { b = t >> 12; pos = t & 4095; } else { b = t >> 8; pos = 4096 + (t & 255); }
;         u16* base = qkv + (size_t)(b * 32 + chunk) * LTOT * 64;
;         if (isV) {
; #pragma unroll
;           for (int bj = 0; bj < 2; ++bj)
; #pragma unroll
;             for (int n = 0; n < 2; ++n)
; #pragma unroll
;               for (int e = 0; e < 4; ++e) {
;                 int d = 32 * bj + 8 * fq + 4 * n + e;
;                 base[(size_t)d * LTOT + pos] = f2bf(acc[ai][bj][m][n][e]);
;               }
;         } else {
;           float ss = 0.f;
; #pragma unroll
;           for (int bj = 0; bj < 2; ++bj)
; #pragma unroll
;             for (int n = 0; n < 2; ++n)
; #pragma unroll
;               for (int e = 0; e < 4; ++e) ss += acc[ai][bj][m][n][e] * acc[ai][bj][m][n][e];
;           ss += __shfl_xor(ss, 16);
;           ss += __shfl_xor(ss, 32);
;           const float rinv = rsqrtf(ss * (1.f / 64.f) + EPSV);
;           float o1[8], o2[8];
; #pragma unroll
;           for (int n = 0; n < 2; ++n) {
;             f32x4 cs0 = (f32x4){1.f, 0.f, 1.f, 0.f}, cs1 = cs0;
;             if (ropeT) { cs0 = csr[m & 1][n][0]; cs1 = csr[m & 1][n][1]; }
; #pragma unroll
;             for (int e = 0; e < 4; ++e) {
;               float x1 = acc[ai][0][m][n][e] * (rinv * qs) * g4[0][n][e];
;               float x2 = acc[ai][1][m][n][e] * (rinv * qs) * g4[1][n][e];
;               float c = (e < 2) ? cs0[2 * e] : cs1[2 * (e - 2)], s = (e < 2) ? cs0[2 * e + 1] : cs1[2 * (e - 2) + 1];
;               o1[n * 4 + e] = x1 * c - x2 * s;
;               o2[n * 4 + e] = x2 * c + x1 * s;
;             }
;           }
;           u16* dst = base + (size_t)pos * 64 + 8 * fq;
;           *(uint4*)(dst) = make_uint4(pack_bf16(o1[0], o1[1]), pack_bf16(o1[2], o1[3]), pack_bf16(o1[4], o1[5]), pack_bf16(o1[6], o1[7]));
;           *(uint4*)(dst + 32) = make_uint4(pack_bf16(o2[0], o2[1]), pack_bf16(o2[2], o2[3]), pack_bf16(o2[4], o2[5]), pack_bf16(o2[6], o2[7]));
.LBB0_857:
	s_add_i32 s0, s15, 0x80
	s_add_i32 s1, s0, s10
	s_and_b32 s0, s0, 0xc0
	v_or_b32_e32 v0, s0, v150
	s_ashr_i32 s0, s1, 3
	s_andn2_b32 s0, s0, 31
	s_add_i32 s0, s0, s8
	s_mul_hi_i32 s1, s0, 0x88000
	s_mul_i32 s0, s0, 0x88000
	s_add_u32 s0, s88, s0
	v_or_b32_e32 v66, 0x1000, v0
	s_addc_u32 s1, s89, s1
	s_and_b64 vcc, exec, s[4:5]
	s_mov_b64 s[2:3], -1
	s_cbranch_vccnz .LBB0_859
	v_mul_f32_e32 v0, v63, v63
	v_fmac_f32_e32 v0, v62, v62
	v_fmac_f32_e32 v0, v64, v64
	v_fmac_f32_e32 v0, v65, v65
	v_fmac_f32_e32 v0, v58, v58
	v_fmac_f32_e32 v0, v59, v59
	v_fmac_f32_e32 v0, v60, v60
	v_fmac_f32_e32 v0, v61, v61
	v_pk_mul_f32 v[70:71], v[54:55], v[54:55]
	v_pk_mul_f32 v[68:69], v[56:57], v[56:57]
	v_add_f32_e32 v0, v70, v0
	v_add_f32_e32 v0, v71, v0
	v_add_f32_e32 v0, v68, v0
	v_add_f32_e32 v0, v69, v0
	v_pk_mul_f32 v[70:71], v[50:51], v[50:51]
	v_pk_mul_f32 v[68:69], v[52:53], v[52:53]
	v_add_f32_e32 v0, v70, v0
	v_add_f32_e32 v0, v71, v0
	v_add_f32_e32 v0, v68, v0
	v_add_f32_e32 v0, v69, v0
	v_mov_b32_e32 v147, v1
	v_mov_b32_e32 v67, v0
	s_nop 1
	v_permlane16_swap_b32_e32 v0, v67
	s_mov_b64 s[2:3], 0
	s_waitcnt lgkmcnt(0)
	v_add_f32_e32 v0, v0, v67
	s_nop 1
	v_mov_b32_e32 v67, v0
	s_nop 1
	v_permlane32_swap_b32_e32 v0, v67
	s_waitcnt lgkmcnt(0)
	v_add_f32_e32 v0, v0, v67
	v_fmamk_f32 v0, v0, 0x3c800000, v210
	v_mul_f32_e32 v67, 0x4b800000, v0
	v_cmp_gt_f32_e32 vcc, s11, v0
	s_nop 1
	v_cndmask_b32_e32 v0, v0, v67, vcc
	v_rsq_f32_e32 v0, v0
	s_nop 0
	v_mul_f32_e32 v67, 0x45800000, v0
	v_cndmask_b32_e32 v0, v0, v67, vcc
	v_mul_f32_e32 v0, v151, v0
	v_pk_mul_f32 v[68:69], v[54:55], v[0:1] op_sel_hi:[1,0]
	v_pk_mul_f32 v[70:71], v[62:63], v[0:1] op_sel_hi:[1,0]
	v_pk_mul_f32 v[68:69], v[94:95], v[68:69]
	v_pk_mul_f32 v[70:71], v[90:91], v[70:71]
	v_pk_mul_f32 v[74:75], v[64:65], v[0:1] op_sel_hi:[1,0]
	v_pk_fma_f32 v[72:73], v[70:71], 0, v[68:69] op_sel_hi:[1,0,1]
	v_pk_fma_f32 v[68:69], v[68:69], 0, v[70:71] op_sel_hi:[1,0,1] neg_lo:[1,0,0] neg_hi:[1,0,0]
	v_pk_mul_f32 v[70:71], v[56:57], v[0:1] op_sel_hi:[1,0]
	v_pk_mul_f32 v[74:75], v[92:93], v[74:75]
	v_pk_mul_f32 v[70:71], v[96:97], v[70:71]
	v_pk_mul_f32 v[78:79], v[58:59], v[0:1] op_sel_hi:[1,0]
	v_pk_fma_f32 v[76:77], v[74:75], 0, v[70:71] op_sel_hi:[1,0,1]
	v_pk_fma_f32 v[70:71], v[70:71], 0, v[74:75] op_sel_hi:[1,0,1] neg_lo:[1,0,0] neg_hi:[1,0,0]
	v_pk_mul_f32 v[74:75], v[50:51], v[0:1] op_sel_hi:[1,0]
	v_pk_mul_f32 v[78:79], v[82:83], v[78:79]
	v_pk_mul_f32 v[74:75], v[86:87], v[74:75]
	v_pk_mul_f32 v[98:99], v[60:61], v[0:1] op_sel_hi:[1,0]
	v_pk_fma_f32 v[80:81], v[78:79], 0, v[74:75] op_sel_hi:[1,0,1]
	v_pk_fma_f32 v[74:75], v[74:75], 0, v[78:79] op_sel_hi:[1,0,1] neg_lo:[1,0,0] neg_hi:[1,0,0]
	v_pk_mul_f32 v[78:79], v[52:53], v[0:1] op_sel_hi:[1,0]
	v_pk_mul_f32 v[98:99], v[84:85], v[98:99]
	v_pk_mul_f32 v[78:79], v[88:89], v[78:79]
	v_lshlrev_b32_e32 v0, 7, v66
	v_pk_fma_f32 v[100:101], v[98:99], 0, v[78:79] op_sel_hi:[1,0,1]
	v_pk_fma_f32 v[78:79], v[78:79], 0, v[98:99] op_sel_hi:[1,0,1] neg_lo:[1,0,0] neg_hi:[1,0,0]
	v_lshl_add_u64 v[98:99], s[0:1], 0, v[0:1]
	v_lshl_add_u64 v[98:99], v[98:99], 0, v[146:147]
	v_cvt_pk_bf16_f32 v68, v68, v69
	v_cvt_pk_bf16_f32 v69, v70, v71
	v_cvt_pk_bf16_f32 v70, v74, v75
	v_cvt_pk_bf16_f32 v71, v78, v79
	global_store_dwordx4 v[98:99], v[68:71], off sc1
	s_nop 1
	v_cvt_pk_bf16_f32 v68, v72, v73
	v_cvt_pk_bf16_f32 v69, v76, v77
	v_cvt_pk_bf16_f32 v70, v80, v81
	v_cvt_pk_bf16_f32 v71, v100, v101
	global_store_dwordx4 v[98:99], v[68:71], off offset:64 sc1

; DI u16 f2bf(float a) { return (u16)(pack_bf16(a, 0.f) & 0xffffu); }
;   DI void operator()(const f32x4 (&acc)[2][2][4][2], const Unit& u, int wr, int wc, int fr, int fq) const {
;     ...
;         const int t = u.pm * BM + ai * HALF + wr * 64 + m * 16 + fr;
;         int b, pos;
;         if (rowbase == 0) { b = t >> 12; pos = t & 4095; } else { b = t >> 8; pos = 4096 + (t & 255); }
;         u16* base = qkv + (size_t)(b * 32 + chunk) * LTOT * 64;
;         if (isV) {
; #pragma unroll
;           for (int bj = 0; bj < 2; ++bj)
; #pragma unroll
;             for (int n = 0; n < 2; ++n)
; #pragma unroll
;               for (int e = 0; e < 4; ++e) {
;                 int d = 32 * bj + 8 * fq + 4 * n + e;
;                 base[(size_t)d * LTOT + pos] = f2bf(acc[ai][bj][m][n][e]);
;               }
;         } else {
;           float ss = 0.f;
; #pragma unroll
;           for (int bj = 0; bj < 2; ++bj)
; #pragma unroll
;             for (int n = 0; n < 2; ++n)
; #pragma unroll
;               for (int e = 0; e < 4; ++e) ss += acc[ai][bj][m][n][e] * acc[ai][bj][m][n][e];
;           ss += __shfl_xor(ss, 16);
;           ss += __shfl_xor(ss, 32);
;           const float rinv = rsqrtf(ss * (1.f / 64.f) + EPSV);
;           float o1[8], o2[8];
; #pragma unroll
;           for (int n = 0; n < 2; ++n) {
;             f32x4 cs0 = (f32x4){1.f, 0.f, 1.f, 0.f}, cs1 = cs0;
;             if (ropeT) { cs0 = csr[m & 1][n][0]; cs1 = csr[m & 1][n][1]; }
; #pragma unroll
;             for (int e = 0; e < 4; ++e) {
;               float x1 = acc[ai][0][m][n][e] * (rinv * qs) * g4[0][n][e];
;               float x2 = acc[ai][1][m][n][e] * (rinv * qs) * g4[1][n][e];
;               float c = (e < 2) ? cs0[2 * e] : cs1[2 * (e - 2)], s = (e < 2) ? cs0[2 * e + 1] : cs1[2 * (e - 2) + 1];
;               o1[n * 4 + e] = x1 * c - x2 * s;
;               o2[n * 4 + e] = x2 * c + x1 * s;
;             }
;           }
;           u16* dst = base + (size_t)pos * 64 + 8 * fq;
;           *(uint4*)(dst) = make_uint4(pack_bf16(o1[0], o1[1]), pack_bf16(o1[2], o1[3]), pack_bf16(o1[4], o1[5]), pack_bf16(o1[6], o1[7]));
;           *(uint4*)(dst + 32) = make_uint4(pack_bf16(o2[0], o2[1]), pack_bf16(o2[2], o2[3]), pack_bf16(o2[4], o2[5]), pack_bf16(o2[6], o2[7]));
.LBB0_861:
	s_add_i32 s0, s15, 0x90
	s_add_i32 s1, s0, s10
	s_and_b32 s0, s0, 0xd0
	v_or_b32_e32 v0, s0, v150
	s_ashr_i32 s0, s1, 3
	s_andn2_b32 s0, s0, 31
	s_add_i32 s0, s0, s8
	s_mul_hi_i32 s1, s0, 0x88000
	s_mul_i32 s0, s0, 0x88000
	s_add_u32 s0, s88, s0
	v_or_b32_e32 v50, 0x1000, v0
	s_addc_u32 s1, s89, s1
	s_and_b64 vcc, exec, s[4:5]
	s_mov_b64 s[2:3], -1
	s_cbranch_vccnz .LBB0_863
	v_mul_f32_e32 v0, v47, v47
	v_fmac_f32_e32 v0, v46, v46
	v_fmac_f32_e32 v0, v48, v48
	v_fmac_f32_e32 v0, v49, v49
	v_fmac_f32_e32 v0, v42, v42
	v_fmac_f32_e32 v0, v43, v43
	v_fmac_f32_e32 v0, v44, v44
	v_fmac_f32_e32 v0, v45, v45
	v_pk_mul_f32 v[54:55], v[38:39], v[38:39]
	v_pk_mul_f32 v[52:53], v[40:41], v[40:41]
	v_add_f32_e32 v0, v54, v0
	v_add_f32_e32 v0, v55, v0
	v_add_f32_e32 v0, v52, v0
	v_add_f32_e32 v0, v53, v0
	v_pk_mul_f32 v[54:55], v[34:35], v[34:35]
	v_pk_mul_f32 v[52:53], v[36:37], v[36:37]
	v_add_f32_e32 v0, v54, v0
	v_add_f32_e32 v0, v55, v0
	v_add_f32_e32 v0, v52, v0
	v_add_f32_e32 v0, v53, v0
	v_mov_b32_e32 v147, v1
	v_mov_b32_e32 v51, v0
	s_nop 1
	v_permlane16_swap_b32_e32 v0, v51
	s_mov_b64 s[2:3], 0
	s_waitcnt lgkmcnt(0)
	v_add_f32_e32 v0, v0, v51
	s_nop 1
	v_mov_b32_e32 v51, v0
	s_nop 1
	v_permlane32_swap_b32_e32 v0, v51
	s_waitcnt lgkmcnt(0)
	v_add_f32_e32 v0, v0, v51
	v_fmamk_f32 v0, v0, 0x3c800000, v210
	v_mul_f32_e32 v51, 0x4b800000, v0
	v_cmp_gt_f32_e32 vcc, s11, v0
	s_nop 1
	v_cndmask_b32_e32 v0, v0, v51, vcc
	v_rsq_f32_e32 v0, v0
	s_nop 0
	v_mul_f32_e32 v51, 0x45800000, v0
	v_cndmask_b32_e32 v0, v0, v51, vcc
	v_mul_f32_e32 v0, v151, v0
	v_pk_mul_f32 v[52:53], v[38:39], v[0:1] op_sel_hi:[1,0]
	v_pk_mul_f32 v[54:55], v[46:47], v[0:1] op_sel_hi:[1,0]
	v_pk_mul_f32 v[52:53], v[94:95], v[52:53]
	v_pk_mul_f32 v[54:55], v[90:91], v[54:55]
	v_pk_mul_f32 v[58:59], v[48:49], v[0:1] op_sel_hi:[1,0]
	v_pk_fma_f32 v[56:57], v[54:55], 0, v[52:53] op_sel_hi:[1,0,1]
	v_pk_fma_f32 v[52:53], v[52:53], 0, v[54:55] op_sel_hi:[1,0,1] neg_lo:[1,0,0] neg_hi:[1,0,0]
	v_pk_mul_f32 v[54:55], v[40:41], v[0:1] op_sel_hi:[1,0]
	v_pk_mul_f32 v[58:59], v[92:93], v[58:59]
	v_pk_mul_f32 v[54:55], v[96:97], v[54:55]
	v_pk_mul_f32 v[62:63], v[42:43], v[0:1] op_sel_hi:[1,0]
	v_pk_fma_f32 v[60:61], v[58:59], 0, v[54:55] op_sel_hi:[1,0,1]
	v_pk_fma_f32 v[54:55], v[54:55], 0, v[58:59] op_sel_hi:[1,0,1] neg_lo:[1,0,0] neg_hi:[1,0,0]
	v_pk_mul_f32 v[58:59], v[34:35], v[0:1] op_sel_hi:[1,0]
	v_pk_mul_f32 v[62:63], v[82:83], v[62:63]
	v_pk_mul_f32 v[58:59], v[86:87], v[58:59]
	v_pk_mul_f32 v[66:67], v[44:45], v[0:1] op_sel_hi:[1,0]
	v_pk_fma_f32 v[64:65], v[62:63], 0, v[58:59] op_sel_hi:[1,0,1]
	v_pk_fma_f32 v[58:59], v[58:59], 0, v[62:63] op_sel_hi:[1,0,1] neg_lo:[1,0,0] neg_hi:[1,0,0]
	v_pk_mul_f32 v[62:63], v[36:37], v[0:1] op_sel_hi:[1,0]
	v_pk_mul_f32 v[66:67], v[84:85], v[66:67]
	v_pk_mul_f32 v[62:63], v[88:89], v[62:63]
	v_lshlrev_b32_e32 v0, 7, v50
	v_pk_fma_f32 v[68:69], v[66:67], 0, v[62:63] op_sel_hi:[1,0,1]
	v_pk_fma_f32 v[62:63], v[62:63], 0, v[66:67] op_sel_hi:[1,0,1] neg_lo:[1,0,0] neg_hi:[1,0,0]
	v_lshl_add_u64 v[66:67], s[0:1], 0, v[0:1]
	v_lshl_add_u64 v[66:67], v[66:67], 0, v[146:147]
	v_cvt_pk_bf16_f32 v52, v52, v53
	v_cvt_pk_bf16_f32 v53, v54, v55
	v_cvt_pk_bf16_f32 v54, v58, v59
	v_cvt_pk_bf16_f32 v55, v62, v63
	global_store_dwordx4 v[66:67], v[52:55], off sc1
	s_nop 1
	v_cvt_pk_bf16_f32 v52, v56, v57
	v_cvt_pk_bf16_f32 v53, v60, v61
	v_cvt_pk_bf16_f32 v54, v64, v65
	v_cvt_pk_bf16_f32 v55, v68, v69
	global_store_dwordx4 v[66:67], v[52:55], off offset:64 sc1

; DI u16 f2bf(float a) { return (u16)(pack_bf16(a, 0.f) & 0xffffu); }
;   DI void operator()(const f32x4 (&acc)[2][2][4][2], const Unit& u, int wr, int wc, int fr, int fq) const {
;     ...
;         const int t = u.pm * BM + ai * HALF + wr * 64 + m * 16 + fr;
;         int b, pos;
;         if (rowbase == 0) { b = t >> 12; pos = t & 4095; } else { b = t >> 8; pos = 4096 + (t & 255); }
;         u16* base = qkv + (size_t)(b * 32 + chunk) * LTOT * 64;
;         if (isV) {
; #pragma unroll
;           for (int bj = 0; bj < 2; ++bj)
; #pragma unroll
;             for (int n = 0; n < 2; ++n)
; #pragma unroll
;               for (int e = 0; e < 4; ++e) {
;                 int d = 32 * bj + 8 * fq + 4 * n + e;
;                 base[(size_t)d * LTOT + pos] = f2bf(acc[ai][bj][m][n][e]);
;               }
;         } else {
;           float ss = 0.f;
; #pragma unroll
;           for (int bj = 0; bj < 2; ++bj)
; #pragma unroll
;             for (int n = 0; n < 2; ++n)
; #pragma unroll
;               for (int e = 0; e < 4; ++e) ss += acc[ai][bj][m][n][e] * acc[ai][bj][m][n][e];
;           ss += __shfl_xor(ss, 16);
;           ss += __shfl_xor(ss, 32);
;           const float rinv = rsqrtf(ss * (1.f / 64.f) + EPSV);
;           float o1[8], o2[8];
; #pragma unroll
;           for (int n = 0; n < 2; ++n) {
;             f32x4 cs0 = (f32x4){1.f, 0.f, 1.f, 0.f}, cs1 = cs0;
;             if (ropeT) { cs0 = csr[m & 1][n][0]; cs1 = csr[m & 1][n][1]; }
; #pragma unroll
;             for (int e = 0; e < 4; ++e) {
;               float x1 = acc[ai][0][m][n][e] * (rinv * qs) * g4[0][n][e];
;               float x2 = acc[ai][1][m][n][e] * (rinv * qs) * g4[1][n][e];
;               float c = (e < 2) ? cs0[2 * e] : cs1[2 * (e - 2)], s = (e < 2) ? cs0[2 * e + 1] : cs1[2 * (e - 2) + 1];
;               o1[n * 4 + e] = x1 * c - x2 * s;
;               o2[n * 4 + e] = x2 * c + x1 * s;
;             }
;           }
;           u16* dst = base + (size_t)pos * 64 + 8 * fq;
;           *(uint4*)(dst) = make_uint4(pack_bf16(o1[0], o1[1]), pack_bf16(o1[2], o1[3]), pack_bf16(o1[4], o1[5]), pack_bf16(o1[6], o1[7]));
;           *(uint4*)(dst + 32) = make_uint4(pack_bf16(o2[0], o2[1]), pack_bf16(o2[2], o2[3]), pack_bf16(o2[4], o2[5]), pack_bf16(o2[6], o2[7]));
.LBB0_865:
	s_add_i32 s0, s15, 0xa0
	s_add_i32 s1, s0, s10
	s_and_b32 s0, s0, 0xe0
	v_or_b32_e32 v0, s0, v150
	s_ashr_i32 s0, s1, 3
	s_andn2_b32 s0, s0, 31
	s_add_i32 s0, s0, s8
	s_mul_hi_i32 s1, s0, 0x88000
	s_mul_i32 s0, s0, 0x88000
	s_add_u32 s0, s88, s0
	v_or_b32_e32 v34, 0x1000, v0
	s_addc_u32 s1, s89, s1
	s_and_b64 vcc, exec, s[4:5]
	s_mov_b64 s[2:3], -1
	s_cbranch_vccnz .LBB0_867
	v_mul_f32_e32 v0, v31, v31
	v_fmac_f32_e32 v0, v30, v30
	v_fmac_f32_e32 v0, v32, v32
	v_fmac_f32_e32 v0, v33, v33
	v_fmac_f32_e32 v0, v26, v26
	v_fmac_f32_e32 v0, v27, v27
	v_fmac_f32_e32 v0, v28, v28
	v_fmac_f32_e32 v0, v29, v29
	v_pk_mul_f32 v[38:39], v[22:23], v[22:23]
	v_pk_mul_f32 v[36:37], v[24:25], v[24:25]
	v_add_f32_e32 v0, v38, v0
	v_add_f32_e32 v0, v39, v0
	v_add_f32_e32 v0, v36, v0
	v_add_f32_e32 v0, v37, v0
	v_pk_mul_f32 v[38:39], v[18:19], v[18:19]
	v_pk_mul_f32 v[36:37], v[20:21], v[20:21]
	v_add_f32_e32 v0, v38, v0
	v_add_f32_e32 v0, v39, v0
	v_add_f32_e32 v0, v36, v0
	v_add_f32_e32 v0, v37, v0
	v_mov_b32_e32 v147, v1
	v_mov_b32_e32 v35, v0
	s_nop 1
	v_permlane16_swap_b32_e32 v0, v35
	s_mov_b64 s[2:3], 0
	s_waitcnt lgkmcnt(0)
	v_add_f32_e32 v0, v0, v35
	s_nop 1
	v_mov_b32_e32 v35, v0
	s_nop 1
	v_permlane32_swap_b32_e32 v0, v35
	s_waitcnt lgkmcnt(0)
	v_add_f32_e32 v0, v0, v35
	v_fmamk_f32 v0, v0, 0x3c800000, v210
	v_mul_f32_e32 v35, 0x4b800000, v0
	v_cmp_gt_f32_e32 vcc, s11, v0
	s_nop 1
	v_cndmask_b32_e32 v0, v0, v35, vcc
	v_rsq_f32_e32 v0, v0
	s_nop 0
	v_mul_f32_e32 v35, 0x45800000, v0
	v_cndmask_b32_e32 v0, v0, v35, vcc
	v_mul_f32_e32 v0, v151, v0
	v_pk_mul_f32 v[36:37], v[22:23], v[0:1] op_sel_hi:[1,0]
	v_pk_mul_f32 v[38:39], v[30:31], v[0:1] op_sel_hi:[1,0]
	v_pk_mul_f32 v[36:37], v[94:95], v[36:37]
	v_pk_mul_f32 v[38:39], v[90:91], v[38:39]
	v_pk_mul_f32 v[42:43], v[32:33], v[0:1] op_sel_hi:[1,0]
	v_pk_fma_f32 v[40:41], v[38:39], 0, v[36:37] op_sel_hi:[1,0,1]
	v_pk_fma_f32 v[36:37], v[36:37], 0, v[38:39] op_sel_hi:[1,0,1] neg_lo:[1,0,0] neg_hi:[1,0,0]
	v_pk_mul_f32 v[38:39], v[24:25], v[0:1] op_sel_hi:[1,0]
	v_pk_mul_f32 v[42:43], v[92:93], v[42:43]
	v_pk_mul_f32 v[38:39], v[96:97], v[38:39]
	v_pk_mul_f32 v[46:47], v[26:27], v[0:1] op_sel_hi:[1,0]
	v_pk_fma_f32 v[44:45], v[42:43], 0, v[38:39] op_sel_hi:[1,0,1]
	v_pk_fma_f32 v[38:39], v[38:39], 0, v[42:43] op_sel_hi:[1,0,1] neg_lo:[1,0,0] neg_hi:[1,0,0]
	v_pk_mul_f32 v[42:43], v[18:19], v[0:1] op_sel_hi:[1,0]
	v_pk_mul_f32 v[46:47], v[82:83], v[46:47]
	v_pk_mul_f32 v[42:43], v[86:87], v[42:43]
	v_pk_mul_f32 v[50:51], v[28:29], v[0:1] op_sel_hi:[1,0]
	v_pk_fma_f32 v[48:49], v[46:47], 0, v[42:43] op_sel_hi:[1,0,1]
	v_pk_fma_f32 v[42:43], v[42:43], 0, v[46:47] op_sel_hi:[1,0,1] neg_lo:[1,0,0] neg_hi:[1,0,0]
	v_pk_mul_f32 v[46:47], v[20:21], v[0:1] op_sel_hi:[1,0]
	v_pk_mul_f32 v[50:51], v[84:85], v[50:51]
	v_pk_mul_f32 v[46:47], v[88:89], v[46:47]
	v_lshlrev_b32_e32 v0, 7, v34
	v_pk_fma_f32 v[52:53], v[50:51], 0, v[46:47] op_sel_hi:[1,0,1]
	v_pk_fma_f32 v[46:47], v[46:47], 0, v[50:51] op_sel_hi:[1,0,1] neg_lo:[1,0,0] neg_hi:[1,0,0]
	v_lshl_add_u64 v[50:51], s[0:1], 0, v[0:1]
	v_lshl_add_u64 v[50:51], v[50:51], 0, v[146:147]
	v_cvt_pk_bf16_f32 v36, v36, v37
	v_cvt_pk_bf16_f32 v37, v38, v39
	v_cvt_pk_bf16_f32 v38, v42, v43
	v_cvt_pk_bf16_f32 v39, v46, v47
	global_store_dwordx4 v[50:51], v[36:39], off sc1
	s_nop 1
	v_cvt_pk_bf16_f32 v36, v40, v41
	v_cvt_pk_bf16_f32 v37, v44, v45
	v_cvt_pk_bf16_f32 v38, v48, v49
	v_cvt_pk_bf16_f32 v39, v52, v53
	global_store_dwordx4 v[50:51], v[36:39], off offset:64 sc1

; DI u16 f2bf(float a) { return (u16)(pack_bf16(a, 0.f) & 0xffffu); }
;   DI void operator()(const f32x4 (&acc)[2][2][4][2], const Unit& u, int wr, int wc, int fr, int fq) const {
;     ...
;         const int t = u.pm * BM + ai * HALF + wr * 64 + m * 16 + fr;
;         int b, pos;
;         if (rowbase == 0) { b = t >> 12; pos = t & 4095; } else { b = t >> 8; pos = 4096 + (t & 255); }
;         u16* base = qkv + (size_t)(b * 32 + chunk) * LTOT * 64;
;         if (isV) {
; #pragma unroll
;           for (int bj = 0; bj < 2; ++bj)
; #pragma unroll
;             for (int n = 0; n < 2; ++n)
; #pragma unroll
;               for (int e = 0; e < 4; ++e) {
;                 int d = 32 * bj + 8 * fq + 4 * n + e;
;                 base[(size_t)d * LTOT + pos] = f2bf(acc[ai][bj][m][n][e]);
;               }
;         } else {
;           float ss = 0.f;
; #pragma unroll
;           for (int bj = 0; bj < 2; ++bj)
; #pragma unroll
;             for (int n = 0; n < 2; ++n)
; #pragma unroll
;               for (int e = 0; e < 4; ++e) ss += acc[ai][bj][m][n][e] * acc[ai][bj][m][n][e];
;           ss += __shfl_xor(ss, 16);
;           ss += __shfl_xor(ss, 32);
;           const float rinv = rsqrtf(ss * (1.f / 64.f) + EPSV);
;           float o1[8], o2[8];
; #pragma unroll
;           for (int n = 0; n < 2; ++n) {
;             f32x4 cs0 = (f32x4){1.f, 0.f, 1.f, 0.f}, cs1 = cs0;
;             if (ropeT) { cs0 = csr[m & 1][n][0]; cs1 = csr[m & 1][n][1]; }
; #pragma unroll
;             for (int e = 0; e < 4; ++e) {
;               float x1 = acc[ai][0][m][n][e] * (rinv * qs) * g4[0][n][e];
;               float x2 = acc[ai][1][m][n][e] * (rinv * qs) * g4[1][n][e];
;               float c = (e < 2) ? cs0[2 * e] : cs1[2 * (e - 2)], s = (e < 2) ? cs0[2 * e + 1] : cs1[2 * (e - 2) + 1];
;               o1[n * 4 + e] = x1 * c - x2 * s;
;               o2[n * 4 + e] = x2 * c + x1 * s;
;             }
;           }
;           u16* dst = base + (size_t)pos * 64 + 8 * fq;
;           *(uint4*)(dst) = make_uint4(pack_bf16(o1[0], o1[1]), pack_bf16(o1[2], o1[3]), pack_bf16(o1[4], o1[5]), pack_bf16(o1[6], o1[7]));
;           *(uint4*)(dst + 32) = make_uint4(pack_bf16(o2[0], o2[1]), pack_bf16(o2[2], o2[3]), pack_bf16(o2[4], o2[5]), pack_bf16(o2[6], o2[7]));
.LBB0_869:
	s_add_i32 s0, s15, 0xb0
	s_add_i32 s1, s0, s10
	s_and_b32 s0, s0, 0xf0
	v_or_b32_e32 v0, s0, v150
	s_ashr_i32 s0, s1, 3
	s_andn2_b32 s0, s0, 31
	s_add_i32 s0, s0, s8
	s_mul_hi_i32 s1, s0, 0x88000
	s_mul_i32 s0, s0, 0x88000
	s_add_u32 s0, s88, s0
	v_or_b32_e32 v18, 0x1000, v0
	s_addc_u32 s1, s89, s1
	s_and_b64 vcc, exec, s[4:5]
	s_mov_b64 s[2:3], -1
	s_cbranch_vccnz .LBB0_871
	v_mul_f32_e32 v0, v15, v15
	v_fmac_f32_e32 v0, v14, v14
	v_fmac_f32_e32 v0, v16, v16
	v_fmac_f32_e32 v0, v17, v17
	v_fmac_f32_e32 v0, v10, v10
	v_fmac_f32_e32 v0, v11, v11
	v_fmac_f32_e32 v0, v12, v12
	v_fmac_f32_e32 v0, v13, v13
	v_pk_mul_f32 v[22:23], v[6:7], v[6:7]
	v_pk_mul_f32 v[20:21], v[8:9], v[8:9]
	v_add_f32_e32 v0, v22, v0
	v_add_f32_e32 v0, v23, v0
	v_add_f32_e32 v0, v20, v0
	v_add_f32_e32 v0, v21, v0
	v_pk_mul_f32 v[22:23], v[2:3], v[2:3]
	v_pk_mul_f32 v[20:21], v[4:5], v[4:5]
	v_add_f32_e32 v0, v22, v0
	v_add_f32_e32 v0, v23, v0
	v_add_f32_e32 v0, v20, v0
	v_add_f32_e32 v0, v21, v0
	v_mov_b32_e32 v147, v1
	v_mov_b32_e32 v19, v0
	s_nop 1
	v_permlane16_swap_b32_e32 v0, v19
	s_mov_b64 s[2:3], 0
	s_waitcnt lgkmcnt(0)
	v_add_f32_e32 v0, v0, v19
	s_nop 1
	v_mov_b32_e32 v19, v0
	s_nop 1
	v_permlane32_swap_b32_e32 v0, v19
	s_waitcnt lgkmcnt(0)
	v_add_f32_e32 v0, v0, v19
	v_fmamk_f32 v0, v0, 0x3c800000, v210
	v_mul_f32_e32 v19, 0x4b800000, v0
	v_cmp_gt_f32_e32 vcc, s11, v0
	s_nop 1
	v_cndmask_b32_e32 v0, v0, v19, vcc
	v_rsq_f32_e32 v0, v0
	s_nop 0
	v_mul_f32_e32 v19, 0x45800000, v0
	v_cndmask_b32_e32 v0, v0, v19, vcc
	v_mul_f32_e32 v0, v151, v0
	v_pk_mul_f32 v[20:21], v[6:7], v[0:1] op_sel_hi:[1,0]
	v_pk_mul_f32 v[22:23], v[14:15], v[0:1] op_sel_hi:[1,0]
	v_pk_mul_f32 v[20:21], v[94:95], v[20:21]
	v_pk_mul_f32 v[22:23], v[90:91], v[22:23]
	v_pk_mul_f32 v[26:27], v[16:17], v[0:1] op_sel_hi:[1,0]
	v_pk_fma_f32 v[24:25], v[22:23], 0, v[20:21] op_sel_hi:[1,0,1]
	v_pk_fma_f32 v[20:21], v[20:21], 0, v[22:23] op_sel_hi:[1,0,1] neg_lo:[1,0,0] neg_hi:[1,0,0]
	v_pk_mul_f32 v[22:23], v[8:9], v[0:1] op_sel_hi:[1,0]
	v_pk_mul_f32 v[26:27], v[92:93], v[26:27]
	v_pk_mul_f32 v[22:23], v[96:97], v[22:23]
	v_pk_mul_f32 v[30:31], v[10:11], v[0:1] op_sel_hi:[1,0]
	v_pk_fma_f32 v[28:29], v[26:27], 0, v[22:23] op_sel_hi:[1,0,1]
	v_pk_fma_f32 v[22:23], v[22:23], 0, v[26:27] op_sel_hi:[1,0,1] neg_lo:[1,0,0] neg_hi:[1,0,0]
	v_pk_mul_f32 v[26:27], v[2:3], v[0:1] op_sel_hi:[1,0]
	v_pk_mul_f32 v[30:31], v[82:83], v[30:31]
	v_pk_mul_f32 v[26:27], v[86:87], v[26:27]
	v_pk_mul_f32 v[34:35], v[12:13], v[0:1] op_sel_hi:[1,0]
	v_pk_fma_f32 v[32:33], v[30:31], 0, v[26:27] op_sel_hi:[1,0,1]
	v_pk_fma_f32 v[26:27], v[26:27], 0, v[30:31] op_sel_hi:[1,0,1] neg_lo:[1,0,0] neg_hi:[1,0,0]
	v_pk_mul_f32 v[30:31], v[4:5], v[0:1] op_sel_hi:[1,0]
	v_pk_mul_f32 v[34:35], v[84:85], v[34:35]
	v_pk_mul_f32 v[30:31], v[88:89], v[30:31]
	v_lshlrev_b32_e32 v0, 7, v18
	v_pk_fma_f32 v[36:37], v[34:35], 0, v[30:31] op_sel_hi:[1,0,1]
	v_pk_fma_f32 v[30:31], v[30:31], 0, v[34:35] op_sel_hi:[1,0,1] neg_lo:[1,0,0] neg_hi:[1,0,0]
	v_lshl_add_u64 v[34:35], s[0:1], 0, v[0:1]
	v_lshl_add_u64 v[34:35], v[34:35], 0, v[146:147]
	v_cvt_pk_bf16_f32 v20, v20, v21
	v_cvt_pk_bf16_f32 v21, v22, v23
	v_cvt_pk_bf16_f32 v22, v26, v27
	v_cvt_pk_bf16_f32 v23, v30, v31
	global_store_dwordx4 v[34:35], v[20:23], off sc1
	s_nop 1
	v_cvt_pk_bf16_f32 v20, v24, v25
	v_cvt_pk_bf16_f32 v21, v28, v29
	v_cvt_pk_bf16_f32 v22, v32, v33
	v_cvt_pk_bf16_f32 v23, v36, v37
	global_store_dwordx4 v[34:35], v[20:23], off offset:64 sc1
